# 8-phase GEMM loops: per-segment s_setprio 1/0 toggling around every MMA group removed (static priority)
# speedup vs baseline: 1.0052x; 1.0024x over previous
.LBB0_190:
	ds_read_b128 v[180:183], v172
	ds_read_b128 v[184:187], v172 offset:1024
	ds_read_b128 v[188:191], v172 offset:2048
	ds_read_b128 v[192:195], v172 offset:3072
	v_add_u32_e32 v178, 0xc000, v152
	v_lshl_add_u64 v[244:245], s[20:21], 0, v[146:147]
	v_readfirstlane_b32 s1, v178
	v_add_u32_e32 v179, 0xe000, v152
	v_lshl_add_u64 v[224:225], v[244:245], 0, s[48:49]
	s_mov_b32 m0, s1
	v_lshl_add_u64 v[246:247], s[20:21], 0, v[148:149]
	v_readfirstlane_b32 s1, v179
	ds_read_b128 v[174:177], v161
	ds_read_b128 v[196:199], v161 offset:1024
	ds_read_b128 v[200:203], v160
	ds_read_b128 v[204:207], v160 offset:1024
	ds_read_b128 v[208:211], v159
	ds_read_b128 v[212:215], v159 offset:1024
	ds_read_b128 v[216:219], v158
	ds_read_b128 v[220:223], v158 offset:1024
	global_load_lds_dwordx4 v[224:225], off
	v_lshl_add_u64 v[224:225], v[246:247], 0, s[48:49]
	s_mov_b32 m0, s1
	s_nop 0
	global_load_lds_dwordx4 v[224:225], off
	s_waitcnt lgkmcnt(8)
	s_barrier
	s_waitcnt lgkmcnt(0)
	s_waitcnt lgkmcnt(0)
	v_mfma_f32_16x16x32_bf16 v[124:127], v[180:183], v[174:177], v[124:127]
	v_mfma_f32_16x16x32_bf16 v[120:123], v[188:191], v[174:177], v[120:123]
	v_mfma_f32_16x16x32_bf16 v[116:119], v[180:183], v[200:203], v[116:119]
	v_mfma_f32_16x16x32_bf16 v[112:115], v[188:191], v[200:203], v[112:115]
	v_mfma_f32_16x16x32_bf16 v[108:111], v[180:183], v[208:211], v[108:111]
	v_mfma_f32_16x16x32_bf16 v[104:107], v[188:191], v[208:211], v[104:107]
	v_mfma_f32_16x16x32_bf16 v[100:103], v[180:183], v[216:219], v[100:103]
	v_mfma_f32_16x16x32_bf16 v[96:99], v[188:191], v[216:219], v[96:99]
	v_mfma_f32_16x16x32_bf16 v[124:127], v[184:187], v[196:199], v[124:127]
	v_mfma_f32_16x16x32_bf16 v[120:123], v[192:195], v[196:199], v[120:123]
	v_mfma_f32_16x16x32_bf16 v[116:119], v[184:187], v[204:207], v[116:119]
	v_mfma_f32_16x16x32_bf16 v[112:115], v[192:195], v[204:207], v[112:115]
	v_mfma_f32_16x16x32_bf16 v[108:111], v[184:187], v[212:215], v[108:111]
	v_mfma_f32_16x16x32_bf16 v[104:107], v[192:195], v[212:215], v[104:107]
	v_mfma_f32_16x16x32_bf16 v[100:103], v[184:187], v[220:223], v[100:103]
	v_mfma_f32_16x16x32_bf16 v[96:99], v[192:195], v[220:223], v[96:99]
	s_barrier
	v_lshl_add_u64 v[248:249], s[20:21], 0, v[142:143]
	v_readfirstlane_b32 s1, v153
	v_add_u32_e32 v173, 0x2000, v153
	v_lshl_add_u64 v[240:241], v[248:249], 0, s[50:51]
	s_mov_b32 m0, s1
	v_lshl_add_u64 v[250:251], s[20:21], 0, v[144:145]
	v_readfirstlane_b32 s1, v173
	ds_read_b128 v[224:227], v169
	ds_read_b128 v[228:231], v169 offset:1024
	ds_read_b128 v[232:235], v169 offset:2048
	ds_read_b128 v[236:239], v169 offset:3072
	global_load_lds_dwordx4 v[240:241], off
	v_lshl_add_u64 v[240:241], v[250:251], 0, s[50:51]
	s_mov_b32 m0, s1
	s_nop 0
	global_load_lds_dwordx4 v[240:241], off
	s_barrier
	s_waitcnt lgkmcnt(0)
	s_waitcnt lgkmcnt(0)
	v_mfma_f32_16x16x32_bf16 v[92:95], v[224:227], v[174:177], v[92:95]
	v_mfma_f32_16x16x32_bf16 v[88:91], v[232:235], v[174:177], v[88:91]
	v_mfma_f32_16x16x32_bf16 v[84:87], v[224:227], v[200:203], v[84:87]
	v_mfma_f32_16x16x32_bf16 v[80:83], v[232:235], v[200:203], v[80:83]
	v_mfma_f32_16x16x32_bf16 v[76:79], v[224:227], v[208:211], v[76:79]
	v_mfma_f32_16x16x32_bf16 v[72:75], v[232:235], v[208:211], v[72:75]
	v_mfma_f32_16x16x32_bf16 v[68:71], v[224:227], v[216:219], v[68:71]
	v_mfma_f32_16x16x32_bf16 v[64:67], v[232:235], v[216:219], v[64:67]
	v_mfma_f32_16x16x32_bf16 v[92:95], v[228:231], v[196:199], v[92:95]
	v_mfma_f32_16x16x32_bf16 v[88:91], v[236:239], v[196:199], v[88:91]
	v_mfma_f32_16x16x32_bf16 v[84:87], v[228:231], v[204:207], v[84:87]
	v_mfma_f32_16x16x32_bf16 v[80:83], v[236:239], v[204:207], v[80:83]
	v_mfma_f32_16x16x32_bf16 v[76:79], v[228:231], v[212:215], v[76:79]
	v_mfma_f32_16x16x32_bf16 v[72:75], v[236:239], v[212:215], v[72:75]
	v_mfma_f32_16x16x32_bf16 v[68:71], v[228:231], v[220:223], v[68:71]
	v_mfma_f32_16x16x32_bf16 v[64:67], v[236:239], v[220:223], v[64:67]
	v_readfirstlane_b32 s1, v152
	v_lshl_add_u64 v[174:175], v[244:245], 0, s[52:53]
	s_mov_b32 m0, s1
	s_barrier
	ds_read_b128 v[196:199], v161 offset:16384
	ds_read_b128 v[200:203], v161 offset:17408
	ds_read_b128 v[204:207], v160 offset:16384
	ds_read_b128 v[208:211], v160 offset:17408
	ds_read_b128 v[212:215], v159 offset:16384
	ds_read_b128 v[216:219], v159 offset:17408
	ds_read_b128 v[220:223], v158 offset:16384
	ds_read_b128 v[240:243], v158 offset:17408
	global_load_lds_dwordx4 v[174:175], off
	v_add_u32_e32 v174, 0x2000, v152
	v_lshl_add_u64 v[176:177], v[246:247], 0, s[52:53]
	v_readfirstlane_b32 s1, v174
	s_mov_b32 m0, s1
	s_nop 0
	global_load_lds_dwordx4 v[176:177], off
	s_barrier
	s_waitcnt lgkmcnt(0)
	s_waitcnt lgkmcnt(0)
	v_mfma_f32_16x16x32_bf16 v[60:63], v[180:183], v[196:199], v[60:63]
	v_mfma_f32_16x16x32_bf16 v[56:59], v[188:191], v[196:199], v[56:59]
	v_mfma_f32_16x16x32_bf16 v[52:55], v[180:183], v[204:207], v[52:55]
	v_mfma_f32_16x16x32_bf16 v[48:51], v[188:191], v[204:207], v[48:51]
	v_mfma_f32_16x16x32_bf16 v[44:47], v[180:183], v[212:215], v[44:47]
	v_mfma_f32_16x16x32_bf16 v[40:43], v[188:191], v[212:215], v[40:43]
	v_mfma_f32_16x16x32_bf16 v[36:39], v[180:183], v[220:223], v[36:39]
	v_mfma_f32_16x16x32_bf16 v[32:35], v[188:191], v[220:223], v[32:35]
	v_mfma_f32_16x16x32_bf16 v[60:63], v[184:187], v[200:203], v[60:63]
	v_mfma_f32_16x16x32_bf16 v[56:59], v[192:195], v[200:203], v[56:59]
	v_mfma_f32_16x16x32_bf16 v[52:55], v[184:187], v[208:211], v[52:55]
	v_mfma_f32_16x16x32_bf16 v[48:51], v[192:195], v[208:211], v[48:51]
	v_mfma_f32_16x16x32_bf16 v[44:47], v[184:187], v[216:219], v[44:47]
	v_mfma_f32_16x16x32_bf16 v[40:43], v[192:195], v[216:219], v[40:43]
	v_mfma_f32_16x16x32_bf16 v[36:39], v[184:187], v[240:243], v[36:39]
	v_mfma_f32_16x16x32_bf16 v[32:35], v[192:195], v[240:243], v[32:35]
	s_barrier
	v_readfirstlane_b32 s1, v151
	v_add_u32_e32 v175, 0x2000, v151
	v_lshl_add_u64 v[176:177], v[248:249], 0, s[54:55]
	s_mov_b32 m0, s1
	v_readfirstlane_b32 s1, v175
	global_load_lds_dwordx4 v[176:177], off
	v_lshl_add_u64 v[176:177], v[250:251], 0, s[54:55]
	s_mov_b32 m0, s1
	s_nop 0
	global_load_lds_dwordx4 v[176:177], off
	s_waitcnt vmcnt(6)
	s_barrier
	v_mfma_f32_16x16x32_bf16 v[28:31], v[224:227], v[196:199], v[28:31]
	v_mfma_f32_16x16x32_bf16 v[24:27], v[232:235], v[196:199], v[24:27]
	v_mfma_f32_16x16x32_bf16 v[20:23], v[224:227], v[204:207], v[20:23]
	v_mfma_f32_16x16x32_bf16 v[16:19], v[232:235], v[204:207], v[16:19]
	v_mfma_f32_16x16x32_bf16 v[12:15], v[224:227], v[212:215], v[12:15]
	v_mfma_f32_16x16x32_bf16 v[8:11], v[232:235], v[212:215], v[8:11]
	v_mfma_f32_16x16x32_bf16 v[4:7], v[224:227], v[220:223], v[4:7]
	v_mfma_f32_16x16x32_bf16 v[0:3], v[232:235], v[220:223], v[0:3]
	v_mfma_f32_16x16x32_bf16 v[28:31], v[228:231], v[200:203], v[28:31]
	v_mfma_f32_16x16x32_bf16 v[24:27], v[236:239], v[200:203], v[24:27]
	v_mfma_f32_16x16x32_bf16 v[20:23], v[228:231], v[208:211], v[20:23]
	v_mfma_f32_16x16x32_bf16 v[16:19], v[236:239], v[208:211], v[16:19]
	v_mfma_f32_16x16x32_bf16 v[12:15], v[228:231], v[216:219], v[12:15]
	v_mfma_f32_16x16x32_bf16 v[8:11], v[236:239], v[216:219], v[8:11]
	v_mfma_f32_16x16x32_bf16 v[4:7], v[228:231], v[240:243], v[4:7]
	v_mfma_f32_16x16x32_bf16 v[0:3], v[236:239], v[240:243], v[0:3]
	s_barrier
	ds_read_b128 v[180:183], v163
	ds_read_b128 v[184:187], v163 offset:1024
	ds_read_b128 v[188:191], v163 offset:2048
	ds_read_b128 v[192:195], v163 offset:3072
	v_add_u32_e32 v176, 0x4000, v152
	v_add_u32_e32 v177, 0x6000, v152
	v_readfirstlane_b32 s1, v176
	v_lshl_add_u64 v[228:229], v[244:245], 0, s[56:57]
	s_mov_b32 m0, s1
	v_readfirstlane_b32 s1, v177
	ds_read_b128 v[196:199], v161 offset:32768
	ds_read_b128 v[200:203], v161 offset:33792
	ds_read_b128 v[204:207], v160 offset:32768
	ds_read_b128 v[208:211], v160 offset:33792
	ds_read_b128 v[212:215], v159 offset:32768
	ds_read_b128 v[216:219], v159 offset:33792
	ds_read_b128 v[220:223], v158 offset:32768
	ds_read_b128 v[224:227], v158 offset:33792
	global_load_lds_dwordx4 v[228:229], off
	v_lshl_add_u64 v[228:229], v[246:247], 0, s[56:57]
	s_mov_b32 m0, s1
	s_nop 0
	global_load_lds_dwordx4 v[228:229], off
	s_waitcnt lgkmcnt(8)
	s_barrier
	s_waitcnt lgkmcnt(0)
	s_waitcnt lgkmcnt(0)
	v_mfma_f32_16x16x32_bf16 v[124:127], v[180:183], v[196:199], v[124:127]
	v_mfma_f32_16x16x32_bf16 v[120:123], v[188:191], v[196:199], v[120:123]
	v_mfma_f32_16x16x32_bf16 v[116:119], v[180:183], v[204:207], v[116:119]
	v_mfma_f32_16x16x32_bf16 v[112:115], v[188:191], v[204:207], v[112:115]
	v_mfma_f32_16x16x32_bf16 v[108:111], v[180:183], v[212:215], v[108:111]
	v_mfma_f32_16x16x32_bf16 v[104:107], v[188:191], v[212:215], v[104:107]
	v_mfma_f32_16x16x32_bf16 v[100:103], v[180:183], v[220:223], v[100:103]
	v_mfma_f32_16x16x32_bf16 v[96:99], v[188:191], v[220:223], v[96:99]
	v_mfma_f32_16x16x32_bf16 v[124:127], v[184:187], v[200:203], v[124:127]
	v_mfma_f32_16x16x32_bf16 v[120:123], v[192:195], v[200:203], v[120:123]
	v_mfma_f32_16x16x32_bf16 v[116:119], v[184:187], v[208:211], v[116:119]
	v_mfma_f32_16x16x32_bf16 v[112:115], v[192:195], v[208:211], v[112:115]
	v_mfma_f32_16x16x32_bf16 v[108:111], v[184:187], v[216:219], v[108:111]
	v_mfma_f32_16x16x32_bf16 v[104:107], v[192:195], v[216:219], v[104:107]
	v_mfma_f32_16x16x32_bf16 v[100:103], v[184:187], v[224:227], v[100:103]
	v_mfma_f32_16x16x32_bf16 v[96:99], v[192:195], v[224:227], v[96:99]
	s_barrier
	v_readfirstlane_b32 s1, v167
	v_add_u32_e32 v254, 0x2000, v167
	v_lshl_add_u64 v[252:253], v[248:249], 0, s[58:59]
	s_mov_b32 m0, s1
	v_readfirstlane_b32 s1, v254
	ds_read_b128 v[228:231], v162
	ds_read_b128 v[232:235], v162 offset:1024
	ds_read_b128 v[236:239], v162 offset:2048
	ds_read_b128 v[240:243], v162 offset:3072
	global_load_lds_dwordx4 v[252:253], off
	v_lshl_add_u64 v[252:253], v[250:251], 0, s[58:59]
	s_mov_b32 m0, s1
	s_nop 0
	global_load_lds_dwordx4 v[252:253], off
	s_barrier
	s_waitcnt lgkmcnt(0)
	s_waitcnt lgkmcnt(0)
	v_mfma_f32_16x16x32_bf16 v[92:95], v[228:231], v[196:199], v[92:95]
	v_mfma_f32_16x16x32_bf16 v[88:91], v[236:239], v[196:199], v[88:91]
	v_mfma_f32_16x16x32_bf16 v[84:87], v[228:231], v[204:207], v[84:87]
	v_mfma_f32_16x16x32_bf16 v[80:83], v[236:239], v[204:207], v[80:83]
	v_mfma_f32_16x16x32_bf16 v[76:79], v[228:231], v[212:215], v[76:79]
	v_mfma_f32_16x16x32_bf16 v[72:75], v[236:239], v[212:215], v[72:75]
	v_mfma_f32_16x16x32_bf16 v[68:71], v[228:231], v[220:223], v[68:71]
	v_mfma_f32_16x16x32_bf16 v[64:67], v[236:239], v[220:223], v[64:67]
	v_mfma_f32_16x16x32_bf16 v[92:95], v[232:235], v[200:203], v[92:95]
	v_mfma_f32_16x16x32_bf16 v[88:91], v[240:243], v[200:203], v[88:91]
	v_mfma_f32_16x16x32_bf16 v[84:87], v[232:235], v[208:211], v[84:87]
	v_mfma_f32_16x16x32_bf16 v[80:83], v[240:243], v[208:211], v[80:83]
	v_mfma_f32_16x16x32_bf16 v[76:79], v[232:235], v[216:219], v[76:79]
	v_mfma_f32_16x16x32_bf16 v[72:75], v[240:243], v[216:219], v[72:75]
	v_mfma_f32_16x16x32_bf16 v[68:71], v[232:235], v[224:227], v[68:71]
	v_mfma_f32_16x16x32_bf16 v[64:67], v[240:243], v[224:227], v[64:67]
	v_readfirstlane_b32 s1, v168
	v_lshl_add_u64 v[244:245], v[244:245], 0, s[60:61]
	s_mov_b32 m0, s1
	v_readfirstlane_b32 s1, v170
	s_barrier
	ds_read_b128 v[196:199], v161 offset:49152
	ds_read_b128 v[200:203], v161 offset:50176
	ds_read_b128 v[204:207], v160 offset:49152
	ds_read_b128 v[208:211], v160 offset:50176
	ds_read_b128 v[212:215], v159 offset:49152
	ds_read_b128 v[216:219], v159 offset:50176
	ds_read_b128 v[220:223], v158 offset:49152
	ds_read_b128 v[224:227], v158 offset:50176
	global_load_lds_dwordx4 v[244:245], off
	v_lshl_add_u64 v[244:245], v[246:247], 0, s[60:61]
	s_mov_b32 m0, s1
	s_nop 0
	global_load_lds_dwordx4 v[244:245], off
	s_barrier
	s_waitcnt lgkmcnt(0)
	s_waitcnt lgkmcnt(0)
	v_mfma_f32_16x16x32_bf16 v[60:63], v[180:183], v[196:199], v[60:63]
	v_mfma_f32_16x16x32_bf16 v[56:59], v[188:191], v[196:199], v[56:59]
	v_mfma_f32_16x16x32_bf16 v[52:55], v[180:183], v[204:207], v[52:55]
	v_mfma_f32_16x16x32_bf16 v[48:51], v[188:191], v[204:207], v[48:51]
	v_mfma_f32_16x16x32_bf16 v[44:47], v[180:183], v[212:215], v[44:47]
	v_mfma_f32_16x16x32_bf16 v[40:43], v[188:191], v[212:215], v[40:43]
	v_mfma_f32_16x16x32_bf16 v[36:39], v[180:183], v[220:223], v[36:39]
	v_mfma_f32_16x16x32_bf16 v[32:35], v[188:191], v[220:223], v[32:35]
	v_mfma_f32_16x16x32_bf16 v[60:63], v[184:187], v[200:203], v[60:63]
	v_mfma_f32_16x16x32_bf16 v[56:59], v[192:195], v[200:203], v[56:59]
	v_mfma_f32_16x16x32_bf16 v[52:55], v[184:187], v[208:211], v[52:55]
	v_mfma_f32_16x16x32_bf16 v[48:51], v[192:195], v[208:211], v[48:51]
	v_mfma_f32_16x16x32_bf16 v[44:47], v[184:187], v[216:219], v[44:47]
	v_mfma_f32_16x16x32_bf16 v[40:43], v[192:195], v[216:219], v[40:43]
	v_mfma_f32_16x16x32_bf16 v[36:39], v[184:187], v[224:227], v[36:39]
	v_mfma_f32_16x16x32_bf16 v[32:35], v[192:195], v[224:227], v[32:35]
	s_barrier
	v_readfirstlane_b32 s1, v171
	v_add_u32_e32 v182, 0x2000, v171
	v_lshl_add_u64 v[180:181], v[248:249], 0, s[62:63]
	s_mov_b32 m0, s1
	v_readfirstlane_b32 s1, v182
	global_load_lds_dwordx4 v[180:181], off
	v_lshl_add_u64 v[180:181], v[250:251], 0, s[62:63]
	s_mov_b32 m0, s1
	s_nop 0
	global_load_lds_dwordx4 v[180:181], off
	s_waitcnt vmcnt(6)
	s_barrier
	v_mfma_f32_16x16x32_bf16 v[28:31], v[228:231], v[196:199], v[28:31]
	v_mfma_f32_16x16x32_bf16 v[24:27], v[236:239], v[196:199], v[24:27]
	v_mfma_f32_16x16x32_bf16 v[20:23], v[228:231], v[204:207], v[20:23]
	v_mfma_f32_16x16x32_bf16 v[16:19], v[236:239], v[204:207], v[16:19]
	v_mfma_f32_16x16x32_bf16 v[12:15], v[228:231], v[212:215], v[12:15]
	v_mfma_f32_16x16x32_bf16 v[8:11], v[236:239], v[212:215], v[8:11]
	v_mfma_f32_16x16x32_bf16 v[4:7], v[228:231], v[220:223], v[4:7]
	v_mfma_f32_16x16x32_bf16 v[0:3], v[236:239], v[220:223], v[0:3]
	v_mfma_f32_16x16x32_bf16 v[28:31], v[232:235], v[200:203], v[28:31]
	v_mfma_f32_16x16x32_bf16 v[24:27], v[240:243], v[200:203], v[24:27]
	v_mfma_f32_16x16x32_bf16 v[20:23], v[232:235], v[208:211], v[20:23]
	v_mfma_f32_16x16x32_bf16 v[16:19], v[240:243], v[208:211], v[16:19]
	v_mfma_f32_16x16x32_bf16 v[12:15], v[232:235], v[216:219], v[12:15]
	v_mfma_f32_16x16x32_bf16 v[8:11], v[240:243], v[216:219], v[8:11]
	v_mfma_f32_16x16x32_bf16 v[4:7], v[232:235], v[224:227], v[4:7]
	v_mfma_f32_16x16x32_bf16 v[0:3], v[240:243], v[224:227], v[0:3]
	s_add_i32 s0, s0, 2
	v_lshl_add_u64 v[142:143], v[142:143], 0, s[50:51]
	v_lshl_add_u64 v[144:145], v[144:145], 0, s[50:51]
	v_lshl_add_u64 v[146:147], v[146:147], 0, s[50:51]
	s_cmp_lt_u32 s0, 12
	v_lshl_add_u64 v[148:149], v[148:149], 0, s[50:51]
	s_barrier
	s_cbranch_scc1 .LBB0_190
	s_or_b32 s0, s6, 0x80
	s_ashr_i32 s1, s0, 31
	s_lshl_b64 s[0:1], s[0:1], 11
	s_add_u32 s0, s45, s0
	s_addc_u32 s1, s46, s1
	v_lshl_add_u64 v[170:171], s[0:1], 0, v[130:131]
	v_lshl_add_u64 v[138:139], v[138:139], 1, v[170:171]
	v_readfirstlane_b32 s2, v178
	v_lshl_add_u64 v[138:139], v[138:139], 0, s[64:65]
	s_mov_b32 m0, s2
	ds_read_b128 v[142:145], v172
	ds_read_b128 v[146:149], v172 offset:1024
	ds_read_b128 v[180:183], v172 offset:2048
	ds_read_b128 v[184:187], v172 offset:3072
	ds_read_b128 v[188:191], v161
	ds_read_b128 v[192:195], v161 offset:1024
	ds_read_b128 v[196:199], v160
	ds_read_b128 v[200:203], v160 offset:1024
	ds_read_b128 v[204:207], v159
	ds_read_b128 v[208:211], v159 offset:1024
	ds_read_b128 v[212:215], v158
	ds_read_b128 v[216:219], v158 offset:1024
	global_load_lds_dwordx4 v[138:139], off
	v_lshl_add_u64 v[138:139], s[0:1], 0, v[134:135]
	v_lshl_add_u64 v[138:139], v[140:141], 1, v[138:139]
	v_readfirstlane_b32 s0, v179
	v_lshl_add_u64 v[138:139], v[138:139], 0, s[64:65]
	s_mov_b32 m0, s0
	v_readlane_b32 s0, v255, 11
	global_load_lds_dwordx4 v[138:139], off
	s_add_i32 s82, s82, s0
	s_barrier
	s_waitcnt lgkmcnt(0)
	s_cmpk_gt_i32 s82, 0x54
	s_cselect_b64 s[66:67], -1, 0
	s_waitcnt lgkmcnt(0)
	v_mfma_f32_16x16x32_bf16 v[124:127], v[142:145], v[188:191], v[124:127]
	v_mfma_f32_16x16x32_bf16 v[116:119], v[142:145], v[196:199], v[116:119]
	v_mfma_f32_16x16x32_bf16 v[108:111], v[142:145], v[204:207], v[108:111]
	v_mfma_f32_16x16x32_bf16 v[100:103], v[142:145], v[212:215], v[100:103]
	v_mfma_f32_16x16x32_bf16 v[124:127], v[146:149], v[192:195], v[124:127]
	v_mfma_f32_16x16x32_bf16 v[120:123], v[180:183], v[188:191], v[120:123]
	v_mfma_f32_16x16x32_bf16 v[116:119], v[146:149], v[200:203], v[116:119]
	v_mfma_f32_16x16x32_bf16 v[112:115], v[180:183], v[196:199], v[112:115]
	v_mfma_f32_16x16x32_bf16 v[108:111], v[146:149], v[208:211], v[108:111]
	v_mfma_f32_16x16x32_bf16 v[104:107], v[180:183], v[204:207], v[104:107]
	v_mfma_f32_16x16x32_bf16 v[100:103], v[146:149], v[216:219], v[100:103]
	v_mfma_f32_16x16x32_bf16 v[96:99], v[180:183], v[212:215], v[96:99]
	v_mfma_f32_16x16x32_bf16 v[138:141], v[184:187], v[192:195], v[120:123]
	v_mfma_f32_16x16x32_bf16 v[220:223], v[184:187], v[200:203], v[112:115]
	v_mfma_f32_16x16x32_bf16 v[224:227], v[184:187], v[208:211], v[104:107]
	v_mfma_f32_16x16x32_bf16 v[228:231], v[184:187], v[216:219], v[96:99]
	s_barrier
	s_nop 1
	ds_read_b128 v[96:99], v169
	ds_read_b128 v[104:107], v169 offset:1024
	ds_read_b128 v[112:115], v169 offset:2048
	ds_read_b128 v[120:123], v169 offset:3072
	s_barrier
	s_waitcnt lgkmcnt(0)
	s_waitcnt lgkmcnt(0)
	v_mfma_f32_16x16x32_bf16 v[92:95], v[96:99], v[188:191], v[92:95]
	v_mfma_f32_16x16x32_bf16 v[88:91], v[112:115], v[188:191], v[88:91]
	v_mfma_f32_16x16x32_bf16 v[84:87], v[96:99], v[196:199], v[84:87]
	v_mfma_f32_16x16x32_bf16 v[80:83], v[112:115], v[196:199], v[80:83]
	v_mfma_f32_16x16x32_bf16 v[76:79], v[96:99], v[204:207], v[76:79]
	v_mfma_f32_16x16x32_bf16 v[72:75], v[112:115], v[204:207], v[72:75]
	v_mfma_f32_16x16x32_bf16 v[68:71], v[96:99], v[212:215], v[68:71]
	v_mfma_f32_16x16x32_bf16 v[64:67], v[112:115], v[212:215], v[64:67]
	v_mfma_f32_16x16x32_bf16 v[92:95], v[104:107], v[192:195], v[92:95]
	v_mfma_f32_16x16x32_bf16 v[88:91], v[120:123], v[192:195], v[88:91]
	v_mfma_f32_16x16x32_bf16 v[84:87], v[104:107], v[200:203], v[84:87]
	v_mfma_f32_16x16x32_bf16 v[80:83], v[120:123], v[200:203], v[80:83]
	v_mfma_f32_16x16x32_bf16 v[76:79], v[104:107], v[208:211], v[76:79]
	v_mfma_f32_16x16x32_bf16 v[72:75], v[120:123], v[208:211], v[72:75]
	v_mfma_f32_16x16x32_bf16 v[68:71], v[104:107], v[216:219], v[68:71]
	v_mfma_f32_16x16x32_bf16 v[64:67], v[120:123], v[216:219], v[64:67]
	s_barrier
	ds_read_b128 v[168:171], v161 offset:16384
	ds_read_b128 v[188:191], v161 offset:17408
	ds_read_b128 v[192:195], v160 offset:16384
	ds_read_b128 v[196:199], v160 offset:17408
	ds_read_b128 v[200:203], v159 offset:16384
	ds_read_b128 v[204:207], v159 offset:17408
	ds_read_b128 v[208:211], v158 offset:16384
	ds_read_b128 v[212:215], v158 offset:17408
	s_waitcnt vmcnt(4)
	s_barrier
	s_waitcnt lgkmcnt(0)
	s_waitcnt lgkmcnt(0)
	v_mfma_f32_16x16x32_bf16 v[60:63], v[142:145], v[168:171], v[60:63]
	v_mfma_f32_16x16x32_bf16 v[52:55], v[142:145], v[192:195], v[52:55]
	v_mfma_f32_16x16x32_bf16 v[44:47], v[142:145], v[200:203], v[44:47]
	v_mfma_f32_16x16x32_bf16 v[36:39], v[142:145], v[208:211], v[36:39]
	v_mfma_f32_16x16x32_bf16 v[60:63], v[146:149], v[188:191], v[60:63]
	v_mfma_f32_16x16x32_bf16 v[56:59], v[180:183], v[168:171], v[56:59]
	v_mfma_f32_16x16x32_bf16 v[52:55], v[146:149], v[196:199], v[52:55]
	v_mfma_f32_16x16x32_bf16 v[48:51], v[180:183], v[192:195], v[48:51]
	v_mfma_f32_16x16x32_bf16 v[44:47], v[146:149], v[204:207], v[44:47]
	v_mfma_f32_16x16x32_bf16 v[40:43], v[180:183], v[200:203], v[40:43]
	v_mfma_f32_16x16x32_bf16 v[36:39], v[146:149], v[212:215], v[36:39]
	v_mfma_f32_16x16x32_bf16 v[32:35], v[180:183], v[208:211], v[32:35]
	v_mfma_f32_16x16x32_bf16 v[216:219], v[184:187], v[188:191], v[56:59]
	v_mfma_f32_16x16x32_bf16 v[232:235], v[184:187], v[196:199], v[48:51]
	v_mfma_f32_16x16x32_bf16 v[236:239], v[184:187], v[204:207], v[40:43]
	v_mfma_f32_16x16x32_bf16 v[142:145], v[184:187], v[212:215], v[32:35]
	v_mfma_f32_16x16x32_bf16 v[28:31], v[96:99], v[168:171], v[28:31]
	v_mfma_f32_16x16x32_bf16 v[24:27], v[112:115], v[168:171], v[24:27]
	v_mfma_f32_16x16x32_bf16 v[20:23], v[96:99], v[192:195], v[20:23]
	v_mfma_f32_16x16x32_bf16 v[16:19], v[112:115], v[192:195], v[16:19]
	v_mfma_f32_16x16x32_bf16 v[12:15], v[96:99], v[200:203], v[12:15]
	v_mfma_f32_16x16x32_bf16 v[8:11], v[112:115], v[200:203], v[8:11]
	v_mfma_f32_16x16x32_bf16 v[4:7], v[96:99], v[208:211], v[4:7]
	v_mfma_f32_16x16x32_bf16 v[0:3], v[112:115], v[208:211], v[0:3]
	v_mfma_f32_16x16x32_bf16 v[28:31], v[104:107], v[188:191], v[28:31]
	v_mfma_f32_16x16x32_bf16 v[24:27], v[120:123], v[188:191], v[24:27]
	v_mfma_f32_16x16x32_bf16 v[20:23], v[104:107], v[196:199], v[20:23]
	v_mfma_f32_16x16x32_bf16 v[16:19], v[120:123], v[196:199], v[16:19]
	v_mfma_f32_16x16x32_bf16 v[12:15], v[104:107], v[204:207], v[12:15]
	v_mfma_f32_16x16x32_bf16 v[8:11], v[120:123], v[204:207], v[8:11]
	v_mfma_f32_16x16x32_bf16 v[4:7], v[104:107], v[212:215], v[4:7]
	v_mfma_f32_16x16x32_bf16 v[0:3], v[120:123], v[212:215], v[0:3]
	s_barrier
	ds_read_b128 v[32:35], v163
	ds_read_b128 v[146:149], v163 offset:1024
	ds_read_b128 v[168:171], v163 offset:2048
	ds_read_b128 v[178:181], v163 offset:3072
	ds_read_b128 v[40:43], v161 offset:32768
	ds_read_b128 v[48:51], v161 offset:33792
	ds_read_b128 v[56:59], v160 offset:32768
	ds_read_b128 v[182:185], v160 offset:33792
	ds_read_b128 v[186:189], v159 offset:32768
	ds_read_b128 v[190:193], v159 offset:33792
	ds_read_b128 v[194:197], v158 offset:32768
	ds_read_b128 v[198:201], v158 offset:33792
	s_waitcnt vmcnt(2)
	s_barrier
	s_waitcnt lgkmcnt(0)
	s_waitcnt lgkmcnt(0)
	v_mfma_f32_16x16x32_bf16 v[96:99], v[32:35], v[40:43], v[124:127]
	v_mfma_f32_16x16x32_bf16 v[120:123], v[146:149], v[48:51], v[96:99]
	v_mfma_f32_16x16x32_bf16 v[96:99], v[168:171], v[40:43], v[138:141]
	v_mfma_f32_16x16x32_bf16 v[124:127], v[178:181], v[48:51], v[96:99]
	v_mfma_f32_16x16x32_bf16 v[96:99], v[32:35], v[56:59], v[116:119]
	v_mfma_f32_16x16x32_bf16 v[112:115], v[146:149], v[182:185], v[96:99]
	v_mfma_f32_16x16x32_bf16 v[96:99], v[168:171], v[56:59], v[220:223]
	v_mfma_f32_16x16x32_bf16 v[116:119], v[178:181], v[182:185], v[96:99]
	v_mfma_f32_16x16x32_bf16 v[96:99], v[32:35], v[186:189], v[108:111]
	v_mfma_f32_16x16x32_bf16 v[104:107], v[146:149], v[190:193], v[96:99]
	v_mfma_f32_16x16x32_bf16 v[96:99], v[168:171], v[186:189], v[224:227]
	v_mfma_f32_16x16x32_bf16 v[108:111], v[178:181], v[190:193], v[96:99]
	v_mfma_f32_16x16x32_bf16 v[96:99], v[32:35], v[194:197], v[100:103]
	v_mfma_f32_16x16x32_bf16 v[100:103], v[168:171], v[194:197], v[228:231]
	v_mfma_f32_16x16x32_bf16 v[96:99], v[146:149], v[198:201], v[96:99]
	v_mfma_f32_16x16x32_bf16 v[100:103], v[178:181], v[198:201], v[100:103]
	s_barrier
	ds_read_b128 v[138:141], v162
	ds_read_b128 v[202:205], v162 offset:1024
	ds_read_b128 v[206:209], v162 offset:2048
	ds_read_b128 v[210:213], v162 offset:3072
	s_waitcnt vmcnt(0)
	s_barrier
	s_waitcnt lgkmcnt(0)
	s_waitcnt lgkmcnt(0)
	v_mfma_f32_16x16x32_bf16 v[92:95], v[138:141], v[40:43], v[92:95]
	v_mfma_f32_16x16x32_bf16 v[40:43], v[206:209], v[40:43], v[88:91]
	v_mfma_f32_16x16x32_bf16 v[88:91], v[210:213], v[48:51], v[40:43]
	v_mfma_f32_16x16x32_bf16 v[40:43], v[138:141], v[56:59], v[84:87]
	v_mfma_f32_16x16x32_bf16 v[84:87], v[202:205], v[182:185], v[40:43]
	v_mfma_f32_16x16x32_bf16 v[40:43], v[206:209], v[56:59], v[80:83]
	v_mfma_f32_16x16x32_bf16 v[80:83], v[210:213], v[182:185], v[40:43]
	v_mfma_f32_16x16x32_bf16 v[40:43], v[138:141], v[186:189], v[76:79]
	v_mfma_f32_16x16x32_bf16 v[76:79], v[202:205], v[190:193], v[40:43]
	v_mfma_f32_16x16x32_bf16 v[40:43], v[206:209], v[186:189], v[72:75]
	v_mfma_f32_16x16x32_bf16 v[72:75], v[210:213], v[190:193], v[40:43]
	v_mfma_f32_16x16x32_bf16 v[40:43], v[138:141], v[194:197], v[68:71]
	v_mfma_f32_16x16x32_bf16 v[68:71], v[202:205], v[198:201], v[40:43]
	v_mfma_f32_16x16x32_bf16 v[40:43], v[206:209], v[194:197], v[64:67]
	v_mfma_f32_16x16x32_bf16 v[92:95], v[202:205], v[48:51], v[92:95]
	v_mfma_f32_16x16x32_bf16 v[64:67], v[210:213], v[198:201], v[40:43]
	s_barrier
	ds_read_b128 v[182:185], v161 offset:49152
	ds_read_b128 v[186:189], v161 offset:50176
	ds_read_b128 v[190:193], v160 offset:49152
	ds_read_b128 v[160:163], v160 offset:50176
	ds_read_b128 v[194:197], v159 offset:49152
	ds_read_b128 v[198:201], v159 offset:50176
	ds_read_b128 v[220:223], v158 offset:49152
	ds_read_b128 v[224:227], v158 offset:50176
	s_barrier
	s_waitcnt lgkmcnt(0)
	s_waitcnt lgkmcnt(0)
	v_mfma_f32_16x16x32_bf16 v[40:43], v[32:35], v[182:185], v[60:63]
	v_mfma_f32_16x16x32_bf16 v[56:59], v[146:149], v[186:189], v[40:43]
	v_mfma_f32_16x16x32_bf16 v[40:43], v[168:171], v[182:185], v[216:219]
	v_mfma_f32_16x16x32_bf16 v[60:63], v[178:181], v[186:189], v[40:43]
	v_mfma_f32_16x16x32_bf16 v[40:43], v[32:35], v[190:193], v[52:55]
	v_mfma_f32_16x16x32_bf16 v[48:51], v[146:149], v[160:163], v[40:43]
	v_mfma_f32_16x16x32_bf16 v[40:43], v[168:171], v[190:193], v[232:235]
	v_mfma_f32_16x16x32_bf16 v[52:55], v[178:181], v[160:163], v[40:43]
	v_mfma_f32_16x16x32_bf16 v[40:43], v[32:35], v[194:197], v[44:47]
	v_mfma_f32_16x16x32_bf16 v[44:47], v[168:171], v[194:197], v[236:239]
	v_mfma_f32_16x16x32_bf16 v[32:35], v[32:35], v[220:223], v[36:39]
	v_mfma_f32_16x16x32_bf16 v[36:39], v[168:171], v[220:223], v[142:145]
	v_mfma_f32_16x16x32_bf16 v[40:43], v[146:149], v[198:201], v[40:43]
	v_mfma_f32_16x16x32_bf16 v[44:47], v[178:181], v[198:201], v[44:47]
	v_mfma_f32_16x16x32_bf16 v[32:35], v[146:149], v[224:227], v[32:35]
	v_mfma_f32_16x16x32_bf16 v[36:39], v[178:181], v[224:227], v[36:39]
	v_mfma_f32_16x16x32_bf16 v[28:31], v[138:141], v[182:185], v[28:31]
	v_mfma_f32_16x16x32_bf16 v[24:27], v[206:209], v[182:185], v[24:27]
	v_mfma_f32_16x16x32_bf16 v[20:23], v[138:141], v[190:193], v[20:23]
	v_mfma_f32_16x16x32_bf16 v[16:19], v[206:209], v[190:193], v[16:19]
	v_mfma_f32_16x16x32_bf16 v[12:15], v[138:141], v[194:197], v[12:15]
	v_mfma_f32_16x16x32_bf16 v[8:11], v[206:209], v[194:197], v[8:11]
	v_mfma_f32_16x16x32_bf16 v[4:7], v[138:141], v[220:223], v[4:7]
	v_mfma_f32_16x16x32_bf16 v[0:3], v[206:209], v[220:223], v[0:3]
	v_mfma_f32_16x16x32_bf16 v[28:31], v[202:205], v[186:189], v[28:31]
	v_mfma_f32_16x16x32_bf16 v[24:27], v[210:213], v[186:189], v[24:27]
	v_mfma_f32_16x16x32_bf16 v[20:23], v[202:205], v[160:163], v[20:23]
	v_mfma_f32_16x16x32_bf16 v[16:19], v[210:213], v[160:163], v[16:19]
	v_mfma_f32_16x16x32_bf16 v[12:15], v[202:205], v[198:201], v[12:15]
	v_mfma_f32_16x16x32_bf16 v[8:11], v[210:213], v[198:201], v[8:11]
	v_mfma_f32_16x16x32_bf16 v[4:7], v[202:205], v[224:227], v[4:7]
	v_mfma_f32_16x16x32_bf16 v[0:3], v[210:213], v[224:227], v[0:3]
	s_and_b64 vcc, exec, s[66:67]
	s_barrier
	s_cbranch_vccnz .LBB0_193
	s_mul_hi_i32 s0, s82, 0x66666667
	s_lshr_b32 s1, s0, 31
	s_ashr_i32 s0, s0, 1
	s_add_i32 s0, s0, s1
	v_readlane_b32 s1, v255, 15
	s_add_i32 s1, s0, s1
	s_mul_i32 s0, s0, 5
	s_sub_i32 s0, s82, s0
	v_readlane_b32 s2, v255, 14
	s_add_i32 s2, s0, s2
	s_lshl_b32 s8, s2, 8
	s_ashr_i32 s9, s8, 31
	s_lshl_b32 s0, s1, 8
	s_lshl_b64 s[40:41], s[8:9], 11
	s_add_u32 s40, s20, s40
	s_addc_u32 s41, s21, s41
	v_lshl_add_u64 v[138:139], s[40:41], 0, v[130:131]
	v_readfirstlane_b32 s1, v153
	v_lshl_add_u64 v[138:139], v[138:139], 0, v[132:133]
	s_mov_b32 m0, s1
	v_readfirstlane_b32 s1, v173
	global_load_lds_dwordx4 v[138:139], off
	s_mov_b32 m0, s1
	s_ashr_i32 s1, s0, 31
	v_lshl_add_u64 v[138:139], s[40:41], 0, v[134:135]
	s_lshl_b64 s[40:41], s[0:1], 11
	s_add_u32 s40, s45, s40
	v_lshl_add_u64 v[138:139], v[138:139], 0, v[136:137]
	s_addc_u32 s41, s46, s41
	s_bitset1_b32 s8, 7
	global_load_lds_dwordx4 v[138:139], off
	v_lshl_add_u64 v[138:139], s[40:41], 0, v[130:131]
	v_readfirstlane_b32 s1, v152
	s_ashr_i32 s9, s8, 31
	v_lshl_add_u64 v[138:139], v[138:139], 0, v[132:133]
	s_mov_b32 m0, s1
	s_lshl_b64 s[8:9], s[8:9], 11
	global_load_lds_dwordx4 v[138:139], off
	v_lshl_add_u64 v[138:139], s[40:41], 0, v[134:135]
	v_readfirstlane_b32 s1, v174
	s_add_u32 s8, s20, s8
	v_lshl_add_u64 v[138:139], v[138:139], 0, v[136:137]
	s_mov_b32 m0, s1
	s_addc_u32 s9, s21, s9
	global_load_lds_dwordx4 v[138:139], off
	v_lshl_add_u64 v[138:139], s[8:9], 0, v[130:131]
	v_readfirstlane_b32 s1, v151
	v_lshl_add_u64 v[138:139], v[138:139], 0, v[132:133]
	s_mov_b32 m0, s1
	v_readfirstlane_b32 s1, v175
	s_bitset1_b32 s0, 7
	global_load_lds_dwordx4 v[138:139], off
	s_mov_b32 m0, s1
	s_ashr_i32 s1, s0, 31
	s_lshl_b64 s[0:1], s[0:1], 11
	s_add_u32 s0, s45, s0
	v_lshl_add_u64 v[138:139], s[8:9], 0, v[134:135]
	s_addc_u32 s1, s46, s1
	v_lshl_add_u64 v[138:139], v[138:139], 0, v[136:137]
	v_lshl_add_u64 v[130:131], s[0:1], 0, v[130:131]
	v_readfirstlane_b32 s2, v176
	global_load_lds_dwordx4 v[138:139], off
	v_lshl_add_u64 v[130:131], v[130:131], 0, v[132:133]
	s_mov_b32 m0, s2
	s_nop 0
	global_load_lds_dwordx4 v[130:131], off
	v_lshl_add_u64 v[130:131], s[0:1], 0, v[134:135]
	v_readfirstlane_b32 s0, v177
	v_lshl_add_u64 v[130:131], v[130:131], 0, v[136:137]
	s_mov_b32 m0, s0
	s_nop 0
	global_load_lds_dwordx4 v[130:131], off

.LBB0_1529:
	ds_read_b128 v[182:185], v180
	ds_read_b128 v[186:189], v180 offset:1024
	ds_read_b128 v[190:193], v180 offset:2048
	ds_read_b128 v[194:197], v180 offset:3072
	v_add_u32_e32 v0, 0xc000, v162
	v_lshl_add_u64 v[246:247], v[142:143], 0, s[60:61]
	v_readfirstlane_b32 s1, v0
	v_lshl_add_u64 v[2:3], v[246:247], 0, s[18:19]
	s_mov_b32 m0, s1
	ds_read_b128 v[198:201], v161
	ds_read_b128 v[202:205], v161 offset:1024
	ds_read_b128 v[206:209], v160
	ds_read_b128 v[210:213], v160 offset:1024
	ds_read_b128 v[214:217], v159
	ds_read_b128 v[218:221], v159 offset:1024
	ds_read_b128 v[222:225], v158
	ds_read_b128 v[226:229], v158 offset:1024
	global_load_lds_dwordx4 v[2:3], off
	v_add_u32_e32 v2, 0xe000, v162
	v_lshl_add_u64 v[248:249], v[144:145], 0, s[60:61]
	v_readfirstlane_b32 s1, v2
	v_lshl_add_u64 v[230:231], v[248:249], 0, s[18:19]
	s_mov_b32 m0, s1
	s_nop 0
	global_load_lds_dwordx4 v[230:231], off
	s_waitcnt lgkmcnt(8)
	s_barrier
	s_waitcnt lgkmcnt(0)
	s_waitcnt lgkmcnt(0)
	v_mfma_f32_16x16x32_bf16 v[128:131], v[182:185], v[198:201], v[128:131]
	v_mfma_f32_16x16x32_bf16 v[124:127], v[190:193], v[198:201], v[124:127]
	v_mfma_f32_16x16x32_bf16 v[120:123], v[182:185], v[206:209], v[120:123]
	v_mfma_f32_16x16x32_bf16 v[116:119], v[190:193], v[206:209], v[116:119]
	v_mfma_f32_16x16x32_bf16 v[112:115], v[182:185], v[214:217], v[112:115]
	v_mfma_f32_16x16x32_bf16 v[108:111], v[190:193], v[214:217], v[108:111]
	v_mfma_f32_16x16x32_bf16 v[104:107], v[182:185], v[222:225], v[104:107]
	v_mfma_f32_16x16x32_bf16 v[100:103], v[190:193], v[222:225], v[100:103]
	v_mfma_f32_16x16x32_bf16 v[128:131], v[186:189], v[202:205], v[128:131]
	v_mfma_f32_16x16x32_bf16 v[124:127], v[194:197], v[202:205], v[124:127]
	v_mfma_f32_16x16x32_bf16 v[120:123], v[186:189], v[210:213], v[120:123]
	v_mfma_f32_16x16x32_bf16 v[116:119], v[194:197], v[210:213], v[116:119]
	v_mfma_f32_16x16x32_bf16 v[112:115], v[186:189], v[218:221], v[112:115]
	v_mfma_f32_16x16x32_bf16 v[108:111], v[194:197], v[218:221], v[108:111]
	v_mfma_f32_16x16x32_bf16 v[104:107], v[186:189], v[226:229], v[104:107]
	v_mfma_f32_16x16x32_bf16 v[100:103], v[194:197], v[226:229], v[100:103]
	s_barrier
	v_lshl_add_u64 v[250:251], v[138:139], 0, s[60:61]
	v_readfirstlane_b32 s1, v147
	v_lshl_add_u64 v[252:253], v[250:251], 0, s[20:21]
	s_mov_b32 m0, s1
	v_add_u32_e32 v3, 0x2000, v147
	ds_read_b128 v[230:233], v178
	ds_read_b128 v[234:237], v178 offset:1024
	ds_read_b128 v[238:241], v178 offset:2048
	ds_read_b128 v[242:245], v178 offset:3072
	global_load_lds_dwordx4 v[252:253], off
	v_lshl_add_u64 v[252:253], v[140:141], 0, s[60:61]
	v_readfirstlane_b32 s1, v3
	v_lshl_add_u64 v[132:133], v[252:253], 0, s[20:21]
	s_mov_b32 m0, s1
	s_add_i32 s1, s0, 2
	global_load_lds_dwordx4 v[132:133], off
	s_barrier
	s_waitcnt lgkmcnt(0)
	s_waitcnt lgkmcnt(0)
	v_mfma_f32_16x16x32_bf16 v[96:99], v[230:233], v[198:201], v[96:99]
	v_mfma_f32_16x16x32_bf16 v[92:95], v[238:241], v[198:201], v[92:95]
	v_mfma_f32_16x16x32_bf16 v[88:91], v[230:233], v[206:209], v[88:91]
	v_mfma_f32_16x16x32_bf16 v[84:87], v[238:241], v[206:209], v[84:87]
	v_mfma_f32_16x16x32_bf16 v[80:83], v[230:233], v[214:217], v[80:83]
	v_mfma_f32_16x16x32_bf16 v[76:79], v[238:241], v[214:217], v[76:79]
	v_mfma_f32_16x16x32_bf16 v[72:75], v[230:233], v[222:225], v[72:75]
	v_mfma_f32_16x16x32_bf16 v[68:71], v[238:241], v[222:225], v[68:71]
	v_mfma_f32_16x16x32_bf16 v[96:99], v[234:237], v[202:205], v[96:99]
	v_mfma_f32_16x16x32_bf16 v[92:95], v[242:245], v[202:205], v[92:95]
	v_mfma_f32_16x16x32_bf16 v[88:91], v[234:237], v[210:213], v[88:91]
	v_mfma_f32_16x16x32_bf16 v[84:87], v[242:245], v[210:213], v[84:87]
	v_mfma_f32_16x16x32_bf16 v[80:83], v[234:237], v[218:221], v[80:83]
	v_mfma_f32_16x16x32_bf16 v[76:79], v[242:245], v[218:221], v[76:79]
	v_mfma_f32_16x16x32_bf16 v[72:75], v[234:237], v[226:229], v[72:75]
	v_mfma_f32_16x16x32_bf16 v[68:71], v[242:245], v[226:229], v[68:71]
	v_readfirstlane_b32 s2, v162
	v_lshl_add_u64 v[132:133], v[246:247], 0, s[24:25]
	s_mov_b32 m0, s2
	v_readfirstlane_b32 s2, v163
	s_barrier
	ds_read_b128 v[198:201], v161 offset:16384
	ds_read_b128 v[202:205], v161 offset:17408
	ds_read_b128 v[206:209], v160 offset:16384
	ds_read_b128 v[210:213], v160 offset:17408
	ds_read_b128 v[214:217], v159 offset:16384
	ds_read_b128 v[218:221], v159 offset:17408
	ds_read_b128 v[222:225], v158 offset:16384
	ds_read_b128 v[226:229], v158 offset:17408
	global_load_lds_dwordx4 v[132:133], off
	v_lshl_add_u64 v[132:133], v[248:249], 0, s[24:25]
	s_mov_b32 m0, s2
	s_nop 0
	global_load_lds_dwordx4 v[132:133], off
	s_barrier
	s_waitcnt lgkmcnt(0)
	s_waitcnt lgkmcnt(0)
	v_mfma_f32_16x16x32_bf16 v[64:67], v[182:185], v[198:201], v[64:67]
	v_mfma_f32_16x16x32_bf16 v[60:63], v[190:193], v[198:201], v[60:63]
	v_mfma_f32_16x16x32_bf16 v[56:59], v[182:185], v[206:209], v[56:59]
	v_mfma_f32_16x16x32_bf16 v[52:55], v[190:193], v[206:209], v[52:55]
	v_mfma_f32_16x16x32_bf16 v[48:51], v[182:185], v[214:217], v[48:51]
	v_mfma_f32_16x16x32_bf16 v[44:47], v[190:193], v[214:217], v[44:47]
	v_mfma_f32_16x16x32_bf16 v[40:43], v[182:185], v[222:225], v[40:43]
	v_mfma_f32_16x16x32_bf16 v[36:39], v[190:193], v[222:225], v[36:39]
	v_mfma_f32_16x16x32_bf16 v[64:67], v[186:189], v[202:205], v[64:67]
	v_mfma_f32_16x16x32_bf16 v[60:63], v[194:197], v[202:205], v[60:63]
	v_mfma_f32_16x16x32_bf16 v[56:59], v[186:189], v[210:213], v[56:59]
	v_mfma_f32_16x16x32_bf16 v[52:55], v[194:197], v[210:213], v[52:55]
	v_mfma_f32_16x16x32_bf16 v[48:51], v[186:189], v[218:221], v[48:51]
	v_mfma_f32_16x16x32_bf16 v[44:47], v[194:197], v[218:221], v[44:47]
	v_mfma_f32_16x16x32_bf16 v[40:43], v[186:189], v[226:229], v[40:43]
	v_mfma_f32_16x16x32_bf16 v[36:39], v[194:197], v[226:229], v[36:39]
	s_barrier
	v_readfirstlane_b32 s2, v168
	v_add_u32_e32 v3, 0x2000, v168
	v_lshl_add_u64 v[132:133], v[250:251], 0, s[26:27]
	s_mov_b32 m0, s2
	v_readfirstlane_b32 s2, v3
	global_load_lds_dwordx4 v[132:133], off
	v_lshl_add_u64 v[132:133], v[252:253], 0, s[26:27]
	s_mov_b32 m0, s2
	s_nop 0
	global_load_lds_dwordx4 v[132:133], off
	s_waitcnt vmcnt(6)
	s_barrier
	v_mfma_f32_16x16x32_bf16 v[32:35], v[230:233], v[198:201], v[32:35]
	v_mfma_f32_16x16x32_bf16 v[28:31], v[238:241], v[198:201], v[28:31]
	v_mfma_f32_16x16x32_bf16 v[24:27], v[230:233], v[206:209], v[24:27]
	v_mfma_f32_16x16x32_bf16 v[20:23], v[238:241], v[206:209], v[20:23]
	v_mfma_f32_16x16x32_bf16 v[16:19], v[230:233], v[214:217], v[16:19]
	v_mfma_f32_16x16x32_bf16 v[12:15], v[238:241], v[214:217], v[12:15]
	v_mfma_f32_16x16x32_bf16 v[8:11], v[230:233], v[222:225], v[8:11]
	v_mfma_f32_16x16x32_bf16 v[4:7], v[238:241], v[222:225], v[4:7]
	v_mfma_f32_16x16x32_bf16 v[32:35], v[234:237], v[202:205], v[32:35]
	v_mfma_f32_16x16x32_bf16 v[28:31], v[242:245], v[202:205], v[28:31]
	v_mfma_f32_16x16x32_bf16 v[24:27], v[234:237], v[210:213], v[24:27]
	v_mfma_f32_16x16x32_bf16 v[20:23], v[242:245], v[210:213], v[20:23]
	v_mfma_f32_16x16x32_bf16 v[16:19], v[234:237], v[218:221], v[16:19]
	v_mfma_f32_16x16x32_bf16 v[12:15], v[242:245], v[218:221], v[12:15]
	v_mfma_f32_16x16x32_bf16 v[8:11], v[234:237], v[226:229], v[8:11]
	v_mfma_f32_16x16x32_bf16 v[4:7], v[242:245], v[226:229], v[4:7]
	s_barrier
	ds_read_b128 v[182:185], v170
	ds_read_b128 v[186:189], v170 offset:1024
	ds_read_b128 v[190:193], v170 offset:2048
	ds_read_b128 v[194:197], v170 offset:3072
	v_readfirstlane_b32 s2, v169
	v_lshl_add_u64 v[132:133], v[246:247], 0, s[28:29]
	s_mov_b32 m0, s2
	v_readfirstlane_b32 s2, v171
	ds_read_b128 v[198:201], v161 offset:32768
	ds_read_b128 v[202:205], v161 offset:33792
	ds_read_b128 v[206:209], v160 offset:32768
	ds_read_b128 v[210:213], v160 offset:33792
	ds_read_b128 v[214:217], v159 offset:32768
	ds_read_b128 v[218:221], v159 offset:33792
	ds_read_b128 v[222:225], v158 offset:32768
	ds_read_b128 v[226:229], v158 offset:33792
	global_load_lds_dwordx4 v[132:133], off
	v_lshl_add_u64 v[132:133], v[248:249], 0, s[28:29]
	s_mov_b32 m0, s2
	s_nop 0
	global_load_lds_dwordx4 v[132:133], off
	s_waitcnt lgkmcnt(8)
	s_barrier
	s_waitcnt lgkmcnt(0)
	s_waitcnt lgkmcnt(0)
	v_mfma_f32_16x16x32_bf16 v[128:131], v[182:185], v[198:201], v[128:131]
	v_mfma_f32_16x16x32_bf16 v[124:127], v[190:193], v[198:201], v[124:127]
	v_mfma_f32_16x16x32_bf16 v[120:123], v[182:185], v[206:209], v[120:123]
	v_mfma_f32_16x16x32_bf16 v[116:119], v[190:193], v[206:209], v[116:119]
	v_mfma_f32_16x16x32_bf16 v[112:115], v[182:185], v[214:217], v[112:115]
	v_mfma_f32_16x16x32_bf16 v[108:111], v[190:193], v[214:217], v[108:111]
	v_mfma_f32_16x16x32_bf16 v[104:107], v[182:185], v[222:225], v[104:107]
	v_mfma_f32_16x16x32_bf16 v[100:103], v[190:193], v[222:225], v[100:103]
	v_mfma_f32_16x16x32_bf16 v[128:131], v[186:189], v[202:205], v[128:131]
	v_mfma_f32_16x16x32_bf16 v[124:127], v[194:197], v[202:205], v[124:127]
	v_mfma_f32_16x16x32_bf16 v[120:123], v[186:189], v[210:213], v[120:123]
	v_mfma_f32_16x16x32_bf16 v[116:119], v[194:197], v[210:213], v[116:119]
	v_mfma_f32_16x16x32_bf16 v[112:115], v[186:189], v[218:221], v[112:115]
	v_mfma_f32_16x16x32_bf16 v[108:111], v[194:197], v[218:221], v[108:111]
	v_mfma_f32_16x16x32_bf16 v[104:107], v[186:189], v[226:229], v[104:107]
	v_mfma_f32_16x16x32_bf16 v[100:103], v[194:197], v[226:229], v[100:103]
	s_barrier
	v_readfirstlane_b32 s2, v172
	v_lshl_add_u64 v[132:133], v[250:251], 0, s[30:31]
	s_mov_b32 m0, s2
	v_readfirstlane_b32 s2, v173
	ds_read_b128 v[230:233], v167
	ds_read_b128 v[234:237], v167 offset:1024
	ds_read_b128 v[238:241], v167 offset:2048
	ds_read_b128 v[242:245], v167 offset:3072
	global_load_lds_dwordx4 v[132:133], off
	v_lshl_add_u64 v[132:133], v[252:253], 0, s[30:31]
	s_mov_b32 m0, s2
	s_nop 0
	global_load_lds_dwordx4 v[132:133], off
	s_barrier
	s_waitcnt lgkmcnt(0)
	s_waitcnt lgkmcnt(0)
	v_mfma_f32_16x16x32_bf16 v[96:99], v[230:233], v[198:201], v[96:99]
	v_mfma_f32_16x16x32_bf16 v[92:95], v[238:241], v[198:201], v[92:95]
	v_mfma_f32_16x16x32_bf16 v[88:91], v[230:233], v[206:209], v[88:91]
	v_mfma_f32_16x16x32_bf16 v[84:87], v[238:241], v[206:209], v[84:87]
	v_mfma_f32_16x16x32_bf16 v[80:83], v[230:233], v[214:217], v[80:83]
	v_mfma_f32_16x16x32_bf16 v[76:79], v[238:241], v[214:217], v[76:79]
	v_mfma_f32_16x16x32_bf16 v[72:75], v[230:233], v[222:225], v[72:75]
	v_mfma_f32_16x16x32_bf16 v[68:71], v[238:241], v[222:225], v[68:71]
	v_mfma_f32_16x16x32_bf16 v[96:99], v[234:237], v[202:205], v[96:99]
	v_mfma_f32_16x16x32_bf16 v[92:95], v[242:245], v[202:205], v[92:95]
	v_mfma_f32_16x16x32_bf16 v[88:91], v[234:237], v[210:213], v[88:91]
	v_mfma_f32_16x16x32_bf16 v[84:87], v[242:245], v[210:213], v[84:87]
	v_mfma_f32_16x16x32_bf16 v[80:83], v[234:237], v[218:221], v[80:83]
	v_mfma_f32_16x16x32_bf16 v[76:79], v[242:245], v[218:221], v[76:79]
	v_mfma_f32_16x16x32_bf16 v[72:75], v[234:237], v[226:229], v[72:75]
	v_mfma_f32_16x16x32_bf16 v[68:71], v[242:245], v[226:229], v[68:71]
	v_readfirstlane_b32 s2, v174
	v_lshl_add_u64 v[132:133], v[246:247], 0, s[34:35]
	s_mov_b32 m0, s2
	v_readfirstlane_b32 s2, v175
	s_barrier
	ds_read_b128 v[198:201], v161 offset:49152
	ds_read_b128 v[202:205], v161 offset:50176
	ds_read_b128 v[206:209], v160 offset:49152
	ds_read_b128 v[210:213], v160 offset:50176
	ds_read_b128 v[214:217], v159 offset:49152
	ds_read_b128 v[218:221], v159 offset:50176
	ds_read_b128 v[222:225], v158 offset:49152
	ds_read_b128 v[226:229], v158 offset:50176
	global_load_lds_dwordx4 v[132:133], off
	v_lshl_add_u64 v[132:133], v[248:249], 0, s[34:35]
	s_mov_b32 m0, s2
	s_nop 0
	global_load_lds_dwordx4 v[132:133], off
	s_barrier
	s_waitcnt lgkmcnt(0)
	s_waitcnt lgkmcnt(0)
	v_mfma_f32_16x16x32_bf16 v[64:67], v[182:185], v[198:201], v[64:67]
	v_mfma_f32_16x16x32_bf16 v[60:63], v[190:193], v[198:201], v[60:63]
	v_mfma_f32_16x16x32_bf16 v[56:59], v[182:185], v[206:209], v[56:59]
	v_mfma_f32_16x16x32_bf16 v[52:55], v[190:193], v[206:209], v[52:55]
	v_mfma_f32_16x16x32_bf16 v[48:51], v[182:185], v[214:217], v[48:51]
	v_mfma_f32_16x16x32_bf16 v[44:47], v[190:193], v[214:217], v[44:47]
	v_mfma_f32_16x16x32_bf16 v[40:43], v[182:185], v[222:225], v[40:43]
	v_mfma_f32_16x16x32_bf16 v[36:39], v[190:193], v[222:225], v[36:39]
	v_mfma_f32_16x16x32_bf16 v[64:67], v[186:189], v[202:205], v[64:67]
	v_mfma_f32_16x16x32_bf16 v[60:63], v[194:197], v[202:205], v[60:63]
	v_mfma_f32_16x16x32_bf16 v[56:59], v[186:189], v[210:213], v[56:59]
	v_mfma_f32_16x16x32_bf16 v[52:55], v[194:197], v[210:213], v[52:55]
	v_mfma_f32_16x16x32_bf16 v[48:51], v[186:189], v[218:221], v[48:51]
	v_mfma_f32_16x16x32_bf16 v[44:47], v[194:197], v[218:221], v[44:47]
	v_mfma_f32_16x16x32_bf16 v[40:43], v[186:189], v[226:229], v[40:43]
	v_mfma_f32_16x16x32_bf16 v[36:39], v[194:197], v[226:229], v[36:39]
	s_barrier
	v_readfirstlane_b32 s2, v176
	v_lshl_add_u64 v[132:133], v[250:251], 0, s[36:37]
	s_mov_b32 m0, s2
	v_readfirstlane_b32 s2, v177
	global_load_lds_dwordx4 v[132:133], off
	v_lshl_add_u64 v[132:133], v[252:253], 0, s[36:37]
	s_mov_b32 m0, s2
	s_nop 0
	global_load_lds_dwordx4 v[132:133], off
	s_waitcnt vmcnt(6)
	s_barrier
	v_mfma_f32_16x16x32_bf16 v[32:35], v[230:233], v[198:201], v[32:35]
	v_mfma_f32_16x16x32_bf16 v[28:31], v[238:241], v[198:201], v[28:31]
	v_mfma_f32_16x16x32_bf16 v[24:27], v[230:233], v[206:209], v[24:27]
	v_mfma_f32_16x16x32_bf16 v[20:23], v[238:241], v[206:209], v[20:23]
	v_mfma_f32_16x16x32_bf16 v[16:19], v[230:233], v[214:217], v[16:19]
	v_mfma_f32_16x16x32_bf16 v[12:15], v[238:241], v[214:217], v[12:15]
	v_mfma_f32_16x16x32_bf16 v[8:11], v[230:233], v[222:225], v[8:11]
	v_mfma_f32_16x16x32_bf16 v[4:7], v[238:241], v[222:225], v[4:7]
	v_mfma_f32_16x16x32_bf16 v[32:35], v[234:237], v[202:205], v[32:35]
	v_mfma_f32_16x16x32_bf16 v[28:31], v[242:245], v[202:205], v[28:31]
	v_mfma_f32_16x16x32_bf16 v[24:27], v[234:237], v[210:213], v[24:27]
	v_mfma_f32_16x16x32_bf16 v[20:23], v[242:245], v[210:213], v[20:23]
	v_mfma_f32_16x16x32_bf16 v[16:19], v[234:237], v[218:221], v[16:19]
	v_mfma_f32_16x16x32_bf16 v[12:15], v[242:245], v[218:221], v[12:15]
	v_mfma_f32_16x16x32_bf16 v[8:11], v[234:237], v[226:229], v[8:11]
	v_mfma_f32_16x16x32_bf16 v[4:7], v[242:245], v[226:229], v[4:7]
	s_add_u32 s60, s60, 0x100
	s_addc_u32 s61, s61, 0
	s_cmp_gt_u32 s0, 11
	s_barrier
	s_cbranch_scc1 .LBB0_1532
	s_mov_b32 s0, s1
	s_cmp_lt_i32 s0, 12
	s_cbranch_scc1 .LBB0_1493

.LBB0_1532:
	v_readfirstlane_b32 s0, v0
	v_lshl_add_u64 v[134:135], v[134:135], 0, s[56:57]
	s_mov_b32 m0, s0
	v_readfirstlane_b32 s0, v2
	ds_read_b128 v[138:141], v180
	ds_read_b128 v[142:145], v180 offset:1024
	ds_read_b128 v[172:175], v180 offset:2048
	ds_read_b128 v[180:183], v180 offset:3072
	ds_read_b128 v[184:187], v161
	ds_read_b128 v[188:191], v161 offset:1024
	ds_read_b128 v[192:195], v160
	ds_read_b128 v[196:199], v160 offset:1024
	ds_read_b128 v[200:203], v159
	ds_read_b128 v[204:207], v159 offset:1024
	ds_read_b128 v[208:211], v158
	ds_read_b128 v[212:215], v158 offset:1024
	global_load_lds_dwordx4 v[134:135], off
	v_lshl_add_u64 v[134:135], v[136:137], 0, s[56:57]
	s_mov_b32 m0, s0
	s_nop 0
	global_load_lds_dwordx4 v[134:135], off
	s_barrier
	s_waitcnt lgkmcnt(0)
	s_waitcnt lgkmcnt(0)
	v_mfma_f32_16x16x32_bf16 v[128:131], v[138:141], v[184:187], v[128:131]
	v_mfma_f32_16x16x32_bf16 v[124:127], v[172:175], v[184:187], v[124:127]
	v_mfma_f32_16x16x32_bf16 v[120:123], v[138:141], v[192:195], v[120:123]
	v_mfma_f32_16x16x32_bf16 v[116:119], v[172:175], v[192:195], v[116:119]
	v_mfma_f32_16x16x32_bf16 v[112:115], v[138:141], v[200:203], v[112:115]
	v_mfma_f32_16x16x32_bf16 v[108:111], v[172:175], v[200:203], v[108:111]
	v_mfma_f32_16x16x32_bf16 v[104:107], v[138:141], v[208:211], v[104:107]
	v_mfma_f32_16x16x32_bf16 v[100:103], v[172:175], v[208:211], v[100:103]
	v_mfma_f32_16x16x32_bf16 v[128:131], v[142:145], v[188:191], v[128:131]
	v_mfma_f32_16x16x32_bf16 v[124:127], v[180:183], v[188:191], v[124:127]
	v_mfma_f32_16x16x32_bf16 v[120:123], v[142:145], v[196:199], v[120:123]
	v_mfma_f32_16x16x32_bf16 v[116:119], v[180:183], v[196:199], v[116:119]
	v_mfma_f32_16x16x32_bf16 v[112:115], v[142:145], v[204:207], v[112:115]
	v_mfma_f32_16x16x32_bf16 v[108:111], v[180:183], v[204:207], v[108:111]
	v_mfma_f32_16x16x32_bf16 v[104:107], v[142:145], v[212:215], v[104:107]
	v_mfma_f32_16x16x32_bf16 v[100:103], v[180:183], v[212:215], v[100:103]
	s_barrier
	ds_read_b128 v[134:137], v178
	ds_read_b128 v[216:219], v178 offset:1024
	ds_read_b128 v[220:223], v178 offset:2048
	ds_read_b128 v[176:179], v178 offset:3072
	s_barrier
	s_waitcnt lgkmcnt(0)
	s_waitcnt lgkmcnt(0)
	v_mfma_f32_16x16x32_bf16 v[96:99], v[134:137], v[184:187], v[96:99]
	v_mfma_f32_16x16x32_bf16 v[92:95], v[220:223], v[184:187], v[92:95]
	v_mfma_f32_16x16x32_bf16 v[88:91], v[134:137], v[192:195], v[88:91]
	v_mfma_f32_16x16x32_bf16 v[84:87], v[220:223], v[192:195], v[84:87]
	v_mfma_f32_16x16x32_bf16 v[80:83], v[134:137], v[200:203], v[80:83]
	v_mfma_f32_16x16x32_bf16 v[76:79], v[220:223], v[200:203], v[76:79]
	v_mfma_f32_16x16x32_bf16 v[72:75], v[134:137], v[208:211], v[72:75]
	v_mfma_f32_16x16x32_bf16 v[68:71], v[220:223], v[208:211], v[68:71]
	v_mfma_f32_16x16x32_bf16 v[96:99], v[216:219], v[188:191], v[96:99]
	v_mfma_f32_16x16x32_bf16 v[92:95], v[176:179], v[188:191], v[92:95]
	v_mfma_f32_16x16x32_bf16 v[88:91], v[216:219], v[196:199], v[88:91]
	v_mfma_f32_16x16x32_bf16 v[84:87], v[176:179], v[196:199], v[84:87]
	v_mfma_f32_16x16x32_bf16 v[80:83], v[216:219], v[204:207], v[80:83]
	v_mfma_f32_16x16x32_bf16 v[76:79], v[176:179], v[204:207], v[76:79]
	v_mfma_f32_16x16x32_bf16 v[72:75], v[216:219], v[212:215], v[72:75]
	v_mfma_f32_16x16x32_bf16 v[68:71], v[176:179], v[212:215], v[68:71]
	s_barrier
	ds_read_b128 v[184:187], v161 offset:16384
	ds_read_b128 v[188:191], v161 offset:17408
	ds_read_b128 v[192:195], v160 offset:16384
	ds_read_b128 v[196:199], v160 offset:17408
	ds_read_b128 v[200:203], v159 offset:16384
	ds_read_b128 v[204:207], v159 offset:17408
	ds_read_b128 v[208:211], v158 offset:16384
	ds_read_b128 v[212:215], v158 offset:17408
	s_waitcnt vmcnt(4)
	s_barrier
	s_waitcnt lgkmcnt(0)
	s_waitcnt lgkmcnt(0)
	v_mfma_f32_16x16x32_bf16 v[64:67], v[138:141], v[184:187], v[64:67]
	v_mfma_f32_16x16x32_bf16 v[56:59], v[138:141], v[192:195], v[56:59]
	v_mfma_f32_16x16x32_bf16 v[48:51], v[138:141], v[200:203], v[48:51]
	v_mfma_f32_16x16x32_bf16 v[40:43], v[138:141], v[208:211], v[40:43]
	v_mfma_f32_16x16x32_bf16 v[36:39], v[172:175], v[208:211], v[36:39]
	v_mfma_f32_16x16x32_bf16 v[224:227], v[142:145], v[188:191], v[64:67]
	v_mfma_f32_16x16x32_bf16 v[60:63], v[172:175], v[184:187], v[60:63]
	v_mfma_f32_16x16x32_bf16 v[232:235], v[142:145], v[196:199], v[56:59]
	v_mfma_f32_16x16x32_bf16 v[52:55], v[172:175], v[192:195], v[52:55]
	v_mfma_f32_16x16x32_bf16 v[240:243], v[142:145], v[204:207], v[48:51]
	v_mfma_f32_16x16x32_bf16 v[44:47], v[172:175], v[200:203], v[44:47]
	v_mfma_f32_16x16x32_bf16 v[138:141], v[142:145], v[212:215], v[40:43]
	v_mfma_f32_16x16x32_bf16 v[142:145], v[180:183], v[212:215], v[36:39]
	v_mfma_f32_16x16x32_bf16 v[228:231], v[180:183], v[188:191], v[60:63]
	v_mfma_f32_16x16x32_bf16 v[236:239], v[180:183], v[196:199], v[52:55]
	v_mfma_f32_16x16x32_bf16 v[244:247], v[180:183], v[204:207], v[44:47]
	v_mfma_f32_16x16x32_bf16 v[8:11], v[134:137], v[208:211], v[8:11]
	v_mfma_f32_16x16x32_bf16 v[32:35], v[134:137], v[184:187], v[32:35]
	v_mfma_f32_16x16x32_bf16 v[28:31], v[220:223], v[184:187], v[28:31]
	v_mfma_f32_16x16x32_bf16 v[24:27], v[134:137], v[192:195], v[24:27]
	v_mfma_f32_16x16x32_bf16 v[20:23], v[220:223], v[192:195], v[20:23]
	v_mfma_f32_16x16x32_bf16 v[16:19], v[134:137], v[200:203], v[16:19]
	v_mfma_f32_16x16x32_bf16 v[12:15], v[220:223], v[200:203], v[12:15]
	v_mfma_f32_16x16x32_bf16 v[134:137], v[216:219], v[212:215], v[8:11]
	v_mfma_f32_16x16x32_bf16 v[2:5], v[220:223], v[208:211], v[4:7]
	v_mfma_f32_16x16x32_bf16 v[172:175], v[216:219], v[188:191], v[32:35]
	v_mfma_f32_16x16x32_bf16 v[180:183], v[176:179], v[188:191], v[28:31]
	v_mfma_f32_16x16x32_bf16 v[184:187], v[216:219], v[196:199], v[24:27]
	v_mfma_f32_16x16x32_bf16 v[188:191], v[176:179], v[196:199], v[20:23]
	v_mfma_f32_16x16x32_bf16 v[192:195], v[216:219], v[204:207], v[16:19]
	v_mfma_f32_16x16x32_bf16 v[196:199], v[176:179], v[204:207], v[12:15]
	v_mfma_f32_16x16x32_bf16 v[176:179], v[176:179], v[212:215], v[2:5]
	s_barrier
	ds_read_b128 v[200:203], v170
	ds_read_b128 v[204:207], v170 offset:1024
	ds_read_b128 v[208:211], v170 offset:2048
	ds_read_b128 v[168:171], v170 offset:3072
	ds_read_b128 v[22:25], v161 offset:32768
	ds_read_b128 v[34:37], v161 offset:33792
	ds_read_b128 v[38:41], v160 offset:32768
	ds_read_b128 v[50:53], v160 offset:33792
	ds_read_b128 v[54:57], v159 offset:32768
	ds_read_b128 v[58:61], v159 offset:33792
	ds_read_b128 v[62:65], v158 offset:32768
	ds_read_b128 v[212:215], v158 offset:33792
	s_waitcnt vmcnt(2)
	s_barrier
	s_waitcnt lgkmcnt(0)
	s_waitcnt lgkmcnt(0)
	v_mfma_f32_16x16x32_bf16 v[18:21], v[200:203], v[54:57], v[112:115]
	v_mfma_f32_16x16x32_bf16 v[26:29], v[204:207], v[58:61], v[18:21]
	v_mfma_f32_16x16x32_bf16 v[18:21], v[208:211], v[54:57], v[108:111]
	v_mfma_f32_16x16x32_bf16 v[30:33], v[168:171], v[58:61], v[18:21]
	v_mfma_f32_16x16x32_bf16 v[18:21], v[200:203], v[62:65], v[104:107]
	v_mfma_f32_16x16x32_bf16 v[2:5], v[200:203], v[22:25], v[128:131]
	v_mfma_f32_16x16x32_bf16 v[6:9], v[208:211], v[22:25], v[124:127]
	v_mfma_f32_16x16x32_bf16 v[10:13], v[200:203], v[38:41], v[120:123]
	v_mfma_f32_16x16x32_bf16 v[14:17], v[208:211], v[38:41], v[116:119]
	v_mfma_f32_16x16x32_bf16 v[42:45], v[204:207], v[212:215], v[18:21]
	v_mfma_f32_16x16x32_bf16 v[18:21], v[208:211], v[62:65], v[100:103]
	v_mfma_f32_16x16x32_bf16 v[2:5], v[204:207], v[34:37], v[2:5]
	v_mfma_f32_16x16x32_bf16 v[6:9], v[168:171], v[34:37], v[6:9]
	v_mfma_f32_16x16x32_bf16 v[10:13], v[204:207], v[50:53], v[10:13]
	v_mfma_f32_16x16x32_bf16 v[14:17], v[168:171], v[50:53], v[14:17]
	v_mfma_f32_16x16x32_bf16 v[46:49], v[168:171], v[212:215], v[18:21]
	s_barrier
	ds_read_b128 v[122:125], v167
	ds_read_b128 v[126:129], v167 offset:1024
	ds_read_b128 v[216:219], v167 offset:2048
	ds_read_b128 v[220:223], v167 offset:3072
	s_waitcnt vmcnt(0)
	s_barrier
	s_waitcnt lgkmcnt(0)
	s_waitcnt lgkmcnt(0)
	v_mfma_f32_16x16x32_bf16 v[18:21], v[122:125], v[22:25], v[96:99]
	v_mfma_f32_16x16x32_bf16 v[22:25], v[216:219], v[22:25], v[92:95]
	v_mfma_f32_16x16x32_bf16 v[18:21], v[126:129], v[34:37], v[18:21]
	v_mfma_f32_16x16x32_bf16 v[22:25], v[220:223], v[34:37], v[22:25]
	v_mfma_f32_16x16x32_bf16 v[34:37], v[122:125], v[38:41], v[88:91]
	v_mfma_f32_16x16x32_bf16 v[38:41], v[216:219], v[38:41], v[84:87]
	v_mfma_f32_16x16x32_bf16 v[34:37], v[126:129], v[50:53], v[34:37]
	v_mfma_f32_16x16x32_bf16 v[38:41], v[220:223], v[50:53], v[38:41]
	v_mfma_f32_16x16x32_bf16 v[50:53], v[122:125], v[54:57], v[80:83]
	v_mfma_f32_16x16x32_bf16 v[54:57], v[216:219], v[54:57], v[76:79]
	v_mfma_f32_16x16x32_bf16 v[50:53], v[126:129], v[58:61], v[50:53]
	v_mfma_f32_16x16x32_bf16 v[54:57], v[220:223], v[58:61], v[54:57]
	v_mfma_f32_16x16x32_bf16 v[58:61], v[122:125], v[62:65], v[72:75]
	v_mfma_f32_16x16x32_bf16 v[62:65], v[216:219], v[62:65], v[68:71]
	v_mfma_f32_16x16x32_bf16 v[58:61], v[126:129], v[212:215], v[58:61]
	v_mfma_f32_16x16x32_bf16 v[62:65], v[220:223], v[212:215], v[62:65]
	s_barrier
	ds_read_b128 v[86:89], v161 offset:49152
	ds_read_b128 v[94:97], v161 offset:50176
	ds_read_b128 v[102:105], v160 offset:49152
	ds_read_b128 v[110:113], v160 offset:50176
	ds_read_b128 v[118:121], v159 offset:49152
	ds_read_b128 v[160:163], v159 offset:50176
	ds_read_b128 v[212:215], v158 offset:49152
	ds_read_b128 v[248:251], v158 offset:50176
	s_barrier
	s_waitcnt lgkmcnt(0)
	s_waitcnt lgkmcnt(0)
	v_mfma_f32_16x16x32_bf16 v[78:81], v[208:211], v[102:105], v[236:239]
	v_mfma_f32_16x16x32_bf16 v[82:85], v[168:171], v[110:113], v[78:81]
	v_mfma_f32_16x16x32_bf16 v[78:81], v[200:203], v[118:121], v[240:243]
	v_mfma_f32_16x16x32_bf16 v[90:93], v[204:207], v[160:163], v[78:81]
	v_mfma_f32_16x16x32_bf16 v[78:81], v[208:211], v[118:121], v[244:247]
	v_mfma_f32_16x16x32_bf16 v[98:101], v[168:171], v[160:163], v[78:81]
	v_mfma_f32_16x16x32_bf16 v[78:81], v[200:203], v[212:215], v[138:141]
	v_mfma_f32_16x16x32_bf16 v[66:69], v[200:203], v[86:89], v[224:227]
	v_mfma_f32_16x16x32_bf16 v[70:73], v[208:211], v[86:89], v[228:231]
	v_mfma_f32_16x16x32_bf16 v[74:77], v[200:203], v[102:105], v[232:235]
	v_mfma_f32_16x16x32_bf16 v[106:109], v[204:207], v[248:251], v[78:81]
	v_mfma_f32_16x16x32_bf16 v[78:81], v[208:211], v[212:215], v[142:145]
	v_mfma_f32_16x16x32_bf16 v[66:69], v[204:207], v[94:97], v[66:69]
	v_mfma_f32_16x16x32_bf16 v[70:73], v[168:171], v[94:97], v[70:73]
	v_mfma_f32_16x16x32_bf16 v[74:77], v[204:207], v[110:113], v[74:77]
	v_mfma_f32_16x16x32_bf16 v[114:117], v[168:171], v[248:251], v[78:81]
	v_mfma_f32_16x16x32_bf16 v[78:81], v[122:125], v[86:89], v[172:175]
	v_mfma_f32_16x16x32_bf16 v[86:89], v[216:219], v[86:89], v[180:183]
	v_mfma_f32_16x16x32_bf16 v[78:81], v[126:129], v[94:97], v[78:81]
	v_mfma_f32_16x16x32_bf16 v[86:89], v[220:223], v[94:97], v[86:89]
	v_mfma_f32_16x16x32_bf16 v[94:97], v[122:125], v[102:105], v[184:187]
	v_mfma_f32_16x16x32_bf16 v[102:105], v[216:219], v[102:105], v[188:191]
	v_mfma_f32_16x16x32_bf16 v[94:97], v[126:129], v[110:113], v[94:97]
	v_mfma_f32_16x16x32_bf16 v[102:105], v[220:223], v[110:113], v[102:105]
	v_mfma_f32_16x16x32_bf16 v[110:113], v[122:125], v[118:121], v[192:195]
	v_mfma_f32_16x16x32_bf16 v[122:125], v[122:125], v[212:215], v[134:137]
	v_mfma_f32_16x16x32_bf16 v[110:113], v[126:129], v[160:163], v[110:113]
	v_mfma_f32_16x16x32_bf16 v[118:121], v[216:219], v[118:121], v[196:199]
	v_mfma_f32_16x16x32_bf16 v[122:125], v[126:129], v[248:251], v[122:125]
	v_mfma_f32_16x16x32_bf16 v[126:129], v[216:219], v[212:215], v[176:179]
	v_mfma_f32_16x16x32_bf16 v[118:121], v[220:223], v[160:163], v[118:121]
	v_mfma_f32_16x16x32_bf16 v[126:129], v[220:223], v[248:251], v[126:129]
	v_and_b32_e32 v0, 0xffffff00, v149
	v_lshlrev_b32_e32 v130, 2, v155
	v_add3_u32 v131, s70, v0, v130
	v_add3_u32 v0, s71, v0, v130
	s_barrier
	ds_read2_b32 v[136:137], v131 offset1:16
	ds_read2_b32 v[138:139], v131 offset0:32 offset1:48
	ds_read2_b32 v[142:143], v0 offset1:16
	ds_read2_b32 v[146:147], v0 offset0:32 offset1:48
	v_cmp_gt_u32_e32 vcc, s55, v149
	s_waitcnt lgkmcnt(0)
	v_mov_b32_e32 v0, v137
	v_mov_b32_e32 v140, v139
	v_mov_b32_e32 v144, v143
	v_mov_b32_e32 v134, v147
	s_and_saveexec_b64 s[4:5], vcc
	s_cbranch_execz .LBB0_1487
	s_barrier
	s_branch .LBB0_1487

.LBB0_1661:
	ds_read_b128 v[180:183], v172
	ds_read_b128 v[184:187], v172 offset:1024
	ds_read_b128 v[188:191], v172 offset:2048
	ds_read_b128 v[192:195], v172 offset:3072
	v_add_u32_e32 v178, 0xc000, v152
	v_lshl_add_u64 v[244:245], s[8:9], 0, v[146:147]
	v_readfirstlane_b32 s1, v178
	v_add_u32_e32 v179, 0xe000, v152
	v_lshl_add_u64 v[224:225], v[244:245], 0, s[12:13]
	s_mov_b32 m0, s1
	v_lshl_add_u64 v[246:247], s[8:9], 0, v[148:149]
	v_readfirstlane_b32 s1, v179
	ds_read_b128 v[174:177], v161
	ds_read_b128 v[196:199], v161 offset:1024
	ds_read_b128 v[200:203], v160
	ds_read_b128 v[204:207], v160 offset:1024
	ds_read_b128 v[208:211], v159
	ds_read_b128 v[212:215], v159 offset:1024
	ds_read_b128 v[216:219], v158
	ds_read_b128 v[220:223], v158 offset:1024
	global_load_lds_dwordx4 v[224:225], off
	v_lshl_add_u64 v[224:225], v[246:247], 0, s[12:13]
	s_mov_b32 m0, s1
	s_nop 0
	global_load_lds_dwordx4 v[224:225], off
	s_waitcnt lgkmcnt(8)
	s_barrier
	s_waitcnt lgkmcnt(0)
	s_waitcnt lgkmcnt(0)
	v_mfma_f32_16x16x32_bf16 v[124:127], v[180:183], v[174:177], v[124:127]
	v_mfma_f32_16x16x32_bf16 v[120:123], v[188:191], v[174:177], v[120:123]
	v_mfma_f32_16x16x32_bf16 v[116:119], v[180:183], v[200:203], v[116:119]
	v_mfma_f32_16x16x32_bf16 v[112:115], v[188:191], v[200:203], v[112:115]
	v_mfma_f32_16x16x32_bf16 v[108:111], v[180:183], v[208:211], v[108:111]
	v_mfma_f32_16x16x32_bf16 v[104:107], v[188:191], v[208:211], v[104:107]
	v_mfma_f32_16x16x32_bf16 v[100:103], v[180:183], v[216:219], v[100:103]
	v_mfma_f32_16x16x32_bf16 v[96:99], v[188:191], v[216:219], v[96:99]
	v_mfma_f32_16x16x32_bf16 v[124:127], v[184:187], v[196:199], v[124:127]
	v_mfma_f32_16x16x32_bf16 v[120:123], v[192:195], v[196:199], v[120:123]
	v_mfma_f32_16x16x32_bf16 v[116:119], v[184:187], v[204:207], v[116:119]
	v_mfma_f32_16x16x32_bf16 v[112:115], v[192:195], v[204:207], v[112:115]
	v_mfma_f32_16x16x32_bf16 v[108:111], v[184:187], v[212:215], v[108:111]
	v_mfma_f32_16x16x32_bf16 v[104:107], v[192:195], v[212:215], v[104:107]
	v_mfma_f32_16x16x32_bf16 v[100:103], v[184:187], v[220:223], v[100:103]
	v_mfma_f32_16x16x32_bf16 v[96:99], v[192:195], v[220:223], v[96:99]
	s_barrier
	v_lshl_add_u64 v[248:249], s[8:9], 0, v[142:143]
	v_readfirstlane_b32 s1, v153
	v_add_u32_e32 v173, 0x2000, v153
	v_lshl_add_u64 v[240:241], v[248:249], 0, s[14:15]
	s_mov_b32 m0, s1
	v_lshl_add_u64 v[250:251], s[8:9], 0, v[144:145]
	v_readfirstlane_b32 s1, v173
	ds_read_b128 v[224:227], v168
	ds_read_b128 v[228:231], v168 offset:1024
	ds_read_b128 v[232:235], v168 offset:2048
	ds_read_b128 v[236:239], v168 offset:3072
	global_load_lds_dwordx4 v[240:241], off
	v_lshl_add_u64 v[240:241], v[250:251], 0, s[14:15]
	s_mov_b32 m0, s1
	s_nop 0
	global_load_lds_dwordx4 v[240:241], off
	s_barrier
	s_waitcnt lgkmcnt(0)
	s_waitcnt lgkmcnt(0)
	v_mfma_f32_16x16x32_bf16 v[92:95], v[224:227], v[174:177], v[92:95]
	v_mfma_f32_16x16x32_bf16 v[88:91], v[232:235], v[174:177], v[88:91]
	v_mfma_f32_16x16x32_bf16 v[84:87], v[224:227], v[200:203], v[84:87]
	v_mfma_f32_16x16x32_bf16 v[80:83], v[232:235], v[200:203], v[80:83]
	v_mfma_f32_16x16x32_bf16 v[76:79], v[224:227], v[208:211], v[76:79]
	v_mfma_f32_16x16x32_bf16 v[72:75], v[232:235], v[208:211], v[72:75]
	v_mfma_f32_16x16x32_bf16 v[68:71], v[224:227], v[216:219], v[68:71]
	v_mfma_f32_16x16x32_bf16 v[64:67], v[232:235], v[216:219], v[64:67]
	v_mfma_f32_16x16x32_bf16 v[92:95], v[228:231], v[196:199], v[92:95]
	v_mfma_f32_16x16x32_bf16 v[88:91], v[236:239], v[196:199], v[88:91]
	v_mfma_f32_16x16x32_bf16 v[84:87], v[228:231], v[204:207], v[84:87]
	v_mfma_f32_16x16x32_bf16 v[80:83], v[236:239], v[204:207], v[80:83]
	v_mfma_f32_16x16x32_bf16 v[76:79], v[228:231], v[212:215], v[76:79]
	v_mfma_f32_16x16x32_bf16 v[72:75], v[236:239], v[212:215], v[72:75]
	v_mfma_f32_16x16x32_bf16 v[68:71], v[228:231], v[220:223], v[68:71]
	v_mfma_f32_16x16x32_bf16 v[64:67], v[236:239], v[220:223], v[64:67]
	v_readfirstlane_b32 s1, v152
	v_lshl_add_u64 v[174:175], v[244:245], 0, s[16:17]
	s_mov_b32 m0, s1
	s_barrier
	ds_read_b128 v[196:199], v161 offset:16384
	ds_read_b128 v[200:203], v161 offset:17408
	ds_read_b128 v[204:207], v160 offset:16384
	ds_read_b128 v[208:211], v160 offset:17408
	ds_read_b128 v[212:215], v159 offset:16384
	ds_read_b128 v[216:219], v159 offset:17408
	ds_read_b128 v[220:223], v158 offset:16384
	ds_read_b128 v[240:243], v158 offset:17408
	global_load_lds_dwordx4 v[174:175], off
	v_add_u32_e32 v174, 0x2000, v152
	v_lshl_add_u64 v[176:177], v[246:247], 0, s[16:17]
	v_readfirstlane_b32 s1, v174
	s_mov_b32 m0, s1
	s_nop 0
	global_load_lds_dwordx4 v[176:177], off
	s_barrier
	s_waitcnt lgkmcnt(0)
	s_waitcnt lgkmcnt(0)
	v_mfma_f32_16x16x32_bf16 v[60:63], v[180:183], v[196:199], v[60:63]
	v_mfma_f32_16x16x32_bf16 v[56:59], v[188:191], v[196:199], v[56:59]
	v_mfma_f32_16x16x32_bf16 v[52:55], v[180:183], v[204:207], v[52:55]
	v_mfma_f32_16x16x32_bf16 v[48:51], v[188:191], v[204:207], v[48:51]
	v_mfma_f32_16x16x32_bf16 v[44:47], v[180:183], v[212:215], v[44:47]
	v_mfma_f32_16x16x32_bf16 v[40:43], v[188:191], v[212:215], v[40:43]
	v_mfma_f32_16x16x32_bf16 v[36:39], v[180:183], v[220:223], v[36:39]
	v_mfma_f32_16x16x32_bf16 v[32:35], v[188:191], v[220:223], v[32:35]
	v_mfma_f32_16x16x32_bf16 v[60:63], v[184:187], v[200:203], v[60:63]
	v_mfma_f32_16x16x32_bf16 v[56:59], v[192:195], v[200:203], v[56:59]
	v_mfma_f32_16x16x32_bf16 v[52:55], v[184:187], v[208:211], v[52:55]
	v_mfma_f32_16x16x32_bf16 v[48:51], v[192:195], v[208:211], v[48:51]
	v_mfma_f32_16x16x32_bf16 v[44:47], v[184:187], v[216:219], v[44:47]
	v_mfma_f32_16x16x32_bf16 v[40:43], v[192:195], v[216:219], v[40:43]
	v_mfma_f32_16x16x32_bf16 v[36:39], v[184:187], v[240:243], v[36:39]
	v_mfma_f32_16x16x32_bf16 v[32:35], v[192:195], v[240:243], v[32:35]
	s_barrier
	v_readfirstlane_b32 s1, v151
	v_add_u32_e32 v175, 0x2000, v151
	v_lshl_add_u64 v[176:177], v[248:249], 0, s[18:19]
	s_mov_b32 m0, s1
	v_readfirstlane_b32 s1, v175
	global_load_lds_dwordx4 v[176:177], off
	v_lshl_add_u64 v[176:177], v[250:251], 0, s[18:19]
	s_mov_b32 m0, s1
	s_nop 0
	global_load_lds_dwordx4 v[176:177], off
	s_waitcnt vmcnt(6)
	s_barrier
	v_mfma_f32_16x16x32_bf16 v[28:31], v[224:227], v[196:199], v[28:31]
	v_mfma_f32_16x16x32_bf16 v[24:27], v[232:235], v[196:199], v[24:27]
	v_mfma_f32_16x16x32_bf16 v[20:23], v[224:227], v[204:207], v[20:23]
	v_mfma_f32_16x16x32_bf16 v[16:19], v[232:235], v[204:207], v[16:19]
	v_mfma_f32_16x16x32_bf16 v[12:15], v[224:227], v[212:215], v[12:15]
	v_mfma_f32_16x16x32_bf16 v[8:11], v[232:235], v[212:215], v[8:11]
	v_mfma_f32_16x16x32_bf16 v[4:7], v[224:227], v[220:223], v[4:7]
	v_mfma_f32_16x16x32_bf16 v[0:3], v[232:235], v[220:223], v[0:3]
	v_mfma_f32_16x16x32_bf16 v[28:31], v[228:231], v[200:203], v[28:31]
	v_mfma_f32_16x16x32_bf16 v[24:27], v[236:239], v[200:203], v[24:27]
	v_mfma_f32_16x16x32_bf16 v[20:23], v[228:231], v[208:211], v[20:23]
	v_mfma_f32_16x16x32_bf16 v[16:19], v[236:239], v[208:211], v[16:19]
	v_mfma_f32_16x16x32_bf16 v[12:15], v[228:231], v[216:219], v[12:15]
	v_mfma_f32_16x16x32_bf16 v[8:11], v[236:239], v[216:219], v[8:11]
	v_mfma_f32_16x16x32_bf16 v[4:7], v[228:231], v[240:243], v[4:7]
	v_mfma_f32_16x16x32_bf16 v[0:3], v[236:239], v[240:243], v[0:3]
	s_barrier
	ds_read_b128 v[180:183], v163
	ds_read_b128 v[184:187], v163 offset:1024
	ds_read_b128 v[188:191], v163 offset:2048
	ds_read_b128 v[192:195], v163 offset:3072
	v_add_u32_e32 v176, 0x4000, v152
	v_add_u32_e32 v177, 0x6000, v152
	v_readfirstlane_b32 s1, v176
	v_lshl_add_u64 v[228:229], v[244:245], 0, s[20:21]
	s_mov_b32 m0, s1
	v_readfirstlane_b32 s1, v177
	ds_read_b128 v[196:199], v161 offset:32768
	ds_read_b128 v[200:203], v161 offset:33792
	ds_read_b128 v[204:207], v160 offset:32768
	ds_read_b128 v[208:211], v160 offset:33792
	ds_read_b128 v[212:215], v159 offset:32768
	ds_read_b128 v[216:219], v159 offset:33792
	ds_read_b128 v[220:223], v158 offset:32768
	ds_read_b128 v[224:227], v158 offset:33792
	global_load_lds_dwordx4 v[228:229], off
	v_lshl_add_u64 v[228:229], v[246:247], 0, s[20:21]
	s_mov_b32 m0, s1
	s_nop 0
	global_load_lds_dwordx4 v[228:229], off
	s_waitcnt lgkmcnt(8)
	s_barrier
	s_waitcnt lgkmcnt(0)
	s_waitcnt lgkmcnt(0)
	v_mfma_f32_16x16x32_bf16 v[124:127], v[180:183], v[196:199], v[124:127]
	v_mfma_f32_16x16x32_bf16 v[120:123], v[188:191], v[196:199], v[120:123]
	v_mfma_f32_16x16x32_bf16 v[116:119], v[180:183], v[204:207], v[116:119]
	v_mfma_f32_16x16x32_bf16 v[112:115], v[188:191], v[204:207], v[112:115]
	v_mfma_f32_16x16x32_bf16 v[108:111], v[180:183], v[212:215], v[108:111]
	v_mfma_f32_16x16x32_bf16 v[104:107], v[188:191], v[212:215], v[104:107]
	v_mfma_f32_16x16x32_bf16 v[100:103], v[180:183], v[220:223], v[100:103]
	v_mfma_f32_16x16x32_bf16 v[96:99], v[188:191], v[220:223], v[96:99]
	v_mfma_f32_16x16x32_bf16 v[124:127], v[184:187], v[200:203], v[124:127]
	v_mfma_f32_16x16x32_bf16 v[120:123], v[192:195], v[200:203], v[120:123]
	v_mfma_f32_16x16x32_bf16 v[116:119], v[184:187], v[208:211], v[116:119]
	v_mfma_f32_16x16x32_bf16 v[112:115], v[192:195], v[208:211], v[112:115]
	v_mfma_f32_16x16x32_bf16 v[108:111], v[184:187], v[216:219], v[108:111]
	v_mfma_f32_16x16x32_bf16 v[104:107], v[192:195], v[216:219], v[104:107]
	v_mfma_f32_16x16x32_bf16 v[100:103], v[184:187], v[224:227], v[100:103]
	v_mfma_f32_16x16x32_bf16 v[96:99], v[192:195], v[224:227], v[96:99]
	s_barrier
	v_readfirstlane_b32 s1, v167
	v_add_u32_e32 v254, 0x2000, v167
	v_lshl_add_u64 v[252:253], v[248:249], 0, s[24:25]
	s_mov_b32 m0, s1
	v_readfirstlane_b32 s1, v254
	ds_read_b128 v[228:231], v162
	ds_read_b128 v[232:235], v162 offset:1024
	ds_read_b128 v[236:239], v162 offset:2048
	ds_read_b128 v[240:243], v162 offset:3072
	global_load_lds_dwordx4 v[252:253], off
	v_lshl_add_u64 v[252:253], v[250:251], 0, s[24:25]
	s_mov_b32 m0, s1
	s_nop 0
	global_load_lds_dwordx4 v[252:253], off
	s_barrier
	s_waitcnt lgkmcnt(0)
	s_waitcnt lgkmcnt(0)
	v_mfma_f32_16x16x32_bf16 v[92:95], v[228:231], v[196:199], v[92:95]
	v_mfma_f32_16x16x32_bf16 v[88:91], v[236:239], v[196:199], v[88:91]
	v_mfma_f32_16x16x32_bf16 v[84:87], v[228:231], v[204:207], v[84:87]
	v_mfma_f32_16x16x32_bf16 v[80:83], v[236:239], v[204:207], v[80:83]
	v_mfma_f32_16x16x32_bf16 v[76:79], v[228:231], v[212:215], v[76:79]
	v_mfma_f32_16x16x32_bf16 v[72:75], v[236:239], v[212:215], v[72:75]
	v_mfma_f32_16x16x32_bf16 v[68:71], v[228:231], v[220:223], v[68:71]
	v_mfma_f32_16x16x32_bf16 v[64:67], v[236:239], v[220:223], v[64:67]
	v_mfma_f32_16x16x32_bf16 v[92:95], v[232:235], v[200:203], v[92:95]
	v_mfma_f32_16x16x32_bf16 v[88:91], v[240:243], v[200:203], v[88:91]
	v_mfma_f32_16x16x32_bf16 v[84:87], v[232:235], v[208:211], v[84:87]
	v_mfma_f32_16x16x32_bf16 v[80:83], v[240:243], v[208:211], v[80:83]
	v_mfma_f32_16x16x32_bf16 v[76:79], v[232:235], v[216:219], v[76:79]
	v_mfma_f32_16x16x32_bf16 v[72:75], v[240:243], v[216:219], v[72:75]
	v_mfma_f32_16x16x32_bf16 v[68:71], v[232:235], v[224:227], v[68:71]
	v_mfma_f32_16x16x32_bf16 v[64:67], v[240:243], v[224:227], v[64:67]
	v_readfirstlane_b32 s1, v169
	v_lshl_add_u64 v[244:245], v[244:245], 0, s[26:27]
	s_mov_b32 m0, s1
	v_readfirstlane_b32 s1, v170
	s_barrier
	ds_read_b128 v[196:199], v161 offset:49152
	ds_read_b128 v[200:203], v161 offset:50176
	ds_read_b128 v[204:207], v160 offset:49152
	ds_read_b128 v[208:211], v160 offset:50176
	ds_read_b128 v[212:215], v159 offset:49152
	ds_read_b128 v[216:219], v159 offset:50176
	ds_read_b128 v[220:223], v158 offset:49152
	ds_read_b128 v[224:227], v158 offset:50176
	global_load_lds_dwordx4 v[244:245], off
	v_lshl_add_u64 v[244:245], v[246:247], 0, s[26:27]
	s_mov_b32 m0, s1
	s_nop 0
	global_load_lds_dwordx4 v[244:245], off
	s_barrier
	s_waitcnt lgkmcnt(0)
	s_waitcnt lgkmcnt(0)
	v_mfma_f32_16x16x32_bf16 v[60:63], v[180:183], v[196:199], v[60:63]
	v_mfma_f32_16x16x32_bf16 v[56:59], v[188:191], v[196:199], v[56:59]
	v_mfma_f32_16x16x32_bf16 v[52:55], v[180:183], v[204:207], v[52:55]
	v_mfma_f32_16x16x32_bf16 v[48:51], v[188:191], v[204:207], v[48:51]
	v_mfma_f32_16x16x32_bf16 v[44:47], v[180:183], v[212:215], v[44:47]
	v_mfma_f32_16x16x32_bf16 v[40:43], v[188:191], v[212:215], v[40:43]
	v_mfma_f32_16x16x32_bf16 v[36:39], v[180:183], v[220:223], v[36:39]
	v_mfma_f32_16x16x32_bf16 v[32:35], v[188:191], v[220:223], v[32:35]
	v_mfma_f32_16x16x32_bf16 v[60:63], v[184:187], v[200:203], v[60:63]
	v_mfma_f32_16x16x32_bf16 v[56:59], v[192:195], v[200:203], v[56:59]
	v_mfma_f32_16x16x32_bf16 v[52:55], v[184:187], v[208:211], v[52:55]
	v_mfma_f32_16x16x32_bf16 v[48:51], v[192:195], v[208:211], v[48:51]
	v_mfma_f32_16x16x32_bf16 v[44:47], v[184:187], v[216:219], v[44:47]
	v_mfma_f32_16x16x32_bf16 v[40:43], v[192:195], v[216:219], v[40:43]
	v_mfma_f32_16x16x32_bf16 v[36:39], v[184:187], v[224:227], v[36:39]
	v_mfma_f32_16x16x32_bf16 v[32:35], v[192:195], v[224:227], v[32:35]
	s_barrier
	v_readfirstlane_b32 s1, v171
	v_add_u32_e32 v182, 0x2000, v171
	v_lshl_add_u64 v[180:181], v[248:249], 0, s[28:29]
	s_mov_b32 m0, s1
	v_readfirstlane_b32 s1, v182
	global_load_lds_dwordx4 v[180:181], off
	v_lshl_add_u64 v[180:181], v[250:251], 0, s[28:29]
	s_mov_b32 m0, s1
	s_nop 0
	global_load_lds_dwordx4 v[180:181], off
	s_waitcnt vmcnt(6)
	s_barrier
	v_mfma_f32_16x16x32_bf16 v[28:31], v[228:231], v[196:199], v[28:31]
	v_mfma_f32_16x16x32_bf16 v[24:27], v[236:239], v[196:199], v[24:27]
	v_mfma_f32_16x16x32_bf16 v[20:23], v[228:231], v[204:207], v[20:23]
	v_mfma_f32_16x16x32_bf16 v[16:19], v[236:239], v[204:207], v[16:19]
	v_mfma_f32_16x16x32_bf16 v[12:15], v[228:231], v[212:215], v[12:15]
	v_mfma_f32_16x16x32_bf16 v[8:11], v[236:239], v[212:215], v[8:11]
	v_mfma_f32_16x16x32_bf16 v[4:7], v[228:231], v[220:223], v[4:7]
	v_mfma_f32_16x16x32_bf16 v[0:3], v[236:239], v[220:223], v[0:3]
	v_mfma_f32_16x16x32_bf16 v[28:31], v[232:235], v[200:203], v[28:31]
	v_mfma_f32_16x16x32_bf16 v[24:27], v[240:243], v[200:203], v[24:27]
	v_mfma_f32_16x16x32_bf16 v[20:23], v[232:235], v[208:211], v[20:23]
	v_mfma_f32_16x16x32_bf16 v[16:19], v[240:243], v[208:211], v[16:19]
	v_mfma_f32_16x16x32_bf16 v[12:15], v[232:235], v[216:219], v[12:15]
	v_mfma_f32_16x16x32_bf16 v[8:11], v[240:243], v[216:219], v[8:11]
	v_mfma_f32_16x16x32_bf16 v[4:7], v[232:235], v[224:227], v[4:7]
	v_mfma_f32_16x16x32_bf16 v[0:3], v[240:243], v[224:227], v[0:3]
	s_add_i32 s0, s0, 2
	v_lshl_add_u64 v[142:143], v[142:143], 0, s[30:31]
	v_lshl_add_u64 v[144:145], v[144:145], 0, s[30:31]
	v_lshl_add_u64 v[146:147], v[146:147], 0, s[30:31]
	s_cmp_lt_u32 s0, 12
	v_lshl_add_u64 v[148:149], v[148:149], 0, s[30:31]
	s_barrier
	s_cbranch_scc1 .LBB0_1661
	s_or_b32 s0, s36, 0x80
	s_ashr_i32 s1, s0, 31
	s_lshl_b64 s[0:1], s[0:1], 11
	s_add_u32 s0, s39, s0
	s_addc_u32 s1, s46, s1
	v_lshl_add_u64 v[170:171], s[0:1], 0, v[130:131]
	v_lshl_add_u64 v[138:139], v[138:139], 1, v[170:171]
	v_readfirstlane_b32 s2, v178
	v_lshl_add_u64 v[138:139], v[138:139], 0, s[34:35]
	s_mov_b32 m0, s2
	ds_read_b128 v[142:145], v172
	ds_read_b128 v[146:149], v172 offset:1024
	ds_read_b128 v[180:183], v172 offset:2048
	ds_read_b128 v[184:187], v172 offset:3072
	ds_read_b128 v[188:191], v161
	ds_read_b128 v[192:195], v161 offset:1024
	ds_read_b128 v[196:199], v160
	ds_read_b128 v[200:203], v160 offset:1024
	ds_read_b128 v[204:207], v159
	ds_read_b128 v[208:211], v159 offset:1024
	ds_read_b128 v[212:215], v158
	ds_read_b128 v[216:219], v158 offset:1024
	global_load_lds_dwordx4 v[138:139], off
	v_lshl_add_u64 v[138:139], s[0:1], 0, v[134:135]
	v_lshl_add_u64 v[138:139], v[140:141], 1, v[138:139]
	v_readfirstlane_b32 s0, v179
	v_lshl_add_u64 v[138:139], v[138:139], 0, s[34:35]
	s_mov_b32 m0, s0
	v_readlane_b32 s0, v255, 11
	global_load_lds_dwordx4 v[138:139], off
	s_add_i32 s70, s70, s0
	s_barrier
	s_waitcnt lgkmcnt(0)
	s_cmpk_gt_i32 s70, 0x7f
	s_cselect_b64 s[58:59], -1, 0
	s_waitcnt lgkmcnt(0)
	v_mfma_f32_16x16x32_bf16 v[124:127], v[142:145], v[188:191], v[124:127]
	v_mfma_f32_16x16x32_bf16 v[120:123], v[180:183], v[188:191], v[120:123]
	v_mfma_f32_16x16x32_bf16 v[116:119], v[142:145], v[196:199], v[116:119]
	v_mfma_f32_16x16x32_bf16 v[112:115], v[180:183], v[196:199], v[112:115]
	v_mfma_f32_16x16x32_bf16 v[108:111], v[142:145], v[204:207], v[108:111]
	v_mfma_f32_16x16x32_bf16 v[104:107], v[180:183], v[204:207], v[104:107]
	v_mfma_f32_16x16x32_bf16 v[100:103], v[142:145], v[212:215], v[100:103]
	v_mfma_f32_16x16x32_bf16 v[96:99], v[180:183], v[212:215], v[96:99]
	v_mfma_f32_16x16x32_bf16 v[124:127], v[146:149], v[192:195], v[124:127]
	v_mfma_f32_16x16x32_bf16 v[120:123], v[184:187], v[192:195], v[120:123]
	v_mfma_f32_16x16x32_bf16 v[116:119], v[146:149], v[200:203], v[116:119]
	v_mfma_f32_16x16x32_bf16 v[112:115], v[184:187], v[200:203], v[112:115]
	v_mfma_f32_16x16x32_bf16 v[108:111], v[146:149], v[208:211], v[108:111]
	v_mfma_f32_16x16x32_bf16 v[104:107], v[184:187], v[208:211], v[104:107]
	v_mfma_f32_16x16x32_bf16 v[100:103], v[146:149], v[216:219], v[100:103]
	v_mfma_f32_16x16x32_bf16 v[96:99], v[184:187], v[216:219], v[96:99]
	s_barrier
	ds_read_b128 v[138:141], v168
	ds_read_b128 v[220:223], v168 offset:1024
	ds_read_b128 v[224:227], v168 offset:2048
	ds_read_b128 v[168:171], v168 offset:3072
	s_barrier
	s_waitcnt lgkmcnt(0)
	s_waitcnt lgkmcnt(0)
	v_mfma_f32_16x16x32_bf16 v[92:95], v[138:141], v[188:191], v[92:95]
	v_mfma_f32_16x16x32_bf16 v[88:91], v[224:227], v[188:191], v[88:91]
	v_mfma_f32_16x16x32_bf16 v[84:87], v[138:141], v[196:199], v[84:87]
	v_mfma_f32_16x16x32_bf16 v[80:83], v[224:227], v[196:199], v[80:83]
	v_mfma_f32_16x16x32_bf16 v[76:79], v[138:141], v[204:207], v[76:79]
	v_mfma_f32_16x16x32_bf16 v[72:75], v[224:227], v[204:207], v[72:75]
	v_mfma_f32_16x16x32_bf16 v[68:71], v[138:141], v[212:215], v[68:71]
	v_mfma_f32_16x16x32_bf16 v[64:67], v[224:227], v[212:215], v[64:67]
	v_mfma_f32_16x16x32_bf16 v[92:95], v[220:223], v[192:195], v[92:95]
	v_mfma_f32_16x16x32_bf16 v[88:91], v[168:171], v[192:195], v[88:91]
	v_mfma_f32_16x16x32_bf16 v[84:87], v[220:223], v[200:203], v[84:87]
	v_mfma_f32_16x16x32_bf16 v[80:83], v[168:171], v[200:203], v[80:83]
	v_mfma_f32_16x16x32_bf16 v[76:79], v[220:223], v[208:211], v[76:79]
	v_mfma_f32_16x16x32_bf16 v[72:75], v[168:171], v[208:211], v[72:75]
	v_mfma_f32_16x16x32_bf16 v[68:71], v[220:223], v[216:219], v[68:71]
	v_mfma_f32_16x16x32_bf16 v[64:67], v[168:171], v[216:219], v[64:67]
	s_barrier
	ds_read_b128 v[188:191], v161 offset:16384
	ds_read_b128 v[192:195], v161 offset:17408
	ds_read_b128 v[196:199], v160 offset:16384
	ds_read_b128 v[200:203], v160 offset:17408
	ds_read_b128 v[204:207], v159 offset:16384
	ds_read_b128 v[208:211], v159 offset:17408
	ds_read_b128 v[212:215], v158 offset:16384
	ds_read_b128 v[216:219], v158 offset:17408
	s_waitcnt vmcnt(4)
	s_barrier
	s_waitcnt lgkmcnt(0)
	s_waitcnt lgkmcnt(0)
	v_mfma_f32_16x16x32_bf16 v[60:63], v[142:145], v[188:191], v[60:63]
	v_mfma_f32_16x16x32_bf16 v[56:59], v[180:183], v[188:191], v[56:59]
	v_mfma_f32_16x16x32_bf16 v[52:55], v[142:145], v[196:199], v[52:55]
	v_mfma_f32_16x16x32_bf16 v[48:51], v[180:183], v[196:199], v[48:51]
	v_mfma_f32_16x16x32_bf16 v[44:47], v[142:145], v[204:207], v[44:47]
	v_mfma_f32_16x16x32_bf16 v[40:43], v[180:183], v[204:207], v[40:43]
	v_mfma_f32_16x16x32_bf16 v[36:39], v[142:145], v[212:215], v[36:39]
	v_mfma_f32_16x16x32_bf16 v[32:35], v[180:183], v[212:215], v[32:35]
	v_mfma_f32_16x16x32_bf16 v[60:63], v[146:149], v[192:195], v[60:63]
	v_mfma_f32_16x16x32_bf16 v[56:59], v[184:187], v[192:195], v[56:59]
	v_mfma_f32_16x16x32_bf16 v[52:55], v[146:149], v[200:203], v[52:55]
	v_mfma_f32_16x16x32_bf16 v[48:51], v[184:187], v[200:203], v[48:51]
	v_mfma_f32_16x16x32_bf16 v[44:47], v[146:149], v[208:211], v[44:47]
	v_mfma_f32_16x16x32_bf16 v[40:43], v[184:187], v[208:211], v[40:43]
	v_mfma_f32_16x16x32_bf16 v[36:39], v[146:149], v[216:219], v[36:39]
	v_mfma_f32_16x16x32_bf16 v[32:35], v[184:187], v[216:219], v[32:35]
	v_mfma_f32_16x16x32_bf16 v[28:31], v[138:141], v[188:191], v[28:31]
	v_mfma_f32_16x16x32_bf16 v[24:27], v[224:227], v[188:191], v[24:27]
	v_mfma_f32_16x16x32_bf16 v[20:23], v[138:141], v[196:199], v[20:23]
	v_mfma_f32_16x16x32_bf16 v[16:19], v[224:227], v[196:199], v[16:19]
	v_mfma_f32_16x16x32_bf16 v[12:15], v[138:141], v[204:207], v[12:15]
	v_mfma_f32_16x16x32_bf16 v[8:11], v[224:227], v[204:207], v[8:11]
	v_mfma_f32_16x16x32_bf16 v[4:7], v[138:141], v[212:215], v[4:7]
	v_mfma_f32_16x16x32_bf16 v[0:3], v[224:227], v[212:215], v[0:3]
	v_mfma_f32_16x16x32_bf16 v[28:31], v[220:223], v[192:195], v[28:31]
	v_mfma_f32_16x16x32_bf16 v[24:27], v[168:171], v[192:195], v[24:27]
	v_mfma_f32_16x16x32_bf16 v[20:23], v[220:223], v[200:203], v[20:23]
	v_mfma_f32_16x16x32_bf16 v[16:19], v[168:171], v[200:203], v[16:19]
	v_mfma_f32_16x16x32_bf16 v[12:15], v[220:223], v[208:211], v[12:15]
	v_mfma_f32_16x16x32_bf16 v[8:11], v[168:171], v[208:211], v[8:11]
	v_mfma_f32_16x16x32_bf16 v[4:7], v[220:223], v[216:219], v[4:7]
	v_mfma_f32_16x16x32_bf16 v[0:3], v[168:171], v[216:219], v[0:3]
	s_barrier
	ds_read_b128 v[138:141], v163
	ds_read_b128 v[142:145], v163 offset:1024
	ds_read_b128 v[146:149], v163 offset:2048
	ds_read_b128 v[168:171], v163 offset:3072
	ds_read_b128 v[178:181], v161 offset:32768
	ds_read_b128 v[182:185], v161 offset:33792
	ds_read_b128 v[186:189], v160 offset:32768
	ds_read_b128 v[190:193], v160 offset:33792
	ds_read_b128 v[194:197], v159 offset:32768
	ds_read_b128 v[198:201], v159 offset:33792
	ds_read_b128 v[202:205], v158 offset:32768
	ds_read_b128 v[206:209], v158 offset:33792
	s_waitcnt vmcnt(2)
	s_barrier
	s_waitcnt lgkmcnt(0)
	s_waitcnt lgkmcnt(0)
	v_mfma_f32_16x16x32_bf16 v[124:127], v[138:141], v[178:181], v[124:127]
	v_mfma_f32_16x16x32_bf16 v[120:123], v[146:149], v[178:181], v[120:123]
	v_mfma_f32_16x16x32_bf16 v[116:119], v[138:141], v[186:189], v[116:119]
	v_mfma_f32_16x16x32_bf16 v[112:115], v[146:149], v[186:189], v[112:115]
	v_mfma_f32_16x16x32_bf16 v[108:111], v[138:141], v[194:197], v[108:111]
	v_mfma_f32_16x16x32_bf16 v[104:107], v[146:149], v[194:197], v[104:107]
	v_mfma_f32_16x16x32_bf16 v[100:103], v[138:141], v[202:205], v[100:103]
	v_mfma_f32_16x16x32_bf16 v[96:99], v[146:149], v[202:205], v[96:99]
	v_mfma_f32_16x16x32_bf16 v[124:127], v[142:145], v[182:185], v[124:127]
	v_mfma_f32_16x16x32_bf16 v[120:123], v[168:171], v[182:185], v[120:123]
	v_mfma_f32_16x16x32_bf16 v[116:119], v[142:145], v[190:193], v[116:119]
	v_mfma_f32_16x16x32_bf16 v[112:115], v[168:171], v[190:193], v[112:115]
	v_mfma_f32_16x16x32_bf16 v[108:111], v[142:145], v[198:201], v[108:111]
	v_mfma_f32_16x16x32_bf16 v[104:107], v[168:171], v[198:201], v[104:107]
	v_mfma_f32_16x16x32_bf16 v[100:103], v[142:145], v[206:209], v[100:103]
	v_mfma_f32_16x16x32_bf16 v[96:99], v[168:171], v[206:209], v[96:99]
	s_barrier
	ds_read_b128 v[210:213], v162
	ds_read_b128 v[214:217], v162 offset:1024
	ds_read_b128 v[218:221], v162 offset:2048
	ds_read_b128 v[222:225], v162 offset:3072
	s_waitcnt vmcnt(0)
	s_barrier
	s_waitcnt lgkmcnt(0)
	s_waitcnt lgkmcnt(0)
	v_mfma_f32_16x16x32_bf16 v[92:95], v[210:213], v[178:181], v[92:95]
	v_mfma_f32_16x16x32_bf16 v[88:91], v[218:221], v[178:181], v[88:91]
	v_mfma_f32_16x16x32_bf16 v[84:87], v[210:213], v[186:189], v[84:87]
	v_mfma_f32_16x16x32_bf16 v[80:83], v[218:221], v[186:189], v[80:83]
	v_mfma_f32_16x16x32_bf16 v[76:79], v[210:213], v[194:197], v[76:79]
	v_mfma_f32_16x16x32_bf16 v[72:75], v[218:221], v[194:197], v[72:75]
	v_mfma_f32_16x16x32_bf16 v[68:71], v[210:213], v[202:205], v[68:71]
	v_mfma_f32_16x16x32_bf16 v[64:67], v[218:221], v[202:205], v[64:67]
	v_mfma_f32_16x16x32_bf16 v[92:95], v[214:217], v[182:185], v[92:95]
	v_mfma_f32_16x16x32_bf16 v[88:91], v[222:225], v[182:185], v[88:91]
	v_mfma_f32_16x16x32_bf16 v[84:87], v[214:217], v[190:193], v[84:87]
	v_mfma_f32_16x16x32_bf16 v[80:83], v[222:225], v[190:193], v[80:83]
	v_mfma_f32_16x16x32_bf16 v[76:79], v[214:217], v[198:201], v[76:79]
	v_mfma_f32_16x16x32_bf16 v[72:75], v[222:225], v[198:201], v[72:75]
	v_mfma_f32_16x16x32_bf16 v[68:71], v[214:217], v[206:209], v[68:71]
	v_mfma_f32_16x16x32_bf16 v[64:67], v[222:225], v[206:209], v[64:67]
	s_barrier
	ds_read_b128 v[178:181], v161 offset:49152
	ds_read_b128 v[182:185], v161 offset:50176
	ds_read_b128 v[186:189], v160 offset:49152
	ds_read_b128 v[160:163], v160 offset:50176
	ds_read_b128 v[190:193], v159 offset:49152
	ds_read_b128 v[194:197], v159 offset:50176
	ds_read_b128 v[198:201], v158 offset:49152
	ds_read_b128 v[202:205], v158 offset:50176
	s_barrier
	s_waitcnt lgkmcnt(0)
	s_waitcnt lgkmcnt(0)
	v_mfma_f32_16x16x32_bf16 v[60:63], v[138:141], v[178:181], v[60:63]
	v_mfma_f32_16x16x32_bf16 v[56:59], v[146:149], v[178:181], v[56:59]
	v_mfma_f32_16x16x32_bf16 v[52:55], v[138:141], v[186:189], v[52:55]
	v_mfma_f32_16x16x32_bf16 v[48:51], v[146:149], v[186:189], v[48:51]
	v_mfma_f32_16x16x32_bf16 v[44:47], v[138:141], v[190:193], v[44:47]
	v_mfma_f32_16x16x32_bf16 v[40:43], v[146:149], v[190:193], v[40:43]
	v_mfma_f32_16x16x32_bf16 v[36:39], v[138:141], v[198:201], v[36:39]
	v_mfma_f32_16x16x32_bf16 v[32:35], v[146:149], v[198:201], v[32:35]
	v_mfma_f32_16x16x32_bf16 v[60:63], v[142:145], v[182:185], v[60:63]
	v_mfma_f32_16x16x32_bf16 v[56:59], v[168:171], v[182:185], v[56:59]
	v_mfma_f32_16x16x32_bf16 v[52:55], v[142:145], v[160:163], v[52:55]
	v_mfma_f32_16x16x32_bf16 v[48:51], v[168:171], v[160:163], v[48:51]
	v_mfma_f32_16x16x32_bf16 v[44:47], v[142:145], v[194:197], v[44:47]
	v_mfma_f32_16x16x32_bf16 v[40:43], v[168:171], v[194:197], v[40:43]
	v_mfma_f32_16x16x32_bf16 v[36:39], v[142:145], v[202:205], v[36:39]
	v_mfma_f32_16x16x32_bf16 v[32:35], v[168:171], v[202:205], v[32:35]
	v_mfma_f32_16x16x32_bf16 v[28:31], v[210:213], v[178:181], v[28:31]
	v_mfma_f32_16x16x32_bf16 v[24:27], v[218:221], v[178:181], v[24:27]
	v_mfma_f32_16x16x32_bf16 v[20:23], v[210:213], v[186:189], v[20:23]
	v_mfma_f32_16x16x32_bf16 v[16:19], v[218:221], v[186:189], v[16:19]
	v_mfma_f32_16x16x32_bf16 v[12:15], v[210:213], v[190:193], v[12:15]
	v_mfma_f32_16x16x32_bf16 v[8:11], v[218:221], v[190:193], v[8:11]
	v_mfma_f32_16x16x32_bf16 v[4:7], v[210:213], v[198:201], v[4:7]
	v_mfma_f32_16x16x32_bf16 v[0:3], v[218:221], v[198:201], v[0:3]
	v_mfma_f32_16x16x32_bf16 v[28:31], v[214:217], v[182:185], v[28:31]
	v_mfma_f32_16x16x32_bf16 v[24:27], v[222:225], v[182:185], v[24:27]
	v_mfma_f32_16x16x32_bf16 v[20:23], v[214:217], v[160:163], v[20:23]
	v_mfma_f32_16x16x32_bf16 v[16:19], v[222:225], v[160:163], v[16:19]
	v_mfma_f32_16x16x32_bf16 v[12:15], v[214:217], v[194:197], v[12:15]
	v_mfma_f32_16x16x32_bf16 v[8:11], v[222:225], v[194:197], v[8:11]
	v_mfma_f32_16x16x32_bf16 v[4:7], v[214:217], v[202:205], v[4:7]
	v_mfma_f32_16x16x32_bf16 v[0:3], v[222:225], v[202:205], v[0:3]
	s_and_b64 vcc, exec, s[58:59]
	s_barrier
	s_cbranch_vccnz .LBB0_1664
	s_lshr_b32 s0, s70, 2
	s_and_b32 s1, s70, 3
	s_add_i32 s0, s0, s56
	s_or_b32 s1, s1, s53
	s_lshl_b32 s0, s0, 8
	s_lshl_b32 s1, s1, 19
	s_add_u32 s40, s57, s1
	s_addc_u32 s41, s62, 0
	v_lshl_add_u64 v[138:139], s[40:41], 0, v[130:131]
	v_readfirstlane_b32 s1, v153
	v_lshl_add_u64 v[138:139], v[138:139], 0, v[132:133]
	s_mov_b32 m0, s1
	v_readfirstlane_b32 s1, v173
	global_load_lds_dwordx4 v[138:139], off
	s_mov_b32 m0, s1
	s_ashr_i32 s1, s0, 31
	s_lshl_b64 s[42:43], s[0:1], 11
	v_lshl_add_u64 v[138:139], s[40:41], 0, v[134:135]
	s_add_u32 s42, s39, s42
	v_lshl_add_u64 v[138:139], v[138:139], 0, v[136:137]
	s_addc_u32 s43, s46, s43
	global_load_lds_dwordx4 v[138:139], off
	v_lshl_add_u64 v[138:139], s[42:43], 0, v[130:131]
	v_readfirstlane_b32 s1, v152
	v_lshl_add_u64 v[138:139], v[138:139], 0, v[132:133]
	s_mov_b32 m0, s1
	v_readfirstlane_b32 s1, v174
	global_load_lds_dwordx4 v[138:139], off
	v_lshl_add_u64 v[138:139], s[42:43], 0, v[134:135]
	s_add_u32 s40, s40, 0x40000
	v_lshl_add_u64 v[138:139], v[138:139], 0, v[136:137]
	s_mov_b32 m0, s1
	s_addc_u32 s41, s41, 0
	global_load_lds_dwordx4 v[138:139], off
	v_lshl_add_u64 v[138:139], s[40:41], 0, v[130:131]
	v_readfirstlane_b32 s1, v151
	v_lshl_add_u64 v[138:139], v[138:139], 0, v[132:133]
	s_mov_b32 m0, s1
	v_readfirstlane_b32 s1, v175
	s_bitset1_b32 s0, 7
	global_load_lds_dwordx4 v[138:139], off
	s_mov_b32 m0, s1
	s_ashr_i32 s1, s0, 31
	s_lshl_b64 s[0:1], s[0:1], 11
	s_add_u32 s0, s39, s0
	v_lshl_add_u64 v[138:139], s[40:41], 0, v[134:135]
	s_addc_u32 s1, s46, s1
	v_lshl_add_u64 v[138:139], v[138:139], 0, v[136:137]
	v_lshl_add_u64 v[130:131], s[0:1], 0, v[130:131]
	v_readfirstlane_b32 s2, v176
	global_load_lds_dwordx4 v[138:139], off
	v_lshl_add_u64 v[130:131], v[130:131], 0, v[132:133]
	s_mov_b32 m0, s2
	s_nop 0
	global_load_lds_dwordx4 v[130:131], off
	v_lshl_add_u64 v[130:131], s[0:1], 0, v[134:135]
	v_readfirstlane_b32 s0, v177
	v_lshl_add_u64 v[130:131], v[130:131], 0, v[136:137]
	s_mov_b32 m0, s0
	s_nop 0
	global_load_lds_dwordx4 v[130:131], off

.LBB0_1720:
	ds_read_b128 v[176:179], v173
	ds_read_b128 v[180:183], v173 offset:1024
	ds_read_b128 v[184:187], v173 offset:2048
	ds_read_b128 v[188:191], v173 offset:3072
	v_add_u32_e32 v174, 0xc000, v157
	v_lshl_add_u64 v[240:241], s[6:7], 0, v[142:143]
	v_readfirstlane_b32 s2, v174
	v_add_u32_e32 v175, 0xe000, v157
	v_lshl_add_u64 v[224:225], v[240:241], 0, s[14:15]
	s_mov_b32 m0, s2
	v_lshl_add_u64 v[242:243], s[6:7], 0, v[144:145]
	v_readfirstlane_b32 s2, v175
	ds_read_b128 v[192:195], v155
	ds_read_b128 v[196:199], v155 offset:1024
	ds_read_b128 v[200:203], v154
	ds_read_b128 v[204:207], v154 offset:1024
	ds_read_b128 v[208:211], v153
	ds_read_b128 v[212:215], v153 offset:1024
	ds_read_b128 v[216:219], v152
	ds_read_b128 v[220:223], v152 offset:1024
	global_load_lds_dwordx4 v[224:225], off
	v_lshl_add_u64 v[224:225], v[242:243], 0, s[14:15]
	s_mov_b32 m0, s2
	s_nop 0
	global_load_lds_dwordx4 v[224:225], off
	s_waitcnt lgkmcnt(8)
	s_barrier
	s_waitcnt lgkmcnt(0)
	s_waitcnt lgkmcnt(0)
	v_mfma_f32_16x16x32_bf16 v[124:127], v[176:179], v[192:195], v[124:127]
	v_mfma_f32_16x16x32_bf16 v[120:123], v[184:187], v[192:195], v[120:123]
	v_mfma_f32_16x16x32_bf16 v[116:119], v[176:179], v[200:203], v[116:119]
	v_mfma_f32_16x16x32_bf16 v[112:115], v[184:187], v[200:203], v[112:115]
	v_mfma_f32_16x16x32_bf16 v[108:111], v[176:179], v[208:211], v[108:111]
	v_mfma_f32_16x16x32_bf16 v[104:107], v[184:187], v[208:211], v[104:107]
	v_mfma_f32_16x16x32_bf16 v[100:103], v[176:179], v[216:219], v[100:103]
	v_mfma_f32_16x16x32_bf16 v[96:99], v[184:187], v[216:219], v[96:99]
	v_mfma_f32_16x16x32_bf16 v[124:127], v[180:183], v[196:199], v[124:127]
	v_mfma_f32_16x16x32_bf16 v[120:123], v[188:191], v[196:199], v[120:123]
	v_mfma_f32_16x16x32_bf16 v[116:119], v[180:183], v[204:207], v[116:119]
	v_mfma_f32_16x16x32_bf16 v[112:115], v[188:191], v[204:207], v[112:115]
	v_mfma_f32_16x16x32_bf16 v[108:111], v[180:183], v[212:215], v[108:111]
	v_mfma_f32_16x16x32_bf16 v[104:107], v[188:191], v[212:215], v[104:107]
	v_mfma_f32_16x16x32_bf16 v[100:103], v[180:183], v[220:223], v[100:103]
	v_mfma_f32_16x16x32_bf16 v[96:99], v[188:191], v[220:223], v[96:99]
	s_barrier
	v_lshl_add_u64 v[244:245], s[6:7], 0, v[138:139]
	v_readfirstlane_b32 s2, v151
	v_lshl_add_u64 v[246:247], v[244:245], 0, s[16:17]
	s_mov_b32 m0, s2
	v_add_u32_e32 v250, 0x2000, v151
	ds_read_b128 v[224:227], v170
	ds_read_b128 v[228:231], v170 offset:1024
	ds_read_b128 v[232:235], v170 offset:2048
	ds_read_b128 v[236:239], v170 offset:3072
	global_load_lds_dwordx4 v[246:247], off
	v_lshl_add_u64 v[246:247], s[6:7], 0, v[140:141]
	v_readfirstlane_b32 s2, v250
	v_lshl_add_u64 v[248:249], v[246:247], 0, s[16:17]
	s_mov_b32 m0, s2
	s_nop 0
	global_load_lds_dwordx4 v[248:249], off
	s_barrier
	s_waitcnt lgkmcnt(0)
	s_waitcnt lgkmcnt(0)
	v_mfma_f32_16x16x32_bf16 v[92:95], v[224:227], v[192:195], v[92:95]
	v_mfma_f32_16x16x32_bf16 v[88:91], v[232:235], v[192:195], v[88:91]
	v_mfma_f32_16x16x32_bf16 v[84:87], v[224:227], v[200:203], v[84:87]
	v_mfma_f32_16x16x32_bf16 v[80:83], v[232:235], v[200:203], v[80:83]
	v_mfma_f32_16x16x32_bf16 v[76:79], v[224:227], v[208:211], v[76:79]
	v_mfma_f32_16x16x32_bf16 v[72:75], v[232:235], v[208:211], v[72:75]
	v_mfma_f32_16x16x32_bf16 v[68:71], v[224:227], v[216:219], v[68:71]
	v_mfma_f32_16x16x32_bf16 v[64:67], v[232:235], v[216:219], v[64:67]
	v_mfma_f32_16x16x32_bf16 v[92:95], v[228:231], v[196:199], v[92:95]
	v_mfma_f32_16x16x32_bf16 v[88:91], v[236:239], v[196:199], v[88:91]
	v_mfma_f32_16x16x32_bf16 v[84:87], v[228:231], v[204:207], v[84:87]
	v_mfma_f32_16x16x32_bf16 v[80:83], v[236:239], v[204:207], v[80:83]
	v_mfma_f32_16x16x32_bf16 v[76:79], v[228:231], v[212:215], v[76:79]
	v_mfma_f32_16x16x32_bf16 v[72:75], v[236:239], v[212:215], v[72:75]
	v_mfma_f32_16x16x32_bf16 v[68:71], v[228:231], v[220:223], v[68:71]
	v_mfma_f32_16x16x32_bf16 v[64:67], v[236:239], v[220:223], v[64:67]
	v_readfirstlane_b32 s2, v157
	v_lshl_add_u64 v[248:249], v[240:241], 0, s[18:19]
	s_mov_b32 m0, s2
	v_readfirstlane_b32 s2, v158
	s_barrier
	ds_read_b128 v[192:195], v155 offset:16384
	ds_read_b128 v[196:199], v155 offset:17408
	ds_read_b128 v[200:203], v154 offset:16384
	ds_read_b128 v[204:207], v154 offset:17408
	ds_read_b128 v[208:211], v153 offset:16384
	ds_read_b128 v[212:215], v153 offset:17408
	ds_read_b128 v[216:219], v152 offset:16384
	ds_read_b128 v[220:223], v152 offset:17408
	global_load_lds_dwordx4 v[248:249], off
	v_lshl_add_u64 v[248:249], v[242:243], 0, s[18:19]
	s_mov_b32 m0, s2
	s_nop 0
	global_load_lds_dwordx4 v[248:249], off
	s_barrier
	s_waitcnt lgkmcnt(0)
	s_waitcnt lgkmcnt(0)
	v_mfma_f32_16x16x32_bf16 v[60:63], v[176:179], v[192:195], v[60:63]
	v_mfma_f32_16x16x32_bf16 v[56:59], v[184:187], v[192:195], v[56:59]
	v_mfma_f32_16x16x32_bf16 v[52:55], v[176:179], v[200:203], v[52:55]
	v_mfma_f32_16x16x32_bf16 v[48:51], v[184:187], v[200:203], v[48:51]
	v_mfma_f32_16x16x32_bf16 v[44:47], v[176:179], v[208:211], v[44:47]
	v_mfma_f32_16x16x32_bf16 v[40:43], v[184:187], v[208:211], v[40:43]
	v_mfma_f32_16x16x32_bf16 v[36:39], v[176:179], v[216:219], v[36:39]
	v_mfma_f32_16x16x32_bf16 v[32:35], v[184:187], v[216:219], v[32:35]
	v_mfma_f32_16x16x32_bf16 v[60:63], v[180:183], v[196:199], v[60:63]
	v_mfma_f32_16x16x32_bf16 v[56:59], v[188:191], v[196:199], v[56:59]
	v_mfma_f32_16x16x32_bf16 v[52:55], v[180:183], v[204:207], v[52:55]
	v_mfma_f32_16x16x32_bf16 v[48:51], v[188:191], v[204:207], v[48:51]
	v_mfma_f32_16x16x32_bf16 v[44:47], v[180:183], v[212:215], v[44:47]
	v_mfma_f32_16x16x32_bf16 v[40:43], v[188:191], v[212:215], v[40:43]
	v_mfma_f32_16x16x32_bf16 v[36:39], v[180:183], v[220:223], v[36:39]
	v_mfma_f32_16x16x32_bf16 v[32:35], v[188:191], v[220:223], v[32:35]
	s_barrier
	v_readfirstlane_b32 s2, v159
	v_add_u32_e32 v178, 0x2000, v159
	v_lshl_add_u64 v[176:177], v[244:245], 0, s[20:21]
	s_mov_b32 m0, s2
	v_readfirstlane_b32 s2, v178
	global_load_lds_dwordx4 v[176:177], off
	v_lshl_add_u64 v[176:177], v[246:247], 0, s[20:21]
	s_mov_b32 m0, s2
	s_nop 0
	global_load_lds_dwordx4 v[176:177], off
	s_waitcnt vmcnt(6)
	s_barrier
	v_mfma_f32_16x16x32_bf16 v[28:31], v[224:227], v[192:195], v[28:31]
	v_mfma_f32_16x16x32_bf16 v[24:27], v[232:235], v[192:195], v[24:27]
	v_mfma_f32_16x16x32_bf16 v[20:23], v[224:227], v[200:203], v[20:23]
	v_mfma_f32_16x16x32_bf16 v[16:19], v[232:235], v[200:203], v[16:19]
	v_mfma_f32_16x16x32_bf16 v[12:15], v[224:227], v[208:211], v[12:15]
	v_mfma_f32_16x16x32_bf16 v[8:11], v[232:235], v[208:211], v[8:11]
	v_mfma_f32_16x16x32_bf16 v[4:7], v[224:227], v[216:219], v[4:7]
	v_mfma_f32_16x16x32_bf16 v[0:3], v[232:235], v[216:219], v[0:3]
	v_mfma_f32_16x16x32_bf16 v[28:31], v[228:231], v[196:199], v[28:31]
	v_mfma_f32_16x16x32_bf16 v[24:27], v[236:239], v[196:199], v[24:27]
	v_mfma_f32_16x16x32_bf16 v[20:23], v[228:231], v[204:207], v[20:23]
	v_mfma_f32_16x16x32_bf16 v[16:19], v[236:239], v[204:207], v[16:19]
	v_mfma_f32_16x16x32_bf16 v[12:15], v[228:231], v[212:215], v[12:15]
	v_mfma_f32_16x16x32_bf16 v[8:11], v[236:239], v[212:215], v[8:11]
	v_mfma_f32_16x16x32_bf16 v[4:7], v[228:231], v[220:223], v[4:7]
	v_mfma_f32_16x16x32_bf16 v[0:3], v[236:239], v[220:223], v[0:3]
	s_barrier
	ds_read_b128 v[176:179], v160
	ds_read_b128 v[180:183], v160 offset:1024
	ds_read_b128 v[184:187], v160 offset:2048
	ds_read_b128 v[188:191], v160 offset:3072
	v_readfirstlane_b32 s2, v161
	v_lshl_add_u64 v[224:225], v[240:241], 0, s[24:25]
	s_mov_b32 m0, s2
	v_readfirstlane_b32 s2, v162
	ds_read_b128 v[192:195], v155 offset:32768
	ds_read_b128 v[196:199], v155 offset:33792
	ds_read_b128 v[200:203], v154 offset:32768
	ds_read_b128 v[204:207], v154 offset:33792
	ds_read_b128 v[208:211], v153 offset:32768
	ds_read_b128 v[212:215], v153 offset:33792
	ds_read_b128 v[216:219], v152 offset:32768
	ds_read_b128 v[220:223], v152 offset:33792
	global_load_lds_dwordx4 v[224:225], off
	v_lshl_add_u64 v[224:225], v[242:243], 0, s[24:25]
	s_mov_b32 m0, s2
	s_nop 0
	global_load_lds_dwordx4 v[224:225], off
	s_waitcnt lgkmcnt(8)
	s_barrier
	s_waitcnt lgkmcnt(0)
	s_waitcnt lgkmcnt(0)
	v_mfma_f32_16x16x32_bf16 v[124:127], v[176:179], v[192:195], v[124:127]
	v_mfma_f32_16x16x32_bf16 v[120:123], v[184:187], v[192:195], v[120:123]
	v_mfma_f32_16x16x32_bf16 v[116:119], v[176:179], v[200:203], v[116:119]
	v_mfma_f32_16x16x32_bf16 v[112:115], v[184:187], v[200:203], v[112:115]
	v_mfma_f32_16x16x32_bf16 v[108:111], v[176:179], v[208:211], v[108:111]
	v_mfma_f32_16x16x32_bf16 v[104:107], v[184:187], v[208:211], v[104:107]
	v_mfma_f32_16x16x32_bf16 v[100:103], v[176:179], v[216:219], v[100:103]
	v_mfma_f32_16x16x32_bf16 v[96:99], v[184:187], v[216:219], v[96:99]
	v_mfma_f32_16x16x32_bf16 v[124:127], v[180:183], v[196:199], v[124:127]
	v_mfma_f32_16x16x32_bf16 v[120:123], v[188:191], v[196:199], v[120:123]
	v_mfma_f32_16x16x32_bf16 v[116:119], v[180:183], v[204:207], v[116:119]
	v_mfma_f32_16x16x32_bf16 v[112:115], v[188:191], v[204:207], v[112:115]
	v_mfma_f32_16x16x32_bf16 v[108:111], v[180:183], v[212:215], v[108:111]
	v_mfma_f32_16x16x32_bf16 v[104:107], v[188:191], v[212:215], v[104:107]
	v_mfma_f32_16x16x32_bf16 v[100:103], v[180:183], v[220:223], v[100:103]
	v_mfma_f32_16x16x32_bf16 v[96:99], v[188:191], v[220:223], v[96:99]
	s_barrier
	v_readfirstlane_b32 s2, v163
	v_lshl_add_u64 v[248:249], v[244:245], 0, s[26:27]
	s_mov_b32 m0, s2
	v_readfirstlane_b32 s2, v167
	ds_read_b128 v[224:227], v156
	ds_read_b128 v[228:231], v156 offset:1024
	ds_read_b128 v[232:235], v156 offset:2048
	ds_read_b128 v[236:239], v156 offset:3072
	global_load_lds_dwordx4 v[248:249], off
	v_lshl_add_u64 v[248:249], v[246:247], 0, s[26:27]
	s_mov_b32 m0, s2
	s_nop 0
	global_load_lds_dwordx4 v[248:249], off
	s_barrier
	s_waitcnt lgkmcnt(0)
	s_waitcnt lgkmcnt(0)
	v_mfma_f32_16x16x32_bf16 v[92:95], v[224:227], v[192:195], v[92:95]
	v_mfma_f32_16x16x32_bf16 v[88:91], v[232:235], v[192:195], v[88:91]
	v_mfma_f32_16x16x32_bf16 v[84:87], v[224:227], v[200:203], v[84:87]
	v_mfma_f32_16x16x32_bf16 v[80:83], v[232:235], v[200:203], v[80:83]
	v_mfma_f32_16x16x32_bf16 v[76:79], v[224:227], v[208:211], v[76:79]
	v_mfma_f32_16x16x32_bf16 v[72:75], v[232:235], v[208:211], v[72:75]
	v_mfma_f32_16x16x32_bf16 v[68:71], v[224:227], v[216:219], v[68:71]
	v_mfma_f32_16x16x32_bf16 v[64:67], v[232:235], v[216:219], v[64:67]
	v_mfma_f32_16x16x32_bf16 v[92:95], v[228:231], v[196:199], v[92:95]
	v_mfma_f32_16x16x32_bf16 v[88:91], v[236:239], v[196:199], v[88:91]
	v_mfma_f32_16x16x32_bf16 v[84:87], v[228:231], v[204:207], v[84:87]
	v_mfma_f32_16x16x32_bf16 v[80:83], v[236:239], v[204:207], v[80:83]
	v_mfma_f32_16x16x32_bf16 v[76:79], v[228:231], v[212:215], v[76:79]
	v_mfma_f32_16x16x32_bf16 v[72:75], v[236:239], v[212:215], v[72:75]
	v_mfma_f32_16x16x32_bf16 v[68:71], v[228:231], v[220:223], v[68:71]
	v_mfma_f32_16x16x32_bf16 v[64:67], v[236:239], v[220:223], v[64:67]
	v_readfirstlane_b32 s2, v168
	v_lshl_add_u64 v[240:241], v[240:241], 0, s[28:29]
	s_mov_b32 m0, s2
	v_readfirstlane_b32 s2, v169
	s_barrier
	ds_read_b128 v[192:195], v155 offset:49152
	ds_read_b128 v[196:199], v155 offset:50176
	ds_read_b128 v[200:203], v154 offset:49152
	ds_read_b128 v[204:207], v154 offset:50176
	ds_read_b128 v[208:211], v153 offset:49152
	ds_read_b128 v[212:215], v153 offset:50176
	ds_read_b128 v[216:219], v152 offset:49152
	ds_read_b128 v[220:223], v152 offset:50176
	global_load_lds_dwordx4 v[240:241], off
	v_lshl_add_u64 v[240:241], v[242:243], 0, s[28:29]
	s_mov_b32 m0, s2
	s_nop 0
	global_load_lds_dwordx4 v[240:241], off
	s_barrier
	s_waitcnt lgkmcnt(0)
	s_waitcnt lgkmcnt(0)
	v_mfma_f32_16x16x32_bf16 v[60:63], v[176:179], v[192:195], v[60:63]
	v_mfma_f32_16x16x32_bf16 v[56:59], v[184:187], v[192:195], v[56:59]
	v_mfma_f32_16x16x32_bf16 v[52:55], v[176:179], v[200:203], v[52:55]
	v_mfma_f32_16x16x32_bf16 v[48:51], v[184:187], v[200:203], v[48:51]
	v_mfma_f32_16x16x32_bf16 v[44:47], v[176:179], v[208:211], v[44:47]
	v_mfma_f32_16x16x32_bf16 v[40:43], v[184:187], v[208:211], v[40:43]
	v_mfma_f32_16x16x32_bf16 v[36:39], v[176:179], v[216:219], v[36:39]
	v_mfma_f32_16x16x32_bf16 v[32:35], v[184:187], v[216:219], v[32:35]
	v_mfma_f32_16x16x32_bf16 v[60:63], v[180:183], v[196:199], v[60:63]
	v_mfma_f32_16x16x32_bf16 v[56:59], v[188:191], v[196:199], v[56:59]
	v_mfma_f32_16x16x32_bf16 v[52:55], v[180:183], v[204:207], v[52:55]
	v_mfma_f32_16x16x32_bf16 v[48:51], v[188:191], v[204:207], v[48:51]
	v_mfma_f32_16x16x32_bf16 v[44:47], v[180:183], v[212:215], v[44:47]
	v_mfma_f32_16x16x32_bf16 v[40:43], v[188:191], v[212:215], v[40:43]
	v_mfma_f32_16x16x32_bf16 v[36:39], v[180:183], v[220:223], v[36:39]
	v_mfma_f32_16x16x32_bf16 v[32:35], v[188:191], v[220:223], v[32:35]
	s_barrier
	v_readfirstlane_b32 s2, v171
	v_lshl_add_u64 v[176:177], v[244:245], 0, s[30:31]
	s_mov_b32 m0, s2
	v_readfirstlane_b32 s2, v172
	global_load_lds_dwordx4 v[176:177], off
	v_lshl_add_u64 v[176:177], v[246:247], 0, s[30:31]
	s_mov_b32 m0, s2
	s_nop 0
	global_load_lds_dwordx4 v[176:177], off
	s_waitcnt vmcnt(6)
	s_barrier
	v_mfma_f32_16x16x32_bf16 v[28:31], v[224:227], v[192:195], v[28:31]
	v_mfma_f32_16x16x32_bf16 v[24:27], v[232:235], v[192:195], v[24:27]
	v_mfma_f32_16x16x32_bf16 v[20:23], v[224:227], v[200:203], v[20:23]
	v_mfma_f32_16x16x32_bf16 v[16:19], v[232:235], v[200:203], v[16:19]
	v_mfma_f32_16x16x32_bf16 v[12:15], v[224:227], v[208:211], v[12:15]
	v_mfma_f32_16x16x32_bf16 v[8:11], v[232:235], v[208:211], v[8:11]
	v_mfma_f32_16x16x32_bf16 v[4:7], v[224:227], v[216:219], v[4:7]
	v_mfma_f32_16x16x32_bf16 v[0:3], v[232:235], v[216:219], v[0:3]
	v_mfma_f32_16x16x32_bf16 v[28:31], v[228:231], v[196:199], v[28:31]
	v_mfma_f32_16x16x32_bf16 v[24:27], v[236:239], v[196:199], v[24:27]
	v_mfma_f32_16x16x32_bf16 v[20:23], v[228:231], v[204:207], v[20:23]
	v_mfma_f32_16x16x32_bf16 v[16:19], v[236:239], v[204:207], v[16:19]
	v_mfma_f32_16x16x32_bf16 v[12:15], v[228:231], v[212:215], v[12:15]
	v_mfma_f32_16x16x32_bf16 v[8:11], v[236:239], v[212:215], v[8:11]
	v_mfma_f32_16x16x32_bf16 v[4:7], v[228:231], v[220:223], v[4:7]
	v_mfma_f32_16x16x32_bf16 v[0:3], v[236:239], v[220:223], v[0:3]
	s_add_i32 s1, s1, 2
	v_lshl_add_u64 v[138:139], v[138:139], 0, s[34:35]
	v_lshl_add_u64 v[140:141], v[140:141], 0, s[34:35]
	v_lshl_add_u64 v[142:143], v[142:143], 0, s[34:35]
	s_cmp_lt_u32 s1, 60
	v_lshl_add_u64 v[144:145], v[144:145], 0, s[34:35]
	s_barrier
	s_cbranch_scc1 .LBB0_1720
	s_add_u32 s4, s38, 0x1f80
	s_addc_u32 s5, s39, 0
	v_lshl_add_u64 v[132:133], s[4:5], 0, v[132:133]
	v_readfirstlane_b32 s1, v174
	v_lshl_add_u64 v[130:131], v[130:131], 1, v[132:133]
	s_mov_b32 m0, s1
	ds_read_b128 v[138:141], v173
	ds_read_b128 v[142:145], v173 offset:1024
	ds_read_b128 v[176:179], v173 offset:2048
	ds_read_b128 v[180:183], v173 offset:3072
	ds_read_b128 v[184:187], v155
	ds_read_b128 v[188:191], v155 offset:1024
	ds_read_b128 v[192:195], v154
	ds_read_b128 v[196:199], v154 offset:1024
	ds_read_b128 v[200:203], v153
	ds_read_b128 v[204:207], v153 offset:1024
	ds_read_b128 v[208:211], v152
	ds_read_b128 v[212:215], v152 offset:1024
	global_load_lds_dwordx4 v[130:131], off
	v_lshl_add_u64 v[130:131], s[4:5], 0, v[136:137]
	v_readfirstlane_b32 s1, v175
	v_lshl_add_u64 v[130:131], v[134:135], 1, v[130:131]
	s_mov_b32 m0, s1
	s_nop 0
	global_load_lds_dwordx4 v[130:131], off
	s_barrier
	s_waitcnt lgkmcnt(0)
	s_waitcnt lgkmcnt(0)
	v_mfma_f32_16x16x32_bf16 v[124:127], v[138:141], v[184:187], v[124:127]
	v_mfma_f32_16x16x32_bf16 v[116:119], v[138:141], v[192:195], v[116:119]
	v_mfma_f32_16x16x32_bf16 v[108:111], v[138:141], v[200:203], v[108:111]
	v_mfma_f32_16x16x32_bf16 v[100:103], v[138:141], v[208:211], v[100:103]
	v_mfma_f32_16x16x32_bf16 v[124:127], v[142:145], v[188:191], v[124:127]
	v_mfma_f32_16x16x32_bf16 v[120:123], v[176:179], v[184:187], v[120:123]
	v_mfma_f32_16x16x32_bf16 v[116:119], v[142:145], v[196:199], v[116:119]
	v_mfma_f32_16x16x32_bf16 v[112:115], v[176:179], v[192:195], v[112:115]
	v_mfma_f32_16x16x32_bf16 v[108:111], v[142:145], v[204:207], v[108:111]
	v_mfma_f32_16x16x32_bf16 v[104:107], v[176:179], v[200:203], v[104:107]
	v_mfma_f32_16x16x32_bf16 v[100:103], v[142:145], v[212:215], v[100:103]
	v_mfma_f32_16x16x32_bf16 v[96:99], v[176:179], v[208:211], v[96:99]
	v_mfma_f32_16x16x32_bf16 v[130:133], v[180:183], v[188:191], v[120:123]
	v_mfma_f32_16x16x32_bf16 v[134:137], v[180:183], v[196:199], v[112:115]
	v_mfma_f32_16x16x32_bf16 v[172:175], v[180:183], v[204:207], v[104:107]
	v_mfma_f32_16x16x32_bf16 v[216:219], v[180:183], v[212:215], v[96:99]
	s_barrier
	s_nop 1
	ds_read_b128 v[96:99], v170
	ds_read_b128 v[104:107], v170 offset:1024
	ds_read_b128 v[112:115], v170 offset:2048
	ds_read_b128 v[120:123], v170 offset:3072
	s_barrier
	s_waitcnt lgkmcnt(0)
	s_waitcnt lgkmcnt(0)
	v_mfma_f32_16x16x32_bf16 v[92:95], v[96:99], v[184:187], v[92:95]
	v_mfma_f32_16x16x32_bf16 v[84:87], v[96:99], v[192:195], v[84:87]
	v_mfma_f32_16x16x32_bf16 v[76:79], v[96:99], v[200:203], v[76:79]
	v_mfma_f32_16x16x32_bf16 v[68:71], v[96:99], v[208:211], v[68:71]
	v_mfma_f32_16x16x32_bf16 v[92:95], v[104:107], v[188:191], v[92:95]
	v_mfma_f32_16x16x32_bf16 v[88:91], v[112:115], v[184:187], v[88:91]
	v_mfma_f32_16x16x32_bf16 v[84:87], v[104:107], v[196:199], v[84:87]
	v_mfma_f32_16x16x32_bf16 v[80:83], v[112:115], v[192:195], v[80:83]
	v_mfma_f32_16x16x32_bf16 v[76:79], v[104:107], v[204:207], v[76:79]
	v_mfma_f32_16x16x32_bf16 v[72:75], v[112:115], v[200:203], v[72:75]
	v_mfma_f32_16x16x32_bf16 v[68:71], v[104:107], v[212:215], v[68:71]
	v_mfma_f32_16x16x32_bf16 v[64:67], v[112:115], v[208:211], v[64:67]
	v_mfma_f32_16x16x32_bf16 v[168:171], v[120:123], v[188:191], v[88:91]
	v_mfma_f32_16x16x32_bf16 v[184:187], v[120:123], v[196:199], v[80:83]
	v_mfma_f32_16x16x32_bf16 v[188:191], v[120:123], v[204:207], v[72:75]
	v_mfma_f32_16x16x32_bf16 v[192:195], v[120:123], v[212:215], v[64:67]
	s_barrier
	s_nop 1
	ds_read_b128 v[64:67], v155 offset:16384
	ds_read_b128 v[72:75], v155 offset:17408
	ds_read_b128 v[80:83], v154 offset:16384
	ds_read_b128 v[88:91], v154 offset:17408
	ds_read_b128 v[196:199], v153 offset:16384
	ds_read_b128 v[200:203], v153 offset:17408
	ds_read_b128 v[204:207], v152 offset:16384
	ds_read_b128 v[208:211], v152 offset:17408
	s_waitcnt vmcnt(4)
	s_barrier
	s_waitcnt lgkmcnt(0)
	s_waitcnt lgkmcnt(0)
	v_mfma_f32_16x16x32_bf16 v[60:63], v[138:141], v[64:67], v[60:63]
	v_mfma_f32_16x16x32_bf16 v[52:55], v[138:141], v[80:83], v[52:55]
	v_mfma_f32_16x16x32_bf16 v[44:47], v[138:141], v[196:199], v[44:47]
	v_mfma_f32_16x16x32_bf16 v[36:39], v[138:141], v[204:207], v[36:39]
	v_mfma_f32_16x16x32_bf16 v[60:63], v[142:145], v[72:75], v[60:63]
	v_mfma_f32_16x16x32_bf16 v[56:59], v[176:179], v[64:67], v[56:59]
	v_mfma_f32_16x16x32_bf16 v[52:55], v[142:145], v[88:91], v[52:55]
	v_mfma_f32_16x16x32_bf16 v[48:51], v[176:179], v[80:83], v[48:51]
	v_mfma_f32_16x16x32_bf16 v[44:47], v[142:145], v[200:203], v[44:47]
	v_mfma_f32_16x16x32_bf16 v[40:43], v[176:179], v[196:199], v[40:43]
	v_mfma_f32_16x16x32_bf16 v[36:39], v[142:145], v[208:211], v[36:39]
	v_mfma_f32_16x16x32_bf16 v[32:35], v[176:179], v[204:207], v[32:35]
	v_mfma_f32_16x16x32_bf16 v[212:215], v[180:183], v[72:75], v[56:59]
	v_mfma_f32_16x16x32_bf16 v[220:223], v[180:183], v[88:91], v[48:51]
	v_mfma_f32_16x16x32_bf16 v[224:227], v[180:183], v[200:203], v[40:43]
	v_mfma_f32_16x16x32_bf16 v[138:141], v[180:183], v[208:211], v[32:35]
	v_mfma_f32_16x16x32_bf16 v[28:31], v[96:99], v[64:67], v[28:31]
	v_mfma_f32_16x16x32_bf16 v[20:23], v[96:99], v[80:83], v[20:23]
	v_mfma_f32_16x16x32_bf16 v[12:15], v[96:99], v[196:199], v[12:15]
	v_mfma_f32_16x16x32_bf16 v[4:7], v[96:99], v[204:207], v[4:7]
	v_mfma_f32_16x16x32_bf16 v[28:31], v[104:107], v[72:75], v[28:31]
	v_mfma_f32_16x16x32_bf16 v[24:27], v[112:115], v[64:67], v[24:27]
	v_mfma_f32_16x16x32_bf16 v[20:23], v[104:107], v[88:91], v[20:23]
	v_mfma_f32_16x16x32_bf16 v[16:19], v[112:115], v[80:83], v[16:19]
	v_mfma_f32_16x16x32_bf16 v[12:15], v[104:107], v[200:203], v[12:15]
	v_mfma_f32_16x16x32_bf16 v[8:11], v[112:115], v[196:199], v[8:11]
	v_mfma_f32_16x16x32_bf16 v[4:7], v[104:107], v[208:211], v[4:7]
	v_mfma_f32_16x16x32_bf16 v[0:3], v[112:115], v[204:207], v[0:3]
	v_mfma_f32_16x16x32_bf16 v[142:145], v[120:123], v[72:75], v[24:27]
	v_mfma_f32_16x16x32_bf16 v[176:179], v[120:123], v[88:91], v[16:19]
	v_mfma_f32_16x16x32_bf16 v[180:183], v[120:123], v[200:203], v[8:11]
	v_mfma_f32_16x16x32_bf16 v[196:199], v[120:123], v[208:211], v[0:3]
	s_barrier
	s_nop 1
	ds_read_b128 v[0:3], v160
	ds_read_b128 v[8:11], v160 offset:1024
	ds_read_b128 v[16:19], v160 offset:2048
	ds_read_b128 v[24:27], v160 offset:3072
	ds_read_b128 v[32:35], v155 offset:32768
	ds_read_b128 v[40:43], v155 offset:33792
	ds_read_b128 v[48:51], v154 offset:32768
	ds_read_b128 v[56:59], v154 offset:33792
	ds_read_b128 v[64:67], v153 offset:32768
	ds_read_b128 v[158:161], v153 offset:33792
	ds_read_b128 v[200:203], v152 offset:32768
	ds_read_b128 v[204:207], v152 offset:33792
	s_waitcnt vmcnt(2)
	s_barrier
	s_waitcnt lgkmcnt(0)
	s_waitcnt lgkmcnt(0)
	v_mfma_f32_16x16x32_bf16 v[72:75], v[0:3], v[32:35], v[124:127]
	v_mfma_f32_16x16x32_bf16 v[120:123], v[8:11], v[40:43], v[72:75]
	v_mfma_f32_16x16x32_bf16 v[72:75], v[16:19], v[32:35], v[130:133]
	v_mfma_f32_16x16x32_bf16 v[124:127], v[24:27], v[40:43], v[72:75]
	v_mfma_f32_16x16x32_bf16 v[72:75], v[0:3], v[48:51], v[116:119]
	v_mfma_f32_16x16x32_bf16 v[112:115], v[8:11], v[56:59], v[72:75]
	v_mfma_f32_16x16x32_bf16 v[72:75], v[16:19], v[48:51], v[134:137]
	v_mfma_f32_16x16x32_bf16 v[116:119], v[24:27], v[56:59], v[72:75]
	v_mfma_f32_16x16x32_bf16 v[72:75], v[0:3], v[64:67], v[108:111]
	v_mfma_f32_16x16x32_bf16 v[104:107], v[8:11], v[158:161], v[72:75]
	v_mfma_f32_16x16x32_bf16 v[72:75], v[16:19], v[64:67], v[172:175]
	v_mfma_f32_16x16x32_bf16 v[108:111], v[24:27], v[158:161], v[72:75]
	v_mfma_f32_16x16x32_bf16 v[72:75], v[0:3], v[200:203], v[100:103]
	v_mfma_f32_16x16x32_bf16 v[96:99], v[8:11], v[204:207], v[72:75]
	v_mfma_f32_16x16x32_bf16 v[72:75], v[16:19], v[200:203], v[216:219]
	v_mfma_f32_16x16x32_bf16 v[100:103], v[24:27], v[204:207], v[72:75]
	s_barrier
	ds_read_b128 v[130:133], v156
	ds_read_b128 v[134:137], v156 offset:1024
	ds_read_b128 v[172:175], v156 offset:2048
	ds_read_b128 v[208:211], v156 offset:3072
	s_waitcnt vmcnt(0)
	s_barrier
	s_waitcnt lgkmcnt(0)
	s_waitcnt lgkmcnt(0)
	v_mfma_f32_16x16x32_bf16 v[72:75], v[130:133], v[32:35], v[92:95]
	v_mfma_f32_16x16x32_bf16 v[32:35], v[172:175], v[32:35], v[168:171]
	v_mfma_f32_16x16x32_bf16 v[92:95], v[208:211], v[40:43], v[32:35]
	v_mfma_f32_16x16x32_bf16 v[32:35], v[130:133], v[48:51], v[84:87]
	v_mfma_f32_16x16x32_bf16 v[80:83], v[134:137], v[56:59], v[32:35]
	v_mfma_f32_16x16x32_bf16 v[32:35], v[172:175], v[48:51], v[184:187]
	v_mfma_f32_16x16x32_bf16 v[84:87], v[208:211], v[56:59], v[32:35]
	v_mfma_f32_16x16x32_bf16 v[32:35], v[130:133], v[64:67], v[76:79]
	v_mfma_f32_16x16x32_bf16 v[88:91], v[134:137], v[40:43], v[72:75]
	v_mfma_f32_16x16x32_bf16 v[72:75], v[134:137], v[158:161], v[32:35]
	v_mfma_f32_16x16x32_bf16 v[32:35], v[172:175], v[64:67], v[188:191]
	v_mfma_f32_16x16x32_bf16 v[76:79], v[208:211], v[158:161], v[32:35]
	v_mfma_f32_16x16x32_bf16 v[32:35], v[130:133], v[200:203], v[68:71]
	v_mfma_f32_16x16x32_bf16 v[64:67], v[134:137], v[204:207], v[32:35]
	v_mfma_f32_16x16x32_bf16 v[32:35], v[172:175], v[200:203], v[192:195]
	v_mfma_f32_16x16x32_bf16 v[68:71], v[208:211], v[204:207], v[32:35]
	s_barrier
	ds_read_b128 v[156:159], v155 offset:49152
	ds_read_b128 v[160:163], v155 offset:50176
	ds_read_b128 v[168:171], v154 offset:49152
	ds_read_b128 v[184:187], v154 offset:50176
	ds_read_b128 v[188:191], v153 offset:49152
	ds_read_b128 v[192:195], v153 offset:50176
	ds_read_b128 v[200:203], v152 offset:49152
	ds_read_b128 v[152:155], v152 offset:50176
	s_barrier
	s_waitcnt lgkmcnt(0)
	s_waitcnt lgkmcnt(0)
	v_mfma_f32_16x16x32_bf16 v[32:35], v[0:3], v[156:159], v[60:63]
	v_mfma_f32_16x16x32_bf16 v[56:59], v[8:11], v[160:163], v[32:35]
	v_mfma_f32_16x16x32_bf16 v[32:35], v[16:19], v[156:159], v[212:215]
	v_mfma_f32_16x16x32_bf16 v[60:63], v[24:27], v[160:163], v[32:35]
	v_mfma_f32_16x16x32_bf16 v[32:35], v[0:3], v[168:171], v[52:55]
	v_mfma_f32_16x16x32_bf16 v[48:51], v[8:11], v[184:187], v[32:35]
	v_mfma_f32_16x16x32_bf16 v[32:35], v[16:19], v[168:171], v[220:223]
	v_mfma_f32_16x16x32_bf16 v[52:55], v[24:27], v[184:187], v[32:35]
	v_mfma_f32_16x16x32_bf16 v[32:35], v[0:3], v[188:191], v[44:47]
	v_mfma_f32_16x16x32_bf16 v[40:43], v[8:11], v[192:195], v[32:35]
	v_mfma_f32_16x16x32_bf16 v[32:35], v[16:19], v[188:191], v[224:227]
	v_mfma_f32_16x16x32_bf16 v[0:3], v[0:3], v[200:203], v[36:39]
	v_mfma_f32_16x16x32_bf16 v[44:47], v[24:27], v[192:195], v[32:35]
	v_mfma_f32_16x16x32_bf16 v[32:35], v[8:11], v[152:155], v[0:3]
	v_mfma_f32_16x16x32_bf16 v[0:3], v[16:19], v[200:203], v[138:141]
	v_mfma_f32_16x16x32_bf16 v[36:39], v[24:27], v[152:155], v[0:3]
	v_mfma_f32_16x16x32_bf16 v[0:3], v[130:133], v[156:159], v[28:31]
	v_mfma_f32_16x16x32_bf16 v[24:27], v[134:137], v[160:163], v[0:3]
	v_mfma_f32_16x16x32_bf16 v[0:3], v[172:175], v[156:159], v[142:145]
	v_mfma_f32_16x16x32_bf16 v[28:31], v[208:211], v[160:163], v[0:3]
	v_mfma_f32_16x16x32_bf16 v[0:3], v[130:133], v[168:171], v[20:23]
	v_mfma_f32_16x16x32_bf16 v[16:19], v[134:137], v[184:187], v[0:3]
	v_mfma_f32_16x16x32_bf16 v[0:3], v[172:175], v[168:171], v[176:179]
	v_mfma_f32_16x16x32_bf16 v[20:23], v[208:211], v[184:187], v[0:3]
	v_mfma_f32_16x16x32_bf16 v[0:3], v[130:133], v[188:191], v[12:15]
	v_mfma_f32_16x16x32_bf16 v[8:11], v[134:137], v[192:195], v[0:3]
	v_mfma_f32_16x16x32_bf16 v[0:3], v[172:175], v[188:191], v[180:183]
	v_mfma_f32_16x16x32_bf16 v[12:15], v[208:211], v[192:195], v[0:3]
	v_mfma_f32_16x16x32_bf16 v[0:3], v[130:133], v[200:203], v[4:7]
	v_mfma_f32_16x16x32_bf16 v[4:7], v[172:175], v[200:203], v[196:199]
	v_mfma_f32_16x16x32_bf16 v[0:3], v[134:137], v[152:155], v[0:3]
	v_mfma_f32_16x16x32_bf16 v[4:7], v[208:211], v[152:155], v[4:7]
	v_cmp_gt_u32_e32 vcc, s75, v128
	s_barrier
	s_and_saveexec_b64 s[38:39], vcc
	s_cbranch_execz .LBB0_1716
	s_barrier
	s_branch .LBB0_1716

.LBB0_1842:
	ds_read_b128 v[180:183], v172
	ds_read_b128 v[184:187], v172 offset:1024
	ds_read_b128 v[188:191], v172 offset:2048
	ds_read_b128 v[192:195], v172 offset:3072
	v_add_u32_e32 v178, 0xc000, v152
	v_lshl_add_u64 v[244:245], s[12:13], 0, v[146:147]
	v_readfirstlane_b32 s1, v178
	v_add_u32_e32 v179, 0xe000, v152
	v_lshl_add_u64 v[224:225], v[244:245], 0, s[20:21]
	s_mov_b32 m0, s1
	v_lshl_add_u64 v[246:247], s[12:13], 0, v[148:149]
	v_readfirstlane_b32 s1, v179
	ds_read_b128 v[174:177], v161
	ds_read_b128 v[196:199], v161 offset:1024
	ds_read_b128 v[200:203], v160
	ds_read_b128 v[204:207], v160 offset:1024
	ds_read_b128 v[208:211], v159
	ds_read_b128 v[212:215], v159 offset:1024
	ds_read_b128 v[216:219], v158
	ds_read_b128 v[220:223], v158 offset:1024
	global_load_lds_dwordx4 v[224:225], off
	v_lshl_add_u64 v[224:225], v[246:247], 0, s[20:21]
	s_mov_b32 m0, s1
	s_nop 0
	global_load_lds_dwordx4 v[224:225], off
	s_waitcnt lgkmcnt(8)
	s_barrier
	s_waitcnt lgkmcnt(0)
	s_waitcnt lgkmcnt(0)
	v_mfma_f32_16x16x32_bf16 v[124:127], v[180:183], v[174:177], v[124:127]
	v_mfma_f32_16x16x32_bf16 v[120:123], v[188:191], v[174:177], v[120:123]
	v_mfma_f32_16x16x32_bf16 v[116:119], v[180:183], v[200:203], v[116:119]
	v_mfma_f32_16x16x32_bf16 v[112:115], v[188:191], v[200:203], v[112:115]
	v_mfma_f32_16x16x32_bf16 v[108:111], v[180:183], v[208:211], v[108:111]
	v_mfma_f32_16x16x32_bf16 v[104:107], v[188:191], v[208:211], v[104:107]
	v_mfma_f32_16x16x32_bf16 v[100:103], v[180:183], v[216:219], v[100:103]
	v_mfma_f32_16x16x32_bf16 v[96:99], v[188:191], v[216:219], v[96:99]
	v_mfma_f32_16x16x32_bf16 v[124:127], v[184:187], v[196:199], v[124:127]
	v_mfma_f32_16x16x32_bf16 v[120:123], v[192:195], v[196:199], v[120:123]
	v_mfma_f32_16x16x32_bf16 v[116:119], v[184:187], v[204:207], v[116:119]
	v_mfma_f32_16x16x32_bf16 v[112:115], v[192:195], v[204:207], v[112:115]
	v_mfma_f32_16x16x32_bf16 v[108:111], v[184:187], v[212:215], v[108:111]
	v_mfma_f32_16x16x32_bf16 v[104:107], v[192:195], v[212:215], v[104:107]
	v_mfma_f32_16x16x32_bf16 v[100:103], v[184:187], v[220:223], v[100:103]
	v_mfma_f32_16x16x32_bf16 v[96:99], v[192:195], v[220:223], v[96:99]
	s_barrier
	v_lshl_add_u64 v[248:249], s[12:13], 0, v[142:143]
	v_readfirstlane_b32 s1, v153
	v_add_u32_e32 v173, 0x2000, v153
	v_lshl_add_u64 v[240:241], v[248:249], 0, s[24:25]
	s_mov_b32 m0, s1
	v_lshl_add_u64 v[250:251], s[12:13], 0, v[144:145]
	v_readfirstlane_b32 s1, v173
	ds_read_b128 v[224:227], v169
	ds_read_b128 v[228:231], v169 offset:1024
	ds_read_b128 v[232:235], v169 offset:2048
	ds_read_b128 v[236:239], v169 offset:3072
	global_load_lds_dwordx4 v[240:241], off
	v_lshl_add_u64 v[240:241], v[250:251], 0, s[24:25]
	s_mov_b32 m0, s1
	s_nop 0
	global_load_lds_dwordx4 v[240:241], off
	s_barrier
	s_waitcnt lgkmcnt(0)
	s_waitcnt lgkmcnt(0)
	v_mfma_f32_16x16x32_bf16 v[92:95], v[224:227], v[174:177], v[92:95]
	v_mfma_f32_16x16x32_bf16 v[88:91], v[232:235], v[174:177], v[88:91]
	v_mfma_f32_16x16x32_bf16 v[84:87], v[224:227], v[200:203], v[84:87]
	v_mfma_f32_16x16x32_bf16 v[80:83], v[232:235], v[200:203], v[80:83]
	v_mfma_f32_16x16x32_bf16 v[76:79], v[224:227], v[208:211], v[76:79]
	v_mfma_f32_16x16x32_bf16 v[72:75], v[232:235], v[208:211], v[72:75]
	v_mfma_f32_16x16x32_bf16 v[68:71], v[224:227], v[216:219], v[68:71]
	v_mfma_f32_16x16x32_bf16 v[64:67], v[232:235], v[216:219], v[64:67]
	v_mfma_f32_16x16x32_bf16 v[92:95], v[228:231], v[196:199], v[92:95]
	v_mfma_f32_16x16x32_bf16 v[88:91], v[236:239], v[196:199], v[88:91]
	v_mfma_f32_16x16x32_bf16 v[84:87], v[228:231], v[204:207], v[84:87]
	v_mfma_f32_16x16x32_bf16 v[80:83], v[236:239], v[204:207], v[80:83]
	v_mfma_f32_16x16x32_bf16 v[76:79], v[228:231], v[212:215], v[76:79]
	v_mfma_f32_16x16x32_bf16 v[72:75], v[236:239], v[212:215], v[72:75]
	v_mfma_f32_16x16x32_bf16 v[68:71], v[228:231], v[220:223], v[68:71]
	v_mfma_f32_16x16x32_bf16 v[64:67], v[236:239], v[220:223], v[64:67]
	v_readfirstlane_b32 s1, v152
	v_lshl_add_u64 v[174:175], v[244:245], 0, s[26:27]
	s_mov_b32 m0, s1
	s_barrier
	ds_read_b128 v[196:199], v161 offset:16384
	ds_read_b128 v[200:203], v161 offset:17408
	ds_read_b128 v[204:207], v160 offset:16384
	ds_read_b128 v[208:211], v160 offset:17408
	ds_read_b128 v[212:215], v159 offset:16384
	ds_read_b128 v[216:219], v159 offset:17408
	ds_read_b128 v[220:223], v158 offset:16384
	ds_read_b128 v[240:243], v158 offset:17408
	global_load_lds_dwordx4 v[174:175], off
	v_add_u32_e32 v174, 0x2000, v152
	v_lshl_add_u64 v[176:177], v[246:247], 0, s[26:27]
	v_readfirstlane_b32 s1, v174
	s_mov_b32 m0, s1
	s_nop 0
	global_load_lds_dwordx4 v[176:177], off
	s_barrier
	s_waitcnt lgkmcnt(0)
	s_waitcnt lgkmcnt(0)
	v_mfma_f32_16x16x32_bf16 v[60:63], v[180:183], v[196:199], v[60:63]
	v_mfma_f32_16x16x32_bf16 v[56:59], v[188:191], v[196:199], v[56:59]
	v_mfma_f32_16x16x32_bf16 v[52:55], v[180:183], v[204:207], v[52:55]
	v_mfma_f32_16x16x32_bf16 v[48:51], v[188:191], v[204:207], v[48:51]
	v_mfma_f32_16x16x32_bf16 v[44:47], v[180:183], v[212:215], v[44:47]
	v_mfma_f32_16x16x32_bf16 v[40:43], v[188:191], v[212:215], v[40:43]
	v_mfma_f32_16x16x32_bf16 v[36:39], v[180:183], v[220:223], v[36:39]
	v_mfma_f32_16x16x32_bf16 v[32:35], v[188:191], v[220:223], v[32:35]
	v_mfma_f32_16x16x32_bf16 v[60:63], v[184:187], v[200:203], v[60:63]
	v_mfma_f32_16x16x32_bf16 v[56:59], v[192:195], v[200:203], v[56:59]
	v_mfma_f32_16x16x32_bf16 v[52:55], v[184:187], v[208:211], v[52:55]
	v_mfma_f32_16x16x32_bf16 v[48:51], v[192:195], v[208:211], v[48:51]
	v_mfma_f32_16x16x32_bf16 v[44:47], v[184:187], v[216:219], v[44:47]
	v_mfma_f32_16x16x32_bf16 v[40:43], v[192:195], v[216:219], v[40:43]
	v_mfma_f32_16x16x32_bf16 v[36:39], v[184:187], v[240:243], v[36:39]
	v_mfma_f32_16x16x32_bf16 v[32:35], v[192:195], v[240:243], v[32:35]
	s_barrier
	v_readfirstlane_b32 s1, v151
	v_add_u32_e32 v175, 0x2000, v151
	v_lshl_add_u64 v[176:177], v[248:249], 0, s[28:29]
	s_mov_b32 m0, s1
	v_readfirstlane_b32 s1, v175
	global_load_lds_dwordx4 v[176:177], off
	v_lshl_add_u64 v[176:177], v[250:251], 0, s[28:29]
	s_mov_b32 m0, s1
	s_nop 0
	global_load_lds_dwordx4 v[176:177], off
	s_waitcnt vmcnt(6)
	s_barrier
	v_mfma_f32_16x16x32_bf16 v[28:31], v[224:227], v[196:199], v[28:31]
	v_mfma_f32_16x16x32_bf16 v[24:27], v[232:235], v[196:199], v[24:27]
	v_mfma_f32_16x16x32_bf16 v[20:23], v[224:227], v[204:207], v[20:23]
	v_mfma_f32_16x16x32_bf16 v[16:19], v[232:235], v[204:207], v[16:19]
	v_mfma_f32_16x16x32_bf16 v[12:15], v[224:227], v[212:215], v[12:15]
	v_mfma_f32_16x16x32_bf16 v[8:11], v[232:235], v[212:215], v[8:11]
	v_mfma_f32_16x16x32_bf16 v[4:7], v[224:227], v[220:223], v[4:7]
	v_mfma_f32_16x16x32_bf16 v[0:3], v[232:235], v[220:223], v[0:3]
	v_mfma_f32_16x16x32_bf16 v[28:31], v[228:231], v[200:203], v[28:31]
	v_mfma_f32_16x16x32_bf16 v[24:27], v[236:239], v[200:203], v[24:27]
	v_mfma_f32_16x16x32_bf16 v[20:23], v[228:231], v[208:211], v[20:23]
	v_mfma_f32_16x16x32_bf16 v[16:19], v[236:239], v[208:211], v[16:19]
	v_mfma_f32_16x16x32_bf16 v[12:15], v[228:231], v[216:219], v[12:15]
	v_mfma_f32_16x16x32_bf16 v[8:11], v[236:239], v[216:219], v[8:11]
	v_mfma_f32_16x16x32_bf16 v[4:7], v[228:231], v[240:243], v[4:7]
	v_mfma_f32_16x16x32_bf16 v[0:3], v[236:239], v[240:243], v[0:3]
	s_barrier
	ds_read_b128 v[180:183], v163
	ds_read_b128 v[184:187], v163 offset:1024
	ds_read_b128 v[188:191], v163 offset:2048
	ds_read_b128 v[192:195], v163 offset:3072
	v_add_u32_e32 v176, 0x4000, v152
	v_add_u32_e32 v177, 0x6000, v152
	v_readfirstlane_b32 s1, v176
	v_lshl_add_u64 v[228:229], v[244:245], 0, s[30:31]
	s_mov_b32 m0, s1
	v_readfirstlane_b32 s1, v177
	ds_read_b128 v[196:199], v161 offset:32768
	ds_read_b128 v[200:203], v161 offset:33792
	ds_read_b128 v[204:207], v160 offset:32768
	ds_read_b128 v[208:211], v160 offset:33792
	ds_read_b128 v[212:215], v159 offset:32768
	ds_read_b128 v[216:219], v159 offset:33792
	ds_read_b128 v[220:223], v158 offset:32768
	ds_read_b128 v[224:227], v158 offset:33792
	global_load_lds_dwordx4 v[228:229], off
	v_lshl_add_u64 v[228:229], v[246:247], 0, s[30:31]
	s_mov_b32 m0, s1
	s_nop 0
	global_load_lds_dwordx4 v[228:229], off
	s_waitcnt lgkmcnt(8)
	s_barrier
	s_waitcnt lgkmcnt(0)
	s_waitcnt lgkmcnt(0)
	v_mfma_f32_16x16x32_bf16 v[124:127], v[180:183], v[196:199], v[124:127]
	v_mfma_f32_16x16x32_bf16 v[120:123], v[188:191], v[196:199], v[120:123]
	v_mfma_f32_16x16x32_bf16 v[116:119], v[180:183], v[204:207], v[116:119]
	v_mfma_f32_16x16x32_bf16 v[112:115], v[188:191], v[204:207], v[112:115]
	v_mfma_f32_16x16x32_bf16 v[108:111], v[180:183], v[212:215], v[108:111]
	v_mfma_f32_16x16x32_bf16 v[104:107], v[188:191], v[212:215], v[104:107]
	v_mfma_f32_16x16x32_bf16 v[100:103], v[180:183], v[220:223], v[100:103]
	v_mfma_f32_16x16x32_bf16 v[96:99], v[188:191], v[220:223], v[96:99]
	v_mfma_f32_16x16x32_bf16 v[124:127], v[184:187], v[200:203], v[124:127]
	v_mfma_f32_16x16x32_bf16 v[120:123], v[192:195], v[200:203], v[120:123]
	v_mfma_f32_16x16x32_bf16 v[116:119], v[184:187], v[208:211], v[116:119]
	v_mfma_f32_16x16x32_bf16 v[112:115], v[192:195], v[208:211], v[112:115]
	v_mfma_f32_16x16x32_bf16 v[108:111], v[184:187], v[216:219], v[108:111]
	v_mfma_f32_16x16x32_bf16 v[104:107], v[192:195], v[216:219], v[104:107]
	v_mfma_f32_16x16x32_bf16 v[100:103], v[184:187], v[224:227], v[100:103]
	v_mfma_f32_16x16x32_bf16 v[96:99], v[192:195], v[224:227], v[96:99]
	s_barrier
	v_readfirstlane_b32 s1, v167
	v_add_u32_e32 v254, 0x2000, v167
	v_lshl_add_u64 v[252:253], v[248:249], 0, s[34:35]
	s_mov_b32 m0, s1
	v_readfirstlane_b32 s1, v254
	ds_read_b128 v[228:231], v162
	ds_read_b128 v[232:235], v162 offset:1024
	ds_read_b128 v[236:239], v162 offset:2048
	ds_read_b128 v[240:243], v162 offset:3072
	global_load_lds_dwordx4 v[252:253], off
	v_lshl_add_u64 v[252:253], v[250:251], 0, s[34:35]
	s_mov_b32 m0, s1
	s_nop 0
	global_load_lds_dwordx4 v[252:253], off
	s_barrier
	s_waitcnt lgkmcnt(0)
	s_waitcnt lgkmcnt(0)
	v_mfma_f32_16x16x32_bf16 v[92:95], v[228:231], v[196:199], v[92:95]
	v_mfma_f32_16x16x32_bf16 v[88:91], v[236:239], v[196:199], v[88:91]
	v_mfma_f32_16x16x32_bf16 v[84:87], v[228:231], v[204:207], v[84:87]
	v_mfma_f32_16x16x32_bf16 v[80:83], v[236:239], v[204:207], v[80:83]
	v_mfma_f32_16x16x32_bf16 v[76:79], v[228:231], v[212:215], v[76:79]
	v_mfma_f32_16x16x32_bf16 v[72:75], v[236:239], v[212:215], v[72:75]
	v_mfma_f32_16x16x32_bf16 v[68:71], v[228:231], v[220:223], v[68:71]
	v_mfma_f32_16x16x32_bf16 v[64:67], v[236:239], v[220:223], v[64:67]
	v_mfma_f32_16x16x32_bf16 v[92:95], v[232:235], v[200:203], v[92:95]
	v_mfma_f32_16x16x32_bf16 v[88:91], v[240:243], v[200:203], v[88:91]
	v_mfma_f32_16x16x32_bf16 v[84:87], v[232:235], v[208:211], v[84:87]
	v_mfma_f32_16x16x32_bf16 v[80:83], v[240:243], v[208:211], v[80:83]
	v_mfma_f32_16x16x32_bf16 v[76:79], v[232:235], v[216:219], v[76:79]
	v_mfma_f32_16x16x32_bf16 v[72:75], v[240:243], v[216:219], v[72:75]
	v_mfma_f32_16x16x32_bf16 v[68:71], v[232:235], v[224:227], v[68:71]
	v_mfma_f32_16x16x32_bf16 v[64:67], v[240:243], v[224:227], v[64:67]
	v_readfirstlane_b32 s1, v168
	v_lshl_add_u64 v[244:245], v[244:245], 0, s[36:37]
	s_mov_b32 m0, s1
	v_readfirstlane_b32 s1, v170
	s_barrier
	ds_read_b128 v[196:199], v161 offset:49152
	ds_read_b128 v[200:203], v161 offset:50176
	ds_read_b128 v[204:207], v160 offset:49152
	ds_read_b128 v[208:211], v160 offset:50176
	ds_read_b128 v[212:215], v159 offset:49152
	ds_read_b128 v[216:219], v159 offset:50176
	ds_read_b128 v[220:223], v158 offset:49152
	ds_read_b128 v[224:227], v158 offset:50176
	global_load_lds_dwordx4 v[244:245], off
	v_lshl_add_u64 v[244:245], v[246:247], 0, s[36:37]
	s_mov_b32 m0, s1
	s_nop 0
	global_load_lds_dwordx4 v[244:245], off
	s_barrier
	s_waitcnt lgkmcnt(0)
	s_waitcnt lgkmcnt(0)
	v_mfma_f32_16x16x32_bf16 v[60:63], v[180:183], v[196:199], v[60:63]
	v_mfma_f32_16x16x32_bf16 v[56:59], v[188:191], v[196:199], v[56:59]
	v_mfma_f32_16x16x32_bf16 v[52:55], v[180:183], v[204:207], v[52:55]
	v_mfma_f32_16x16x32_bf16 v[48:51], v[188:191], v[204:207], v[48:51]
	v_mfma_f32_16x16x32_bf16 v[44:47], v[180:183], v[212:215], v[44:47]
	v_mfma_f32_16x16x32_bf16 v[40:43], v[188:191], v[212:215], v[40:43]
	v_mfma_f32_16x16x32_bf16 v[36:39], v[180:183], v[220:223], v[36:39]
	v_mfma_f32_16x16x32_bf16 v[32:35], v[188:191], v[220:223], v[32:35]
	v_mfma_f32_16x16x32_bf16 v[60:63], v[184:187], v[200:203], v[60:63]
	v_mfma_f32_16x16x32_bf16 v[56:59], v[192:195], v[200:203], v[56:59]
	v_mfma_f32_16x16x32_bf16 v[52:55], v[184:187], v[208:211], v[52:55]
	v_mfma_f32_16x16x32_bf16 v[48:51], v[192:195], v[208:211], v[48:51]
	v_mfma_f32_16x16x32_bf16 v[44:47], v[184:187], v[216:219], v[44:47]
	v_mfma_f32_16x16x32_bf16 v[40:43], v[192:195], v[216:219], v[40:43]
	v_mfma_f32_16x16x32_bf16 v[36:39], v[184:187], v[224:227], v[36:39]
	v_mfma_f32_16x16x32_bf16 v[32:35], v[192:195], v[224:227], v[32:35]
	s_barrier
	v_readfirstlane_b32 s1, v171
	v_add_u32_e32 v182, 0x2000, v171
	v_lshl_add_u64 v[180:181], v[248:249], 0, s[38:39]
	s_mov_b32 m0, s1
	v_readfirstlane_b32 s1, v182
	global_load_lds_dwordx4 v[180:181], off
	v_lshl_add_u64 v[180:181], v[250:251], 0, s[38:39]
	s_mov_b32 m0, s1
	s_nop 0
	global_load_lds_dwordx4 v[180:181], off
	s_waitcnt vmcnt(6)
	s_barrier
	v_mfma_f32_16x16x32_bf16 v[28:31], v[228:231], v[196:199], v[28:31]
	v_mfma_f32_16x16x32_bf16 v[24:27], v[236:239], v[196:199], v[24:27]
	v_mfma_f32_16x16x32_bf16 v[20:23], v[228:231], v[204:207], v[20:23]
	v_mfma_f32_16x16x32_bf16 v[16:19], v[236:239], v[204:207], v[16:19]
	v_mfma_f32_16x16x32_bf16 v[12:15], v[228:231], v[212:215], v[12:15]
	v_mfma_f32_16x16x32_bf16 v[8:11], v[236:239], v[212:215], v[8:11]
	v_mfma_f32_16x16x32_bf16 v[4:7], v[228:231], v[220:223], v[4:7]
	v_mfma_f32_16x16x32_bf16 v[0:3], v[236:239], v[220:223], v[0:3]
	v_mfma_f32_16x16x32_bf16 v[28:31], v[232:235], v[200:203], v[28:31]
	v_mfma_f32_16x16x32_bf16 v[24:27], v[240:243], v[200:203], v[24:27]
	v_mfma_f32_16x16x32_bf16 v[20:23], v[232:235], v[208:211], v[20:23]
	v_mfma_f32_16x16x32_bf16 v[16:19], v[240:243], v[208:211], v[16:19]
	v_mfma_f32_16x16x32_bf16 v[12:15], v[232:235], v[216:219], v[12:15]
	v_mfma_f32_16x16x32_bf16 v[8:11], v[240:243], v[216:219], v[8:11]
	v_mfma_f32_16x16x32_bf16 v[4:7], v[232:235], v[224:227], v[4:7]
	v_mfma_f32_16x16x32_bf16 v[0:3], v[240:243], v[224:227], v[0:3]
	s_add_i32 s0, s0, 2
	v_lshl_add_u64 v[142:143], v[142:143], 0, s[46:47]
	v_lshl_add_u64 v[144:145], v[144:145], 0, s[46:47]
	v_lshl_add_u64 v[146:147], v[146:147], 0, s[46:47]
	s_cmp_lt_u32 s0, 12
	v_lshl_add_u64 v[148:149], v[148:149], 0, s[46:47]
	s_barrier
	s_cbranch_scc1 .LBB0_1842
	s_or_b32 s0, s8, 0x80
	s_ashr_i32 s1, s0, 31
	s_lshl_b64 s[0:1], s[0:1], 11
	s_add_u32 s0, s45, s0
	s_addc_u32 s1, s64, s1
	v_lshl_add_u64 v[170:171], s[0:1], 0, v[130:131]
	v_lshl_add_u64 v[138:139], v[138:139], 1, v[170:171]
	v_readfirstlane_b32 s2, v178
	v_lshl_add_u64 v[138:139], v[138:139], 0, s[58:59]
	s_mov_b32 m0, s2
	ds_read_b128 v[142:145], v172
	ds_read_b128 v[146:149], v172 offset:1024
	ds_read_b128 v[180:183], v172 offset:2048
	ds_read_b128 v[184:187], v172 offset:3072
	ds_read_b128 v[188:191], v161
	ds_read_b128 v[192:195], v161 offset:1024
	ds_read_b128 v[196:199], v160
	ds_read_b128 v[200:203], v160 offset:1024
	ds_read_b128 v[204:207], v159
	ds_read_b128 v[208:211], v159 offset:1024
	ds_read_b128 v[212:215], v158
	ds_read_b128 v[216:219], v158 offset:1024
	global_load_lds_dwordx4 v[138:139], off
	v_lshl_add_u64 v[138:139], s[0:1], 0, v[134:135]
	v_lshl_add_u64 v[138:139], v[140:141], 1, v[138:139]
	v_readfirstlane_b32 s0, v179
	v_lshl_add_u64 v[138:139], v[138:139], 0, s[58:59]
	s_mov_b32 m0, s0
	v_readlane_b32 s0, v255, 11
	global_load_lds_dwordx4 v[138:139], off
	s_add_i32 s79, s79, s0
	s_barrier
	s_waitcnt lgkmcnt(0)
	s_cmpk_gt_i32 s79, 0x54
	s_cselect_b64 s[60:61], -1, 0
	s_waitcnt lgkmcnt(0)
	v_mfma_f32_16x16x32_bf16 v[124:127], v[142:145], v[188:191], v[124:127]
	v_mfma_f32_16x16x32_bf16 v[116:119], v[142:145], v[196:199], v[116:119]
	v_mfma_f32_16x16x32_bf16 v[108:111], v[142:145], v[204:207], v[108:111]
	v_mfma_f32_16x16x32_bf16 v[100:103], v[142:145], v[212:215], v[100:103]
	v_mfma_f32_16x16x32_bf16 v[124:127], v[146:149], v[192:195], v[124:127]
	v_mfma_f32_16x16x32_bf16 v[120:123], v[180:183], v[188:191], v[120:123]
	v_mfma_f32_16x16x32_bf16 v[116:119], v[146:149], v[200:203], v[116:119]
	v_mfma_f32_16x16x32_bf16 v[112:115], v[180:183], v[196:199], v[112:115]
	v_mfma_f32_16x16x32_bf16 v[108:111], v[146:149], v[208:211], v[108:111]
	v_mfma_f32_16x16x32_bf16 v[104:107], v[180:183], v[204:207], v[104:107]
	v_mfma_f32_16x16x32_bf16 v[100:103], v[146:149], v[216:219], v[100:103]
	v_mfma_f32_16x16x32_bf16 v[96:99], v[180:183], v[212:215], v[96:99]
	v_mfma_f32_16x16x32_bf16 v[138:141], v[184:187], v[192:195], v[120:123]
	v_mfma_f32_16x16x32_bf16 v[220:223], v[184:187], v[200:203], v[112:115]
	v_mfma_f32_16x16x32_bf16 v[224:227], v[184:187], v[208:211], v[104:107]
	v_mfma_f32_16x16x32_bf16 v[228:231], v[184:187], v[216:219], v[96:99]
	s_barrier
	s_nop 1
	ds_read_b128 v[96:99], v169
	ds_read_b128 v[104:107], v169 offset:1024
	ds_read_b128 v[112:115], v169 offset:2048
	ds_read_b128 v[120:123], v169 offset:3072
	s_barrier
	s_waitcnt lgkmcnt(0)
	s_waitcnt lgkmcnt(0)
	v_mfma_f32_16x16x32_bf16 v[92:95], v[96:99], v[188:191], v[92:95]
	v_mfma_f32_16x16x32_bf16 v[88:91], v[112:115], v[188:191], v[88:91]
	v_mfma_f32_16x16x32_bf16 v[84:87], v[96:99], v[196:199], v[84:87]
	v_mfma_f32_16x16x32_bf16 v[80:83], v[112:115], v[196:199], v[80:83]
	v_mfma_f32_16x16x32_bf16 v[76:79], v[96:99], v[204:207], v[76:79]
	v_mfma_f32_16x16x32_bf16 v[72:75], v[112:115], v[204:207], v[72:75]
	v_mfma_f32_16x16x32_bf16 v[68:71], v[96:99], v[212:215], v[68:71]
	v_mfma_f32_16x16x32_bf16 v[64:67], v[112:115], v[212:215], v[64:67]
	v_mfma_f32_16x16x32_bf16 v[92:95], v[104:107], v[192:195], v[92:95]
	v_mfma_f32_16x16x32_bf16 v[88:91], v[120:123], v[192:195], v[88:91]
	v_mfma_f32_16x16x32_bf16 v[84:87], v[104:107], v[200:203], v[84:87]
	v_mfma_f32_16x16x32_bf16 v[80:83], v[120:123], v[200:203], v[80:83]
	v_mfma_f32_16x16x32_bf16 v[76:79], v[104:107], v[208:211], v[76:79]
	v_mfma_f32_16x16x32_bf16 v[72:75], v[120:123], v[208:211], v[72:75]
	v_mfma_f32_16x16x32_bf16 v[68:71], v[104:107], v[216:219], v[68:71]
	v_mfma_f32_16x16x32_bf16 v[64:67], v[120:123], v[216:219], v[64:67]
	s_barrier
	ds_read_b128 v[168:171], v161 offset:16384
	ds_read_b128 v[188:191], v161 offset:17408
	ds_read_b128 v[192:195], v160 offset:16384
	ds_read_b128 v[196:199], v160 offset:17408
	ds_read_b128 v[200:203], v159 offset:16384
	ds_read_b128 v[204:207], v159 offset:17408
	ds_read_b128 v[208:211], v158 offset:16384
	ds_read_b128 v[212:215], v158 offset:17408
	s_waitcnt vmcnt(4)
	s_barrier
	s_waitcnt lgkmcnt(0)
	s_waitcnt lgkmcnt(0)
	v_mfma_f32_16x16x32_bf16 v[60:63], v[142:145], v[168:171], v[60:63]
	v_mfma_f32_16x16x32_bf16 v[52:55], v[142:145], v[192:195], v[52:55]
	v_mfma_f32_16x16x32_bf16 v[44:47], v[142:145], v[200:203], v[44:47]
	v_mfma_f32_16x16x32_bf16 v[36:39], v[142:145], v[208:211], v[36:39]
	v_mfma_f32_16x16x32_bf16 v[60:63], v[146:149], v[188:191], v[60:63]
	v_mfma_f32_16x16x32_bf16 v[56:59], v[180:183], v[168:171], v[56:59]
	v_mfma_f32_16x16x32_bf16 v[52:55], v[146:149], v[196:199], v[52:55]
	v_mfma_f32_16x16x32_bf16 v[48:51], v[180:183], v[192:195], v[48:51]
	v_mfma_f32_16x16x32_bf16 v[44:47], v[146:149], v[204:207], v[44:47]
	v_mfma_f32_16x16x32_bf16 v[40:43], v[180:183], v[200:203], v[40:43]
	v_mfma_f32_16x16x32_bf16 v[36:39], v[146:149], v[212:215], v[36:39]
	v_mfma_f32_16x16x32_bf16 v[32:35], v[180:183], v[208:211], v[32:35]
	v_mfma_f32_16x16x32_bf16 v[216:219], v[184:187], v[188:191], v[56:59]
	v_mfma_f32_16x16x32_bf16 v[232:235], v[184:187], v[196:199], v[48:51]
	v_mfma_f32_16x16x32_bf16 v[236:239], v[184:187], v[204:207], v[40:43]
	v_mfma_f32_16x16x32_bf16 v[142:145], v[184:187], v[212:215], v[32:35]
	v_mfma_f32_16x16x32_bf16 v[28:31], v[96:99], v[168:171], v[28:31]
	v_mfma_f32_16x16x32_bf16 v[24:27], v[112:115], v[168:171], v[24:27]
	v_mfma_f32_16x16x32_bf16 v[20:23], v[96:99], v[192:195], v[20:23]
	v_mfma_f32_16x16x32_bf16 v[16:19], v[112:115], v[192:195], v[16:19]
	v_mfma_f32_16x16x32_bf16 v[12:15], v[96:99], v[200:203], v[12:15]
	v_mfma_f32_16x16x32_bf16 v[8:11], v[112:115], v[200:203], v[8:11]
	v_mfma_f32_16x16x32_bf16 v[4:7], v[96:99], v[208:211], v[4:7]
	v_mfma_f32_16x16x32_bf16 v[0:3], v[112:115], v[208:211], v[0:3]
	v_mfma_f32_16x16x32_bf16 v[28:31], v[104:107], v[188:191], v[28:31]
	v_mfma_f32_16x16x32_bf16 v[24:27], v[120:123], v[188:191], v[24:27]
	v_mfma_f32_16x16x32_bf16 v[20:23], v[104:107], v[196:199], v[20:23]
	v_mfma_f32_16x16x32_bf16 v[16:19], v[120:123], v[196:199], v[16:19]
	v_mfma_f32_16x16x32_bf16 v[12:15], v[104:107], v[204:207], v[12:15]
	v_mfma_f32_16x16x32_bf16 v[8:11], v[120:123], v[204:207], v[8:11]
	v_mfma_f32_16x16x32_bf16 v[4:7], v[104:107], v[212:215], v[4:7]
	v_mfma_f32_16x16x32_bf16 v[0:3], v[120:123], v[212:215], v[0:3]
	s_barrier
	ds_read_b128 v[32:35], v163
	ds_read_b128 v[146:149], v163 offset:1024
	ds_read_b128 v[168:171], v163 offset:2048
	ds_read_b128 v[178:181], v163 offset:3072
	ds_read_b128 v[40:43], v161 offset:32768
	ds_read_b128 v[48:51], v161 offset:33792
	ds_read_b128 v[56:59], v160 offset:32768
	ds_read_b128 v[182:185], v160 offset:33792
	ds_read_b128 v[186:189], v159 offset:32768
	ds_read_b128 v[190:193], v159 offset:33792
	ds_read_b128 v[194:197], v158 offset:32768
	ds_read_b128 v[198:201], v158 offset:33792
	s_waitcnt vmcnt(2)
	s_barrier
	s_waitcnt lgkmcnt(0)
	s_waitcnt lgkmcnt(0)
	v_mfma_f32_16x16x32_bf16 v[96:99], v[32:35], v[40:43], v[124:127]
	v_mfma_f32_16x16x32_bf16 v[120:123], v[146:149], v[48:51], v[96:99]
	v_mfma_f32_16x16x32_bf16 v[96:99], v[168:171], v[40:43], v[138:141]
	v_mfma_f32_16x16x32_bf16 v[124:127], v[178:181], v[48:51], v[96:99]
	v_mfma_f32_16x16x32_bf16 v[96:99], v[32:35], v[56:59], v[116:119]
	v_mfma_f32_16x16x32_bf16 v[112:115], v[146:149], v[182:185], v[96:99]
	v_mfma_f32_16x16x32_bf16 v[96:99], v[168:171], v[56:59], v[220:223]
	v_mfma_f32_16x16x32_bf16 v[116:119], v[178:181], v[182:185], v[96:99]
	v_mfma_f32_16x16x32_bf16 v[96:99], v[32:35], v[186:189], v[108:111]
	v_mfma_f32_16x16x32_bf16 v[104:107], v[146:149], v[190:193], v[96:99]
	v_mfma_f32_16x16x32_bf16 v[96:99], v[168:171], v[186:189], v[224:227]
	v_mfma_f32_16x16x32_bf16 v[108:111], v[178:181], v[190:193], v[96:99]
	v_mfma_f32_16x16x32_bf16 v[96:99], v[32:35], v[194:197], v[100:103]
	v_mfma_f32_16x16x32_bf16 v[100:103], v[168:171], v[194:197], v[228:231]
	v_mfma_f32_16x16x32_bf16 v[96:99], v[146:149], v[198:201], v[96:99]
	v_mfma_f32_16x16x32_bf16 v[100:103], v[178:181], v[198:201], v[100:103]
	s_barrier
	ds_read_b128 v[138:141], v162
	ds_read_b128 v[202:205], v162 offset:1024
	ds_read_b128 v[206:209], v162 offset:2048
	ds_read_b128 v[210:213], v162 offset:3072
	s_waitcnt vmcnt(0)
	s_barrier
	s_waitcnt lgkmcnt(0)
	s_waitcnt lgkmcnt(0)
	v_mfma_f32_16x16x32_bf16 v[92:95], v[138:141], v[40:43], v[92:95]
	v_mfma_f32_16x16x32_bf16 v[40:43], v[206:209], v[40:43], v[88:91]
	v_mfma_f32_16x16x32_bf16 v[88:91], v[210:213], v[48:51], v[40:43]
	v_mfma_f32_16x16x32_bf16 v[40:43], v[138:141], v[56:59], v[84:87]
	v_mfma_f32_16x16x32_bf16 v[84:87], v[202:205], v[182:185], v[40:43]
	v_mfma_f32_16x16x32_bf16 v[40:43], v[206:209], v[56:59], v[80:83]
	v_mfma_f32_16x16x32_bf16 v[80:83], v[210:213], v[182:185], v[40:43]
	v_mfma_f32_16x16x32_bf16 v[40:43], v[138:141], v[186:189], v[76:79]
	v_mfma_f32_16x16x32_bf16 v[76:79], v[202:205], v[190:193], v[40:43]
	v_mfma_f32_16x16x32_bf16 v[40:43], v[206:209], v[186:189], v[72:75]
	v_mfma_f32_16x16x32_bf16 v[72:75], v[210:213], v[190:193], v[40:43]
	v_mfma_f32_16x16x32_bf16 v[40:43], v[138:141], v[194:197], v[68:71]
	v_mfma_f32_16x16x32_bf16 v[68:71], v[202:205], v[198:201], v[40:43]
	v_mfma_f32_16x16x32_bf16 v[40:43], v[206:209], v[194:197], v[64:67]
	v_mfma_f32_16x16x32_bf16 v[92:95], v[202:205], v[48:51], v[92:95]
	v_mfma_f32_16x16x32_bf16 v[64:67], v[210:213], v[198:201], v[40:43]
	s_barrier
	ds_read_b128 v[182:185], v161 offset:49152
	ds_read_b128 v[186:189], v161 offset:50176
	ds_read_b128 v[190:193], v160 offset:49152
	ds_read_b128 v[160:163], v160 offset:50176
	ds_read_b128 v[194:197], v159 offset:49152
	ds_read_b128 v[198:201], v159 offset:50176
	ds_read_b128 v[220:223], v158 offset:49152
	ds_read_b128 v[224:227], v158 offset:50176
	s_barrier
	s_waitcnt lgkmcnt(0)
	s_waitcnt lgkmcnt(0)
	v_mfma_f32_16x16x32_bf16 v[40:43], v[32:35], v[182:185], v[60:63]
	v_mfma_f32_16x16x32_bf16 v[56:59], v[146:149], v[186:189], v[40:43]
	v_mfma_f32_16x16x32_bf16 v[40:43], v[168:171], v[182:185], v[216:219]
	v_mfma_f32_16x16x32_bf16 v[60:63], v[178:181], v[186:189], v[40:43]
	v_mfma_f32_16x16x32_bf16 v[40:43], v[32:35], v[190:193], v[52:55]
	v_mfma_f32_16x16x32_bf16 v[48:51], v[146:149], v[160:163], v[40:43]
	v_mfma_f32_16x16x32_bf16 v[40:43], v[168:171], v[190:193], v[232:235]
	v_mfma_f32_16x16x32_bf16 v[52:55], v[178:181], v[160:163], v[40:43]
	v_mfma_f32_16x16x32_bf16 v[40:43], v[32:35], v[194:197], v[44:47]
	v_mfma_f32_16x16x32_bf16 v[44:47], v[168:171], v[194:197], v[236:239]
	v_mfma_f32_16x16x32_bf16 v[32:35], v[32:35], v[220:223], v[36:39]
	v_mfma_f32_16x16x32_bf16 v[36:39], v[168:171], v[220:223], v[142:145]
	v_mfma_f32_16x16x32_bf16 v[40:43], v[146:149], v[198:201], v[40:43]
	v_mfma_f32_16x16x32_bf16 v[44:47], v[178:181], v[198:201], v[44:47]
	v_mfma_f32_16x16x32_bf16 v[32:35], v[146:149], v[224:227], v[32:35]
	v_mfma_f32_16x16x32_bf16 v[36:39], v[178:181], v[224:227], v[36:39]
	v_mfma_f32_16x16x32_bf16 v[28:31], v[138:141], v[182:185], v[28:31]
	v_mfma_f32_16x16x32_bf16 v[24:27], v[206:209], v[182:185], v[24:27]
	v_mfma_f32_16x16x32_bf16 v[20:23], v[138:141], v[190:193], v[20:23]
	v_mfma_f32_16x16x32_bf16 v[16:19], v[206:209], v[190:193], v[16:19]
	v_mfma_f32_16x16x32_bf16 v[12:15], v[138:141], v[194:197], v[12:15]
	v_mfma_f32_16x16x32_bf16 v[8:11], v[206:209], v[194:197], v[8:11]
	v_mfma_f32_16x16x32_bf16 v[4:7], v[138:141], v[220:223], v[4:7]
	v_mfma_f32_16x16x32_bf16 v[0:3], v[206:209], v[220:223], v[0:3]
	v_mfma_f32_16x16x32_bf16 v[28:31], v[202:205], v[186:189], v[28:31]
	v_mfma_f32_16x16x32_bf16 v[24:27], v[210:213], v[186:189], v[24:27]
	v_mfma_f32_16x16x32_bf16 v[20:23], v[202:205], v[160:163], v[20:23]
	v_mfma_f32_16x16x32_bf16 v[16:19], v[210:213], v[160:163], v[16:19]
	v_mfma_f32_16x16x32_bf16 v[12:15], v[202:205], v[198:201], v[12:15]
	v_mfma_f32_16x16x32_bf16 v[8:11], v[210:213], v[198:201], v[8:11]
	v_mfma_f32_16x16x32_bf16 v[4:7], v[202:205], v[224:227], v[4:7]
	v_mfma_f32_16x16x32_bf16 v[0:3], v[210:213], v[224:227], v[0:3]
	s_and_b64 vcc, exec, s[60:61]
	s_barrier
	s_cbranch_vccnz .LBB0_1845
	s_mul_hi_i32 s0, s79, 0x66666667
	s_lshr_b32 s1, s0, 31
	s_ashr_i32 s0, s0, 1
	s_add_i32 s0, s0, s1
	v_readlane_b32 s1, v255, 15
	s_add_i32 s1, s0, s1
	s_mul_i32 s0, s0, 5
	s_sub_i32 s0, s79, s0
	v_readlane_b32 s2, v255, 14
	s_add_i32 s2, s0, s2
	s_lshl_b32 s4, s2, 8
	s_ashr_i32 s5, s4, 31
	s_lshl_b32 s0, s1, 8
	s_lshl_b64 s[10:11], s[4:5], 11
	s_add_u32 s10, s65, s10
	s_addc_u32 s11, s66, s11
	v_lshl_add_u64 v[138:139], s[10:11], 0, v[130:131]
	v_readfirstlane_b32 s1, v153
	v_lshl_add_u64 v[138:139], v[138:139], 0, v[132:133]
	s_mov_b32 m0, s1
	v_readfirstlane_b32 s1, v173
	global_load_lds_dwordx4 v[138:139], off
	s_mov_b32 m0, s1
	s_ashr_i32 s1, s0, 31
	v_lshl_add_u64 v[138:139], s[10:11], 0, v[134:135]
	s_lshl_b64 s[10:11], s[0:1], 11
	s_add_u32 s10, s45, s10
	v_lshl_add_u64 v[138:139], v[138:139], 0, v[136:137]
	s_addc_u32 s11, s64, s11
	s_bitset1_b32 s4, 7
	global_load_lds_dwordx4 v[138:139], off
	v_lshl_add_u64 v[138:139], s[10:11], 0, v[130:131]
	v_readfirstlane_b32 s1, v152
	s_ashr_i32 s5, s4, 31
	v_lshl_add_u64 v[138:139], v[138:139], 0, v[132:133]
	s_mov_b32 m0, s1
	s_lshl_b64 s[4:5], s[4:5], 11
	global_load_lds_dwordx4 v[138:139], off
	v_lshl_add_u64 v[138:139], s[10:11], 0, v[134:135]
	v_readfirstlane_b32 s1, v174
	s_add_u32 s4, s65, s4
	v_lshl_add_u64 v[138:139], v[138:139], 0, v[136:137]
	s_mov_b32 m0, s1
	s_addc_u32 s5, s66, s5
	global_load_lds_dwordx4 v[138:139], off
	v_lshl_add_u64 v[138:139], s[4:5], 0, v[130:131]
	v_readfirstlane_b32 s1, v151
	v_lshl_add_u64 v[138:139], v[138:139], 0, v[132:133]
	s_mov_b32 m0, s1
	v_readfirstlane_b32 s1, v175
	s_bitset1_b32 s0, 7
	global_load_lds_dwordx4 v[138:139], off
	s_mov_b32 m0, s1
	s_ashr_i32 s1, s0, 31
	s_lshl_b64 s[0:1], s[0:1], 11
	s_add_u32 s0, s45, s0
	v_lshl_add_u64 v[138:139], s[4:5], 0, v[134:135]
	s_addc_u32 s1, s64, s1
	v_lshl_add_u64 v[138:139], v[138:139], 0, v[136:137]
	v_lshl_add_u64 v[130:131], s[0:1], 0, v[130:131]
	v_readfirstlane_b32 s2, v176
	global_load_lds_dwordx4 v[138:139], off
	v_lshl_add_u64 v[130:131], v[130:131], 0, v[132:133]
	s_mov_b32 m0, s2
	s_nop 0
	global_load_lds_dwordx4 v[130:131], off
	v_lshl_add_u64 v[130:131], s[0:1], 0, v[134:135]
	v_readfirstlane_b32 s0, v177
	v_lshl_add_u64 v[130:131], v[130:131], 0, v[136:137]
	s_mov_b32 m0, s0
	s_nop 0
	global_load_lds_dwordx4 v[130:131], off

.LBB0_2799:
	ds_read_b128 v[182:185], v180
	ds_read_b128 v[186:189], v180 offset:1024
	ds_read_b128 v[190:193], v180 offset:2048
	ds_read_b128 v[194:197], v180 offset:3072
	v_add_u32_e32 v0, 0xc000, v162
	v_lshl_add_u64 v[246:247], v[142:143], 0, s[48:49]
	v_readfirstlane_b32 s4, v0
	v_lshl_add_u64 v[2:3], v[246:247], 0, s[20:21]
	s_mov_b32 m0, s4
	ds_read_b128 v[198:201], v161
	ds_read_b128 v[202:205], v161 offset:1024
	ds_read_b128 v[206:209], v160
	ds_read_b128 v[210:213], v160 offset:1024
	ds_read_b128 v[214:217], v159
	ds_read_b128 v[218:221], v159 offset:1024
	ds_read_b128 v[222:225], v158
	ds_read_b128 v[226:229], v158 offset:1024
	global_load_lds_dwordx4 v[2:3], off
	v_add_u32_e32 v2, 0xe000, v162
	v_lshl_add_u64 v[248:249], v[144:145], 0, s[48:49]
	v_readfirstlane_b32 s4, v2
	v_lshl_add_u64 v[230:231], v[248:249], 0, s[20:21]
	s_mov_b32 m0, s4
	s_nop 0
	global_load_lds_dwordx4 v[230:231], off
	s_waitcnt lgkmcnt(8)
	s_barrier
	s_waitcnt lgkmcnt(0)
	s_waitcnt lgkmcnt(0)
	v_mfma_f32_16x16x32_bf16 v[128:131], v[182:185], v[198:201], v[128:131]
	v_mfma_f32_16x16x32_bf16 v[124:127], v[190:193], v[198:201], v[124:127]
	v_mfma_f32_16x16x32_bf16 v[120:123], v[182:185], v[206:209], v[120:123]
	v_mfma_f32_16x16x32_bf16 v[116:119], v[190:193], v[206:209], v[116:119]
	v_mfma_f32_16x16x32_bf16 v[112:115], v[182:185], v[214:217], v[112:115]
	v_mfma_f32_16x16x32_bf16 v[108:111], v[190:193], v[214:217], v[108:111]
	v_mfma_f32_16x16x32_bf16 v[104:107], v[182:185], v[222:225], v[104:107]
	v_mfma_f32_16x16x32_bf16 v[100:103], v[190:193], v[222:225], v[100:103]
	v_mfma_f32_16x16x32_bf16 v[128:131], v[186:189], v[202:205], v[128:131]
	v_mfma_f32_16x16x32_bf16 v[124:127], v[194:197], v[202:205], v[124:127]
	v_mfma_f32_16x16x32_bf16 v[120:123], v[186:189], v[210:213], v[120:123]
	v_mfma_f32_16x16x32_bf16 v[116:119], v[194:197], v[210:213], v[116:119]
	v_mfma_f32_16x16x32_bf16 v[112:115], v[186:189], v[218:221], v[112:115]
	v_mfma_f32_16x16x32_bf16 v[108:111], v[194:197], v[218:221], v[108:111]
	v_mfma_f32_16x16x32_bf16 v[104:107], v[186:189], v[226:229], v[104:107]
	v_mfma_f32_16x16x32_bf16 v[100:103], v[194:197], v[226:229], v[100:103]
	s_barrier
	v_lshl_add_u64 v[250:251], v[138:139], 0, s[48:49]
	v_readfirstlane_b32 s4, v147
	v_lshl_add_u64 v[252:253], v[250:251], 0, s[24:25]
	s_mov_b32 m0, s4
	v_add_u32_e32 v3, 0x2000, v147
	ds_read_b128 v[230:233], v178
	ds_read_b128 v[234:237], v178 offset:1024
	ds_read_b128 v[238:241], v178 offset:2048
	ds_read_b128 v[242:245], v178 offset:3072
	global_load_lds_dwordx4 v[252:253], off
	v_lshl_add_u64 v[252:253], v[140:141], 0, s[48:49]
	v_readfirstlane_b32 s4, v3
	v_lshl_add_u64 v[132:133], v[252:253], 0, s[24:25]
	s_mov_b32 m0, s4
	s_add_i32 s4, s2, 2
	global_load_lds_dwordx4 v[132:133], off
	s_barrier
	s_waitcnt lgkmcnt(0)
	s_waitcnt lgkmcnt(0)
	v_mfma_f32_16x16x32_bf16 v[96:99], v[230:233], v[198:201], v[96:99]
	v_mfma_f32_16x16x32_bf16 v[92:95], v[238:241], v[198:201], v[92:95]
	v_mfma_f32_16x16x32_bf16 v[88:91], v[230:233], v[206:209], v[88:91]
	v_mfma_f32_16x16x32_bf16 v[84:87], v[238:241], v[206:209], v[84:87]
	v_mfma_f32_16x16x32_bf16 v[80:83], v[230:233], v[214:217], v[80:83]
	v_mfma_f32_16x16x32_bf16 v[76:79], v[238:241], v[214:217], v[76:79]
	v_mfma_f32_16x16x32_bf16 v[72:75], v[230:233], v[222:225], v[72:75]
	v_mfma_f32_16x16x32_bf16 v[68:71], v[238:241], v[222:225], v[68:71]
	v_mfma_f32_16x16x32_bf16 v[96:99], v[234:237], v[202:205], v[96:99]
	v_mfma_f32_16x16x32_bf16 v[92:95], v[242:245], v[202:205], v[92:95]
	v_mfma_f32_16x16x32_bf16 v[88:91], v[234:237], v[210:213], v[88:91]
	v_mfma_f32_16x16x32_bf16 v[84:87], v[242:245], v[210:213], v[84:87]
	v_mfma_f32_16x16x32_bf16 v[80:83], v[234:237], v[218:221], v[80:83]
	v_mfma_f32_16x16x32_bf16 v[76:79], v[242:245], v[218:221], v[76:79]
	v_mfma_f32_16x16x32_bf16 v[72:75], v[234:237], v[226:229], v[72:75]
	v_mfma_f32_16x16x32_bf16 v[68:71], v[242:245], v[226:229], v[68:71]
	v_readfirstlane_b32 s5, v162
	v_lshl_add_u64 v[132:133], v[246:247], 0, s[26:27]
	s_mov_b32 m0, s5
	v_readfirstlane_b32 s5, v163
	s_barrier
	ds_read_b128 v[198:201], v161 offset:16384
	ds_read_b128 v[202:205], v161 offset:17408
	ds_read_b128 v[206:209], v160 offset:16384
	ds_read_b128 v[210:213], v160 offset:17408
	ds_read_b128 v[214:217], v159 offset:16384
	ds_read_b128 v[218:221], v159 offset:17408
	ds_read_b128 v[222:225], v158 offset:16384
	ds_read_b128 v[226:229], v158 offset:17408
	global_load_lds_dwordx4 v[132:133], off
	v_lshl_add_u64 v[132:133], v[248:249], 0, s[26:27]
	s_mov_b32 m0, s5
	s_nop 0
	global_load_lds_dwordx4 v[132:133], off
	s_barrier
	s_waitcnt lgkmcnt(0)
	s_waitcnt lgkmcnt(0)
	v_mfma_f32_16x16x32_bf16 v[64:67], v[182:185], v[198:201], v[64:67]
	v_mfma_f32_16x16x32_bf16 v[60:63], v[190:193], v[198:201], v[60:63]
	v_mfma_f32_16x16x32_bf16 v[56:59], v[182:185], v[206:209], v[56:59]
	v_mfma_f32_16x16x32_bf16 v[52:55], v[190:193], v[206:209], v[52:55]
	v_mfma_f32_16x16x32_bf16 v[48:51], v[182:185], v[214:217], v[48:51]
	v_mfma_f32_16x16x32_bf16 v[44:47], v[190:193], v[214:217], v[44:47]
	v_mfma_f32_16x16x32_bf16 v[40:43], v[182:185], v[222:225], v[40:43]
	v_mfma_f32_16x16x32_bf16 v[36:39], v[190:193], v[222:225], v[36:39]
	v_mfma_f32_16x16x32_bf16 v[64:67], v[186:189], v[202:205], v[64:67]
	v_mfma_f32_16x16x32_bf16 v[60:63], v[194:197], v[202:205], v[60:63]
	v_mfma_f32_16x16x32_bf16 v[56:59], v[186:189], v[210:213], v[56:59]
	v_mfma_f32_16x16x32_bf16 v[52:55], v[194:197], v[210:213], v[52:55]
	v_mfma_f32_16x16x32_bf16 v[48:51], v[186:189], v[218:221], v[48:51]
	v_mfma_f32_16x16x32_bf16 v[44:47], v[194:197], v[218:221], v[44:47]
	v_mfma_f32_16x16x32_bf16 v[40:43], v[186:189], v[226:229], v[40:43]
	v_mfma_f32_16x16x32_bf16 v[36:39], v[194:197], v[226:229], v[36:39]
	s_barrier
	v_readfirstlane_b32 s5, v168
	v_add_u32_e32 v3, 0x2000, v168
	v_lshl_add_u64 v[132:133], v[250:251], 0, s[28:29]
	s_mov_b32 m0, s5
	v_readfirstlane_b32 s5, v3
	global_load_lds_dwordx4 v[132:133], off
	v_lshl_add_u64 v[132:133], v[252:253], 0, s[28:29]
	s_mov_b32 m0, s5
	s_nop 0
	global_load_lds_dwordx4 v[132:133], off
	s_waitcnt vmcnt(6)
	s_barrier
	v_mfma_f32_16x16x32_bf16 v[32:35], v[230:233], v[198:201], v[32:35]
	v_mfma_f32_16x16x32_bf16 v[28:31], v[238:241], v[198:201], v[28:31]
	v_mfma_f32_16x16x32_bf16 v[24:27], v[230:233], v[206:209], v[24:27]
	v_mfma_f32_16x16x32_bf16 v[20:23], v[238:241], v[206:209], v[20:23]
	v_mfma_f32_16x16x32_bf16 v[16:19], v[230:233], v[214:217], v[16:19]
	v_mfma_f32_16x16x32_bf16 v[12:15], v[238:241], v[214:217], v[12:15]
	v_mfma_f32_16x16x32_bf16 v[8:11], v[230:233], v[222:225], v[8:11]
	v_mfma_f32_16x16x32_bf16 v[4:7], v[238:241], v[222:225], v[4:7]
	v_mfma_f32_16x16x32_bf16 v[32:35], v[234:237], v[202:205], v[32:35]
	v_mfma_f32_16x16x32_bf16 v[28:31], v[242:245], v[202:205], v[28:31]
	v_mfma_f32_16x16x32_bf16 v[24:27], v[234:237], v[210:213], v[24:27]
	v_mfma_f32_16x16x32_bf16 v[20:23], v[242:245], v[210:213], v[20:23]
	v_mfma_f32_16x16x32_bf16 v[16:19], v[234:237], v[218:221], v[16:19]
	v_mfma_f32_16x16x32_bf16 v[12:15], v[242:245], v[218:221], v[12:15]
	v_mfma_f32_16x16x32_bf16 v[8:11], v[234:237], v[226:229], v[8:11]
	v_mfma_f32_16x16x32_bf16 v[4:7], v[242:245], v[226:229], v[4:7]
	s_barrier
	ds_read_b128 v[182:185], v170
	ds_read_b128 v[186:189], v170 offset:1024
	ds_read_b128 v[190:193], v170 offset:2048
	ds_read_b128 v[194:197], v170 offset:3072
	v_readfirstlane_b32 s5, v169
	v_lshl_add_u64 v[132:133], v[246:247], 0, s[30:31]
	s_mov_b32 m0, s5
	v_readfirstlane_b32 s5, v171
	ds_read_b128 v[198:201], v161 offset:32768
	ds_read_b128 v[202:205], v161 offset:33792
	ds_read_b128 v[206:209], v160 offset:32768
	ds_read_b128 v[210:213], v160 offset:33792
	ds_read_b128 v[214:217], v159 offset:32768
	ds_read_b128 v[218:221], v159 offset:33792
	ds_read_b128 v[222:225], v158 offset:32768
	ds_read_b128 v[226:229], v158 offset:33792
	global_load_lds_dwordx4 v[132:133], off
	v_lshl_add_u64 v[132:133], v[248:249], 0, s[30:31]
	s_mov_b32 m0, s5
	s_nop 0
	global_load_lds_dwordx4 v[132:133], off
	s_waitcnt lgkmcnt(8)
	s_barrier
	s_waitcnt lgkmcnt(0)
	s_waitcnt lgkmcnt(0)
	v_mfma_f32_16x16x32_bf16 v[128:131], v[182:185], v[198:201], v[128:131]
	v_mfma_f32_16x16x32_bf16 v[124:127], v[190:193], v[198:201], v[124:127]
	v_mfma_f32_16x16x32_bf16 v[120:123], v[182:185], v[206:209], v[120:123]
	v_mfma_f32_16x16x32_bf16 v[116:119], v[190:193], v[206:209], v[116:119]
	v_mfma_f32_16x16x32_bf16 v[112:115], v[182:185], v[214:217], v[112:115]
	v_mfma_f32_16x16x32_bf16 v[108:111], v[190:193], v[214:217], v[108:111]
	v_mfma_f32_16x16x32_bf16 v[104:107], v[182:185], v[222:225], v[104:107]
	v_mfma_f32_16x16x32_bf16 v[100:103], v[190:193], v[222:225], v[100:103]
	v_mfma_f32_16x16x32_bf16 v[128:131], v[186:189], v[202:205], v[128:131]
	v_mfma_f32_16x16x32_bf16 v[124:127], v[194:197], v[202:205], v[124:127]
	v_mfma_f32_16x16x32_bf16 v[120:123], v[186:189], v[210:213], v[120:123]
	v_mfma_f32_16x16x32_bf16 v[116:119], v[194:197], v[210:213], v[116:119]
	v_mfma_f32_16x16x32_bf16 v[112:115], v[186:189], v[218:221], v[112:115]
	v_mfma_f32_16x16x32_bf16 v[108:111], v[194:197], v[218:221], v[108:111]
	v_mfma_f32_16x16x32_bf16 v[104:107], v[186:189], v[226:229], v[104:107]
	v_mfma_f32_16x16x32_bf16 v[100:103], v[194:197], v[226:229], v[100:103]
	s_barrier
	v_readfirstlane_b32 s5, v172
	v_lshl_add_u64 v[132:133], v[250:251], 0, s[34:35]
	s_mov_b32 m0, s5
	v_readfirstlane_b32 s5, v173
	ds_read_b128 v[230:233], v167
	ds_read_b128 v[234:237], v167 offset:1024
	ds_read_b128 v[238:241], v167 offset:2048
	ds_read_b128 v[242:245], v167 offset:3072
	global_load_lds_dwordx4 v[132:133], off
	v_lshl_add_u64 v[132:133], v[252:253], 0, s[34:35]
	s_mov_b32 m0, s5
	s_nop 0
	global_load_lds_dwordx4 v[132:133], off
	s_barrier
	s_waitcnt lgkmcnt(0)
	s_waitcnt lgkmcnt(0)
	v_mfma_f32_16x16x32_bf16 v[96:99], v[230:233], v[198:201], v[96:99]
	v_mfma_f32_16x16x32_bf16 v[92:95], v[238:241], v[198:201], v[92:95]
	v_mfma_f32_16x16x32_bf16 v[88:91], v[230:233], v[206:209], v[88:91]
	v_mfma_f32_16x16x32_bf16 v[84:87], v[238:241], v[206:209], v[84:87]
	v_mfma_f32_16x16x32_bf16 v[80:83], v[230:233], v[214:217], v[80:83]
	v_mfma_f32_16x16x32_bf16 v[76:79], v[238:241], v[214:217], v[76:79]
	v_mfma_f32_16x16x32_bf16 v[72:75], v[230:233], v[222:225], v[72:75]
	v_mfma_f32_16x16x32_bf16 v[68:71], v[238:241], v[222:225], v[68:71]
	v_mfma_f32_16x16x32_bf16 v[96:99], v[234:237], v[202:205], v[96:99]
	v_mfma_f32_16x16x32_bf16 v[92:95], v[242:245], v[202:205], v[92:95]
	v_mfma_f32_16x16x32_bf16 v[88:91], v[234:237], v[210:213], v[88:91]
	v_mfma_f32_16x16x32_bf16 v[84:87], v[242:245], v[210:213], v[84:87]
	v_mfma_f32_16x16x32_bf16 v[80:83], v[234:237], v[218:221], v[80:83]
	v_mfma_f32_16x16x32_bf16 v[76:79], v[242:245], v[218:221], v[76:79]
	v_mfma_f32_16x16x32_bf16 v[72:75], v[234:237], v[226:229], v[72:75]
	v_mfma_f32_16x16x32_bf16 v[68:71], v[242:245], v[226:229], v[68:71]
	v_readfirstlane_b32 s5, v174
	v_lshl_add_u64 v[132:133], v[246:247], 0, s[36:37]
	s_mov_b32 m0, s5
	v_readfirstlane_b32 s5, v175
	s_barrier
	ds_read_b128 v[198:201], v161 offset:49152
	ds_read_b128 v[202:205], v161 offset:50176
	ds_read_b128 v[206:209], v160 offset:49152
	ds_read_b128 v[210:213], v160 offset:50176
	ds_read_b128 v[214:217], v159 offset:49152
	ds_read_b128 v[218:221], v159 offset:50176
	ds_read_b128 v[222:225], v158 offset:49152
	ds_read_b128 v[226:229], v158 offset:50176
	global_load_lds_dwordx4 v[132:133], off
	v_lshl_add_u64 v[132:133], v[248:249], 0, s[36:37]
	s_mov_b32 m0, s5
	s_nop 0
	global_load_lds_dwordx4 v[132:133], off
	s_barrier
	s_waitcnt lgkmcnt(0)
	s_waitcnt lgkmcnt(0)
	v_mfma_f32_16x16x32_bf16 v[64:67], v[182:185], v[198:201], v[64:67]
	v_mfma_f32_16x16x32_bf16 v[60:63], v[190:193], v[198:201], v[60:63]
	v_mfma_f32_16x16x32_bf16 v[56:59], v[182:185], v[206:209], v[56:59]
	v_mfma_f32_16x16x32_bf16 v[52:55], v[190:193], v[206:209], v[52:55]
	v_mfma_f32_16x16x32_bf16 v[48:51], v[182:185], v[214:217], v[48:51]
	v_mfma_f32_16x16x32_bf16 v[44:47], v[190:193], v[214:217], v[44:47]
	v_mfma_f32_16x16x32_bf16 v[40:43], v[182:185], v[222:225], v[40:43]
	v_mfma_f32_16x16x32_bf16 v[36:39], v[190:193], v[222:225], v[36:39]
	v_mfma_f32_16x16x32_bf16 v[64:67], v[186:189], v[202:205], v[64:67]
	v_mfma_f32_16x16x32_bf16 v[60:63], v[194:197], v[202:205], v[60:63]
	v_mfma_f32_16x16x32_bf16 v[56:59], v[186:189], v[210:213], v[56:59]
	v_mfma_f32_16x16x32_bf16 v[52:55], v[194:197], v[210:213], v[52:55]
	v_mfma_f32_16x16x32_bf16 v[48:51], v[186:189], v[218:221], v[48:51]
	v_mfma_f32_16x16x32_bf16 v[44:47], v[194:197], v[218:221], v[44:47]
	v_mfma_f32_16x16x32_bf16 v[40:43], v[186:189], v[226:229], v[40:43]
	v_mfma_f32_16x16x32_bf16 v[36:39], v[194:197], v[226:229], v[36:39]
	s_barrier
	v_readfirstlane_b32 s5, v176
	v_lshl_add_u64 v[132:133], v[250:251], 0, s[38:39]
	s_mov_b32 m0, s5
	v_readfirstlane_b32 s5, v177
	global_load_lds_dwordx4 v[132:133], off
	v_lshl_add_u64 v[132:133], v[252:253], 0, s[38:39]
	s_mov_b32 m0, s5
	s_nop 0
	global_load_lds_dwordx4 v[132:133], off
	s_waitcnt vmcnt(6)
	s_barrier
	v_mfma_f32_16x16x32_bf16 v[32:35], v[230:233], v[198:201], v[32:35]
	v_mfma_f32_16x16x32_bf16 v[28:31], v[238:241], v[198:201], v[28:31]
	v_mfma_f32_16x16x32_bf16 v[24:27], v[230:233], v[206:209], v[24:27]
	v_mfma_f32_16x16x32_bf16 v[20:23], v[238:241], v[206:209], v[20:23]
	v_mfma_f32_16x16x32_bf16 v[16:19], v[230:233], v[214:217], v[16:19]
	v_mfma_f32_16x16x32_bf16 v[12:15], v[238:241], v[214:217], v[12:15]
	v_mfma_f32_16x16x32_bf16 v[8:11], v[230:233], v[222:225], v[8:11]
	v_mfma_f32_16x16x32_bf16 v[4:7], v[238:241], v[222:225], v[4:7]
	v_mfma_f32_16x16x32_bf16 v[32:35], v[234:237], v[202:205], v[32:35]
	v_mfma_f32_16x16x32_bf16 v[28:31], v[242:245], v[202:205], v[28:31]
	v_mfma_f32_16x16x32_bf16 v[24:27], v[234:237], v[210:213], v[24:27]
	v_mfma_f32_16x16x32_bf16 v[20:23], v[242:245], v[210:213], v[20:23]
	v_mfma_f32_16x16x32_bf16 v[16:19], v[234:237], v[218:221], v[16:19]
	v_mfma_f32_16x16x32_bf16 v[12:15], v[242:245], v[218:221], v[12:15]
	v_mfma_f32_16x16x32_bf16 v[8:11], v[234:237], v[226:229], v[8:11]
	v_mfma_f32_16x16x32_bf16 v[4:7], v[242:245], v[226:229], v[4:7]
	s_add_u32 s48, s48, 0x100
	s_addc_u32 s49, s49, 0
	s_cmp_gt_u32 s2, 11
	s_barrier
	s_cbranch_scc1 .LBB0_2802
	s_mov_b32 s2, s4
	s_cmp_lt_i32 s2, 12
	s_cbranch_scc1 .LBB0_2763

.LBB0_2802:
	v_readfirstlane_b32 s2, v0
	v_lshl_add_u64 v[134:135], v[134:135], 0, s[44:45]
	s_mov_b32 m0, s2
	v_readfirstlane_b32 s2, v2
	ds_read_b128 v[138:141], v180
	ds_read_b128 v[142:145], v180 offset:1024
	ds_read_b128 v[172:175], v180 offset:2048
	ds_read_b128 v[180:183], v180 offset:3072
	ds_read_b128 v[184:187], v161
	ds_read_b128 v[188:191], v161 offset:1024
	ds_read_b128 v[192:195], v160
	ds_read_b128 v[196:199], v160 offset:1024
	ds_read_b128 v[200:203], v159
	ds_read_b128 v[204:207], v159 offset:1024
	ds_read_b128 v[208:211], v158
	ds_read_b128 v[212:215], v158 offset:1024
	global_load_lds_dwordx4 v[134:135], off
	v_lshl_add_u64 v[134:135], v[136:137], 0, s[44:45]
	s_mov_b32 m0, s2
	s_nop 0
	global_load_lds_dwordx4 v[134:135], off
	s_barrier
	s_waitcnt lgkmcnt(0)
	s_waitcnt lgkmcnt(0)
	v_mfma_f32_16x16x32_bf16 v[128:131], v[138:141], v[184:187], v[128:131]
	v_mfma_f32_16x16x32_bf16 v[124:127], v[172:175], v[184:187], v[124:127]
	v_mfma_f32_16x16x32_bf16 v[120:123], v[138:141], v[192:195], v[120:123]
	v_mfma_f32_16x16x32_bf16 v[116:119], v[172:175], v[192:195], v[116:119]
	v_mfma_f32_16x16x32_bf16 v[112:115], v[138:141], v[200:203], v[112:115]
	v_mfma_f32_16x16x32_bf16 v[108:111], v[172:175], v[200:203], v[108:111]
	v_mfma_f32_16x16x32_bf16 v[104:107], v[138:141], v[208:211], v[104:107]
	v_mfma_f32_16x16x32_bf16 v[100:103], v[172:175], v[208:211], v[100:103]
	v_mfma_f32_16x16x32_bf16 v[128:131], v[142:145], v[188:191], v[128:131]
	v_mfma_f32_16x16x32_bf16 v[124:127], v[180:183], v[188:191], v[124:127]
	v_mfma_f32_16x16x32_bf16 v[120:123], v[142:145], v[196:199], v[120:123]
	v_mfma_f32_16x16x32_bf16 v[116:119], v[180:183], v[196:199], v[116:119]
	v_mfma_f32_16x16x32_bf16 v[112:115], v[142:145], v[204:207], v[112:115]
	v_mfma_f32_16x16x32_bf16 v[108:111], v[180:183], v[204:207], v[108:111]
	v_mfma_f32_16x16x32_bf16 v[104:107], v[142:145], v[212:215], v[104:107]
	v_mfma_f32_16x16x32_bf16 v[100:103], v[180:183], v[212:215], v[100:103]
	s_barrier
	ds_read_b128 v[134:137], v178
	ds_read_b128 v[216:219], v178 offset:1024
	ds_read_b128 v[220:223], v178 offset:2048
	ds_read_b128 v[176:179], v178 offset:3072
	s_barrier
	s_waitcnt lgkmcnt(0)
	s_waitcnt lgkmcnt(0)
	v_mfma_f32_16x16x32_bf16 v[96:99], v[134:137], v[184:187], v[96:99]
	v_mfma_f32_16x16x32_bf16 v[92:95], v[220:223], v[184:187], v[92:95]
	v_mfma_f32_16x16x32_bf16 v[88:91], v[134:137], v[192:195], v[88:91]
	v_mfma_f32_16x16x32_bf16 v[84:87], v[220:223], v[192:195], v[84:87]
	v_mfma_f32_16x16x32_bf16 v[80:83], v[134:137], v[200:203], v[80:83]
	v_mfma_f32_16x16x32_bf16 v[76:79], v[220:223], v[200:203], v[76:79]
	v_mfma_f32_16x16x32_bf16 v[72:75], v[134:137], v[208:211], v[72:75]
	v_mfma_f32_16x16x32_bf16 v[68:71], v[220:223], v[208:211], v[68:71]
	v_mfma_f32_16x16x32_bf16 v[96:99], v[216:219], v[188:191], v[96:99]
	v_mfma_f32_16x16x32_bf16 v[92:95], v[176:179], v[188:191], v[92:95]
	v_mfma_f32_16x16x32_bf16 v[88:91], v[216:219], v[196:199], v[88:91]
	v_mfma_f32_16x16x32_bf16 v[84:87], v[176:179], v[196:199], v[84:87]
	v_mfma_f32_16x16x32_bf16 v[80:83], v[216:219], v[204:207], v[80:83]
	v_mfma_f32_16x16x32_bf16 v[76:79], v[176:179], v[204:207], v[76:79]
	v_mfma_f32_16x16x32_bf16 v[72:75], v[216:219], v[212:215], v[72:75]
	v_mfma_f32_16x16x32_bf16 v[68:71], v[176:179], v[212:215], v[68:71]
	s_barrier
	ds_read_b128 v[184:187], v161 offset:16384
	ds_read_b128 v[188:191], v161 offset:17408
	ds_read_b128 v[192:195], v160 offset:16384
	ds_read_b128 v[196:199], v160 offset:17408
	ds_read_b128 v[200:203], v159 offset:16384
	ds_read_b128 v[204:207], v159 offset:17408
	ds_read_b128 v[208:211], v158 offset:16384
	ds_read_b128 v[212:215], v158 offset:17408
	s_waitcnt vmcnt(4)
	s_barrier
	s_waitcnt lgkmcnt(0)
	s_waitcnt lgkmcnt(0)
	v_mfma_f32_16x16x32_bf16 v[64:67], v[138:141], v[184:187], v[64:67]
	v_mfma_f32_16x16x32_bf16 v[56:59], v[138:141], v[192:195], v[56:59]
	v_mfma_f32_16x16x32_bf16 v[48:51], v[138:141], v[200:203], v[48:51]
	v_mfma_f32_16x16x32_bf16 v[40:43], v[138:141], v[208:211], v[40:43]
	v_mfma_f32_16x16x32_bf16 v[36:39], v[172:175], v[208:211], v[36:39]
	v_mfma_f32_16x16x32_bf16 v[224:227], v[142:145], v[188:191], v[64:67]
	v_mfma_f32_16x16x32_bf16 v[60:63], v[172:175], v[184:187], v[60:63]
	v_mfma_f32_16x16x32_bf16 v[232:235], v[142:145], v[196:199], v[56:59]
	v_mfma_f32_16x16x32_bf16 v[52:55], v[172:175], v[192:195], v[52:55]
	v_mfma_f32_16x16x32_bf16 v[240:243], v[142:145], v[204:207], v[48:51]
	v_mfma_f32_16x16x32_bf16 v[44:47], v[172:175], v[200:203], v[44:47]
	v_mfma_f32_16x16x32_bf16 v[138:141], v[142:145], v[212:215], v[40:43]
	v_mfma_f32_16x16x32_bf16 v[142:145], v[180:183], v[212:215], v[36:39]
	v_mfma_f32_16x16x32_bf16 v[228:231], v[180:183], v[188:191], v[60:63]
	v_mfma_f32_16x16x32_bf16 v[236:239], v[180:183], v[196:199], v[52:55]
	v_mfma_f32_16x16x32_bf16 v[244:247], v[180:183], v[204:207], v[44:47]
	v_mfma_f32_16x16x32_bf16 v[8:11], v[134:137], v[208:211], v[8:11]
	v_mfma_f32_16x16x32_bf16 v[32:35], v[134:137], v[184:187], v[32:35]
	v_mfma_f32_16x16x32_bf16 v[28:31], v[220:223], v[184:187], v[28:31]
	v_mfma_f32_16x16x32_bf16 v[24:27], v[134:137], v[192:195], v[24:27]
	v_mfma_f32_16x16x32_bf16 v[20:23], v[220:223], v[192:195], v[20:23]
	v_mfma_f32_16x16x32_bf16 v[16:19], v[134:137], v[200:203], v[16:19]
	v_mfma_f32_16x16x32_bf16 v[12:15], v[220:223], v[200:203], v[12:15]
	v_mfma_f32_16x16x32_bf16 v[134:137], v[216:219], v[212:215], v[8:11]
	v_mfma_f32_16x16x32_bf16 v[2:5], v[220:223], v[208:211], v[4:7]
	v_mfma_f32_16x16x32_bf16 v[172:175], v[216:219], v[188:191], v[32:35]
	v_mfma_f32_16x16x32_bf16 v[180:183], v[176:179], v[188:191], v[28:31]
	v_mfma_f32_16x16x32_bf16 v[184:187], v[216:219], v[196:199], v[24:27]
	v_mfma_f32_16x16x32_bf16 v[188:191], v[176:179], v[196:199], v[20:23]
	v_mfma_f32_16x16x32_bf16 v[192:195], v[216:219], v[204:207], v[16:19]
	v_mfma_f32_16x16x32_bf16 v[196:199], v[176:179], v[204:207], v[12:15]
	v_mfma_f32_16x16x32_bf16 v[176:179], v[176:179], v[212:215], v[2:5]
	s_barrier
	ds_read_b128 v[200:203], v170
	ds_read_b128 v[204:207], v170 offset:1024
	ds_read_b128 v[208:211], v170 offset:2048
	ds_read_b128 v[168:171], v170 offset:3072
	ds_read_b128 v[22:25], v161 offset:32768
	ds_read_b128 v[34:37], v161 offset:33792
	ds_read_b128 v[38:41], v160 offset:32768
	ds_read_b128 v[50:53], v160 offset:33792
	ds_read_b128 v[54:57], v159 offset:32768
	ds_read_b128 v[58:61], v159 offset:33792
	ds_read_b128 v[62:65], v158 offset:32768
	ds_read_b128 v[212:215], v158 offset:33792
	s_waitcnt vmcnt(2)
	s_barrier
	s_waitcnt lgkmcnt(0)
	s_waitcnt lgkmcnt(0)
	v_mfma_f32_16x16x32_bf16 v[18:21], v[200:203], v[54:57], v[112:115]
	v_mfma_f32_16x16x32_bf16 v[26:29], v[204:207], v[58:61], v[18:21]
	v_mfma_f32_16x16x32_bf16 v[18:21], v[208:211], v[54:57], v[108:111]
	v_mfma_f32_16x16x32_bf16 v[30:33], v[168:171], v[58:61], v[18:21]
	v_mfma_f32_16x16x32_bf16 v[18:21], v[200:203], v[62:65], v[104:107]
	v_mfma_f32_16x16x32_bf16 v[2:5], v[200:203], v[22:25], v[128:131]
	v_mfma_f32_16x16x32_bf16 v[6:9], v[208:211], v[22:25], v[124:127]
	v_mfma_f32_16x16x32_bf16 v[10:13], v[200:203], v[38:41], v[120:123]
	v_mfma_f32_16x16x32_bf16 v[14:17], v[208:211], v[38:41], v[116:119]
	v_mfma_f32_16x16x32_bf16 v[42:45], v[204:207], v[212:215], v[18:21]
	v_mfma_f32_16x16x32_bf16 v[18:21], v[208:211], v[62:65], v[100:103]
	v_mfma_f32_16x16x32_bf16 v[2:5], v[204:207], v[34:37], v[2:5]
	v_mfma_f32_16x16x32_bf16 v[6:9], v[168:171], v[34:37], v[6:9]
	v_mfma_f32_16x16x32_bf16 v[10:13], v[204:207], v[50:53], v[10:13]
	v_mfma_f32_16x16x32_bf16 v[14:17], v[168:171], v[50:53], v[14:17]
	v_mfma_f32_16x16x32_bf16 v[46:49], v[168:171], v[212:215], v[18:21]
	s_barrier
	ds_read_b128 v[122:125], v167
	ds_read_b128 v[126:129], v167 offset:1024
	ds_read_b128 v[216:219], v167 offset:2048
	ds_read_b128 v[220:223], v167 offset:3072
	s_waitcnt vmcnt(0)
	s_barrier
	s_waitcnt lgkmcnt(0)
	s_waitcnt lgkmcnt(0)
	v_mfma_f32_16x16x32_bf16 v[18:21], v[122:125], v[22:25], v[96:99]
	v_mfma_f32_16x16x32_bf16 v[22:25], v[216:219], v[22:25], v[92:95]
	v_mfma_f32_16x16x32_bf16 v[18:21], v[126:129], v[34:37], v[18:21]
	v_mfma_f32_16x16x32_bf16 v[22:25], v[220:223], v[34:37], v[22:25]
	v_mfma_f32_16x16x32_bf16 v[34:37], v[122:125], v[38:41], v[88:91]
	v_mfma_f32_16x16x32_bf16 v[38:41], v[216:219], v[38:41], v[84:87]
	v_mfma_f32_16x16x32_bf16 v[34:37], v[126:129], v[50:53], v[34:37]
	v_mfma_f32_16x16x32_bf16 v[38:41], v[220:223], v[50:53], v[38:41]
	v_mfma_f32_16x16x32_bf16 v[50:53], v[122:125], v[54:57], v[80:83]
	v_mfma_f32_16x16x32_bf16 v[54:57], v[216:219], v[54:57], v[76:79]
	v_mfma_f32_16x16x32_bf16 v[50:53], v[126:129], v[58:61], v[50:53]
	v_mfma_f32_16x16x32_bf16 v[54:57], v[220:223], v[58:61], v[54:57]
	v_mfma_f32_16x16x32_bf16 v[58:61], v[122:125], v[62:65], v[72:75]
	v_mfma_f32_16x16x32_bf16 v[62:65], v[216:219], v[62:65], v[68:71]
	v_mfma_f32_16x16x32_bf16 v[58:61], v[126:129], v[212:215], v[58:61]
	v_mfma_f32_16x16x32_bf16 v[62:65], v[220:223], v[212:215], v[62:65]
	s_barrier
	ds_read_b128 v[86:89], v161 offset:49152
	ds_read_b128 v[94:97], v161 offset:50176
	ds_read_b128 v[102:105], v160 offset:49152
	ds_read_b128 v[110:113], v160 offset:50176
	ds_read_b128 v[118:121], v159 offset:49152
	ds_read_b128 v[160:163], v159 offset:50176
	ds_read_b128 v[212:215], v158 offset:49152
	ds_read_b128 v[248:251], v158 offset:50176
	s_barrier
	s_waitcnt lgkmcnt(0)
	s_waitcnt lgkmcnt(0)
	v_mfma_f32_16x16x32_bf16 v[78:81], v[208:211], v[102:105], v[236:239]
	v_mfma_f32_16x16x32_bf16 v[82:85], v[168:171], v[110:113], v[78:81]
	v_mfma_f32_16x16x32_bf16 v[78:81], v[200:203], v[118:121], v[240:243]
	v_mfma_f32_16x16x32_bf16 v[90:93], v[204:207], v[160:163], v[78:81]
	v_mfma_f32_16x16x32_bf16 v[78:81], v[208:211], v[118:121], v[244:247]
	v_mfma_f32_16x16x32_bf16 v[98:101], v[168:171], v[160:163], v[78:81]
	v_mfma_f32_16x16x32_bf16 v[78:81], v[200:203], v[212:215], v[138:141]
	v_mfma_f32_16x16x32_bf16 v[66:69], v[200:203], v[86:89], v[224:227]
	v_mfma_f32_16x16x32_bf16 v[70:73], v[208:211], v[86:89], v[228:231]
	v_mfma_f32_16x16x32_bf16 v[74:77], v[200:203], v[102:105], v[232:235]
	v_mfma_f32_16x16x32_bf16 v[106:109], v[204:207], v[248:251], v[78:81]
	v_mfma_f32_16x16x32_bf16 v[78:81], v[208:211], v[212:215], v[142:145]
	v_mfma_f32_16x16x32_bf16 v[66:69], v[204:207], v[94:97], v[66:69]
	v_mfma_f32_16x16x32_bf16 v[70:73], v[168:171], v[94:97], v[70:73]
	v_mfma_f32_16x16x32_bf16 v[74:77], v[204:207], v[110:113], v[74:77]
	v_mfma_f32_16x16x32_bf16 v[114:117], v[168:171], v[248:251], v[78:81]
	v_mfma_f32_16x16x32_bf16 v[78:81], v[122:125], v[86:89], v[172:175]
	v_mfma_f32_16x16x32_bf16 v[86:89], v[216:219], v[86:89], v[180:183]
	v_mfma_f32_16x16x32_bf16 v[78:81], v[126:129], v[94:97], v[78:81]
	v_mfma_f32_16x16x32_bf16 v[86:89], v[220:223], v[94:97], v[86:89]
	v_mfma_f32_16x16x32_bf16 v[94:97], v[122:125], v[102:105], v[184:187]
	v_mfma_f32_16x16x32_bf16 v[102:105], v[216:219], v[102:105], v[188:191]
	v_mfma_f32_16x16x32_bf16 v[94:97], v[126:129], v[110:113], v[94:97]
	v_mfma_f32_16x16x32_bf16 v[102:105], v[220:223], v[110:113], v[102:105]
	v_mfma_f32_16x16x32_bf16 v[110:113], v[122:125], v[118:121], v[192:195]
	v_mfma_f32_16x16x32_bf16 v[122:125], v[122:125], v[212:215], v[134:137]
	v_mfma_f32_16x16x32_bf16 v[110:113], v[126:129], v[160:163], v[110:113]
	v_mfma_f32_16x16x32_bf16 v[118:121], v[216:219], v[118:121], v[196:199]
	v_mfma_f32_16x16x32_bf16 v[122:125], v[126:129], v[248:251], v[122:125]
	v_mfma_f32_16x16x32_bf16 v[126:129], v[216:219], v[212:215], v[176:179]
	v_mfma_f32_16x16x32_bf16 v[118:121], v[220:223], v[160:163], v[118:121]
	v_mfma_f32_16x16x32_bf16 v[126:129], v[220:223], v[248:251], v[126:129]
	v_and_b32_e32 v0, 0xffffff00, v149
	v_lshlrev_b32_e32 v130, 2, v155
	v_add3_u32 v131, s67, v0, v130
	v_add3_u32 v0, s68, v0, v130
	s_barrier
	ds_read2_b32 v[136:137], v131 offset1:16
	ds_read2_b32 v[138:139], v131 offset0:32 offset1:48
	ds_read2_b32 v[142:143], v0 offset1:16
	ds_read2_b32 v[146:147], v0 offset0:32 offset1:48
	v_cmp_gt_u32_e32 vcc, s60, v149
	s_waitcnt lgkmcnt(0)
	v_mov_b32_e32 v0, v137
	v_mov_b32_e32 v140, v139
	v_mov_b32_e32 v144, v143
	v_mov_b32_e32 v134, v147
	s_and_saveexec_b64 s[6:7], vcc
	s_cbranch_execz .LBB0_2757
	s_barrier
	s_branch .LBB0_2757

.LBB0_2916:
	ds_read_b128 v[180:183], v172
	ds_read_b128 v[184:187], v172 offset:1024
	ds_read_b128 v[188:191], v172 offset:2048
	ds_read_b128 v[192:195], v172 offset:3072
	v_add_u32_e32 v178, 0xc000, v152
	v_lshl_add_u64 v[244:245], s[6:7], 0, v[146:147]
	v_readfirstlane_b32 s4, v178
	v_add_u32_e32 v179, 0xe000, v152
	v_lshl_add_u64 v[224:225], v[244:245], 0, s[12:13]
	s_mov_b32 m0, s4
	v_lshl_add_u64 v[246:247], s[6:7], 0, v[148:149]
	v_readfirstlane_b32 s4, v179
	ds_read_b128 v[174:177], v161
	ds_read_b128 v[196:199], v161 offset:1024
	ds_read_b128 v[200:203], v160
	ds_read_b128 v[204:207], v160 offset:1024
	ds_read_b128 v[208:211], v159
	ds_read_b128 v[212:215], v159 offset:1024
	ds_read_b128 v[216:219], v158
	ds_read_b128 v[220:223], v158 offset:1024
	global_load_lds_dwordx4 v[224:225], off
	v_lshl_add_u64 v[224:225], v[246:247], 0, s[12:13]
	s_mov_b32 m0, s4
	s_nop 0
	global_load_lds_dwordx4 v[224:225], off
	s_waitcnt lgkmcnt(8)
	s_barrier
	s_waitcnt lgkmcnt(0)
	s_waitcnt lgkmcnt(0)
	v_mfma_f32_16x16x32_bf16 v[124:127], v[180:183], v[174:177], v[124:127]
	v_mfma_f32_16x16x32_bf16 v[120:123], v[188:191], v[174:177], v[120:123]
	v_mfma_f32_16x16x32_bf16 v[116:119], v[180:183], v[200:203], v[116:119]
	v_mfma_f32_16x16x32_bf16 v[112:115], v[188:191], v[200:203], v[112:115]
	v_mfma_f32_16x16x32_bf16 v[108:111], v[180:183], v[208:211], v[108:111]
	v_mfma_f32_16x16x32_bf16 v[104:107], v[188:191], v[208:211], v[104:107]
	v_mfma_f32_16x16x32_bf16 v[100:103], v[180:183], v[216:219], v[100:103]
	v_mfma_f32_16x16x32_bf16 v[96:99], v[188:191], v[216:219], v[96:99]
	v_mfma_f32_16x16x32_bf16 v[124:127], v[184:187], v[196:199], v[124:127]
	v_mfma_f32_16x16x32_bf16 v[120:123], v[192:195], v[196:199], v[120:123]
	v_mfma_f32_16x16x32_bf16 v[116:119], v[184:187], v[204:207], v[116:119]
	v_mfma_f32_16x16x32_bf16 v[112:115], v[192:195], v[204:207], v[112:115]
	v_mfma_f32_16x16x32_bf16 v[108:111], v[184:187], v[212:215], v[108:111]
	v_mfma_f32_16x16x32_bf16 v[104:107], v[192:195], v[212:215], v[104:107]
	v_mfma_f32_16x16x32_bf16 v[100:103], v[184:187], v[220:223], v[100:103]
	v_mfma_f32_16x16x32_bf16 v[96:99], v[192:195], v[220:223], v[96:99]
	s_barrier
	v_lshl_add_u64 v[248:249], s[6:7], 0, v[142:143]
	v_readfirstlane_b32 s4, v153
	v_add_u32_e32 v173, 0x2000, v153
	v_lshl_add_u64 v[240:241], v[248:249], 0, s[14:15]
	s_mov_b32 m0, s4
	v_lshl_add_u64 v[250:251], s[6:7], 0, v[144:145]
	v_readfirstlane_b32 s4, v173
	ds_read_b128 v[224:227], v168
	ds_read_b128 v[228:231], v168 offset:1024
	ds_read_b128 v[232:235], v168 offset:2048
	ds_read_b128 v[236:239], v168 offset:3072
	global_load_lds_dwordx4 v[240:241], off
	v_lshl_add_u64 v[240:241], v[250:251], 0, s[14:15]
	s_mov_b32 m0, s4
	s_nop 0
	global_load_lds_dwordx4 v[240:241], off
	s_barrier
	s_waitcnt lgkmcnt(0)
	s_waitcnt lgkmcnt(0)
	v_mfma_f32_16x16x32_bf16 v[92:95], v[224:227], v[174:177], v[92:95]
	v_mfma_f32_16x16x32_bf16 v[88:91], v[232:235], v[174:177], v[88:91]
	v_mfma_f32_16x16x32_bf16 v[84:87], v[224:227], v[200:203], v[84:87]
	v_mfma_f32_16x16x32_bf16 v[80:83], v[232:235], v[200:203], v[80:83]
	v_mfma_f32_16x16x32_bf16 v[76:79], v[224:227], v[208:211], v[76:79]
	v_mfma_f32_16x16x32_bf16 v[72:75], v[232:235], v[208:211], v[72:75]
	v_mfma_f32_16x16x32_bf16 v[68:71], v[224:227], v[216:219], v[68:71]
	v_mfma_f32_16x16x32_bf16 v[64:67], v[232:235], v[216:219], v[64:67]
	v_mfma_f32_16x16x32_bf16 v[92:95], v[228:231], v[196:199], v[92:95]
	v_mfma_f32_16x16x32_bf16 v[88:91], v[236:239], v[196:199], v[88:91]
	v_mfma_f32_16x16x32_bf16 v[84:87], v[228:231], v[204:207], v[84:87]
	v_mfma_f32_16x16x32_bf16 v[80:83], v[236:239], v[204:207], v[80:83]
	v_mfma_f32_16x16x32_bf16 v[76:79], v[228:231], v[212:215], v[76:79]
	v_mfma_f32_16x16x32_bf16 v[72:75], v[236:239], v[212:215], v[72:75]
	v_mfma_f32_16x16x32_bf16 v[68:71], v[228:231], v[220:223], v[68:71]
	v_mfma_f32_16x16x32_bf16 v[64:67], v[236:239], v[220:223], v[64:67]
	v_readfirstlane_b32 s4, v152
	v_lshl_add_u64 v[174:175], v[244:245], 0, s[16:17]
	s_mov_b32 m0, s4
	s_barrier
	ds_read_b128 v[196:199], v161 offset:16384
	ds_read_b128 v[200:203], v161 offset:17408
	ds_read_b128 v[204:207], v160 offset:16384
	ds_read_b128 v[208:211], v160 offset:17408
	ds_read_b128 v[212:215], v159 offset:16384
	ds_read_b128 v[216:219], v159 offset:17408
	ds_read_b128 v[220:223], v158 offset:16384
	ds_read_b128 v[240:243], v158 offset:17408
	global_load_lds_dwordx4 v[174:175], off
	v_add_u32_e32 v174, 0x2000, v152
	v_lshl_add_u64 v[176:177], v[246:247], 0, s[16:17]
	v_readfirstlane_b32 s4, v174
	s_mov_b32 m0, s4
	s_nop 0
	global_load_lds_dwordx4 v[176:177], off
	s_barrier
	s_waitcnt lgkmcnt(0)
	s_waitcnt lgkmcnt(0)
	v_mfma_f32_16x16x32_bf16 v[60:63], v[180:183], v[196:199], v[60:63]
	v_mfma_f32_16x16x32_bf16 v[56:59], v[188:191], v[196:199], v[56:59]
	v_mfma_f32_16x16x32_bf16 v[52:55], v[180:183], v[204:207], v[52:55]
	v_mfma_f32_16x16x32_bf16 v[48:51], v[188:191], v[204:207], v[48:51]
	v_mfma_f32_16x16x32_bf16 v[44:47], v[180:183], v[212:215], v[44:47]
	v_mfma_f32_16x16x32_bf16 v[40:43], v[188:191], v[212:215], v[40:43]
	v_mfma_f32_16x16x32_bf16 v[36:39], v[180:183], v[220:223], v[36:39]
	v_mfma_f32_16x16x32_bf16 v[32:35], v[188:191], v[220:223], v[32:35]
	v_mfma_f32_16x16x32_bf16 v[60:63], v[184:187], v[200:203], v[60:63]
	v_mfma_f32_16x16x32_bf16 v[56:59], v[192:195], v[200:203], v[56:59]
	v_mfma_f32_16x16x32_bf16 v[52:55], v[184:187], v[208:211], v[52:55]
	v_mfma_f32_16x16x32_bf16 v[48:51], v[192:195], v[208:211], v[48:51]
	v_mfma_f32_16x16x32_bf16 v[44:47], v[184:187], v[216:219], v[44:47]
	v_mfma_f32_16x16x32_bf16 v[40:43], v[192:195], v[216:219], v[40:43]
	v_mfma_f32_16x16x32_bf16 v[36:39], v[184:187], v[240:243], v[36:39]
	v_mfma_f32_16x16x32_bf16 v[32:35], v[192:195], v[240:243], v[32:35]
	s_barrier
	v_readfirstlane_b32 s4, v151
	v_add_u32_e32 v175, 0x2000, v151
	v_lshl_add_u64 v[176:177], v[248:249], 0, s[18:19]
	s_mov_b32 m0, s4
	v_readfirstlane_b32 s4, v175
	global_load_lds_dwordx4 v[176:177], off
	v_lshl_add_u64 v[176:177], v[250:251], 0, s[18:19]
	s_mov_b32 m0, s4
	s_nop 0
	global_load_lds_dwordx4 v[176:177], off
	s_waitcnt vmcnt(6)
	s_barrier
	v_mfma_f32_16x16x32_bf16 v[28:31], v[224:227], v[196:199], v[28:31]
	v_mfma_f32_16x16x32_bf16 v[24:27], v[232:235], v[196:199], v[24:27]
	v_mfma_f32_16x16x32_bf16 v[20:23], v[224:227], v[204:207], v[20:23]
	v_mfma_f32_16x16x32_bf16 v[16:19], v[232:235], v[204:207], v[16:19]
	v_mfma_f32_16x16x32_bf16 v[12:15], v[224:227], v[212:215], v[12:15]
	v_mfma_f32_16x16x32_bf16 v[8:11], v[232:235], v[212:215], v[8:11]
	v_mfma_f32_16x16x32_bf16 v[4:7], v[224:227], v[220:223], v[4:7]
	v_mfma_f32_16x16x32_bf16 v[0:3], v[232:235], v[220:223], v[0:3]
	v_mfma_f32_16x16x32_bf16 v[28:31], v[228:231], v[200:203], v[28:31]
	v_mfma_f32_16x16x32_bf16 v[24:27], v[236:239], v[200:203], v[24:27]
	v_mfma_f32_16x16x32_bf16 v[20:23], v[228:231], v[208:211], v[20:23]
	v_mfma_f32_16x16x32_bf16 v[16:19], v[236:239], v[208:211], v[16:19]
	v_mfma_f32_16x16x32_bf16 v[12:15], v[228:231], v[216:219], v[12:15]
	v_mfma_f32_16x16x32_bf16 v[8:11], v[236:239], v[216:219], v[8:11]
	v_mfma_f32_16x16x32_bf16 v[4:7], v[228:231], v[240:243], v[4:7]
	v_mfma_f32_16x16x32_bf16 v[0:3], v[236:239], v[240:243], v[0:3]
	s_barrier
	ds_read_b128 v[180:183], v163
	ds_read_b128 v[184:187], v163 offset:1024
	ds_read_b128 v[188:191], v163 offset:2048
	ds_read_b128 v[192:195], v163 offset:3072
	v_add_u32_e32 v176, 0x4000, v152
	v_add_u32_e32 v177, 0x6000, v152
	v_readfirstlane_b32 s4, v176
	v_lshl_add_u64 v[228:229], v[244:245], 0, s[20:21]
	s_mov_b32 m0, s4
	v_readfirstlane_b32 s4, v177
	ds_read_b128 v[196:199], v161 offset:32768
	ds_read_b128 v[200:203], v161 offset:33792
	ds_read_b128 v[204:207], v160 offset:32768
	ds_read_b128 v[208:211], v160 offset:33792
	ds_read_b128 v[212:215], v159 offset:32768
	ds_read_b128 v[216:219], v159 offset:33792
	ds_read_b128 v[220:223], v158 offset:32768
	ds_read_b128 v[224:227], v158 offset:33792
	global_load_lds_dwordx4 v[228:229], off
	v_lshl_add_u64 v[228:229], v[246:247], 0, s[20:21]
	s_mov_b32 m0, s4
	s_nop 0
	global_load_lds_dwordx4 v[228:229], off
	s_waitcnt lgkmcnt(8)
	s_barrier
	s_waitcnt lgkmcnt(0)
	s_waitcnt lgkmcnt(0)
	v_mfma_f32_16x16x32_bf16 v[124:127], v[180:183], v[196:199], v[124:127]
	v_mfma_f32_16x16x32_bf16 v[120:123], v[188:191], v[196:199], v[120:123]
	v_mfma_f32_16x16x32_bf16 v[116:119], v[180:183], v[204:207], v[116:119]
	v_mfma_f32_16x16x32_bf16 v[112:115], v[188:191], v[204:207], v[112:115]
	v_mfma_f32_16x16x32_bf16 v[108:111], v[180:183], v[212:215], v[108:111]
	v_mfma_f32_16x16x32_bf16 v[104:107], v[188:191], v[212:215], v[104:107]
	v_mfma_f32_16x16x32_bf16 v[100:103], v[180:183], v[220:223], v[100:103]
	v_mfma_f32_16x16x32_bf16 v[96:99], v[188:191], v[220:223], v[96:99]
	v_mfma_f32_16x16x32_bf16 v[124:127], v[184:187], v[200:203], v[124:127]
	v_mfma_f32_16x16x32_bf16 v[120:123], v[192:195], v[200:203], v[120:123]
	v_mfma_f32_16x16x32_bf16 v[116:119], v[184:187], v[208:211], v[116:119]
	v_mfma_f32_16x16x32_bf16 v[112:115], v[192:195], v[208:211], v[112:115]
	v_mfma_f32_16x16x32_bf16 v[108:111], v[184:187], v[216:219], v[108:111]
	v_mfma_f32_16x16x32_bf16 v[104:107], v[192:195], v[216:219], v[104:107]
	v_mfma_f32_16x16x32_bf16 v[100:103], v[184:187], v[224:227], v[100:103]
	v_mfma_f32_16x16x32_bf16 v[96:99], v[192:195], v[224:227], v[96:99]
	s_barrier
	v_readfirstlane_b32 s4, v167
	v_add_u32_e32 v254, 0x2000, v167
	v_lshl_add_u64 v[252:253], v[248:249], 0, s[24:25]
	s_mov_b32 m0, s4
	v_readfirstlane_b32 s4, v254
	ds_read_b128 v[228:231], v162
	ds_read_b128 v[232:235], v162 offset:1024
	ds_read_b128 v[236:239], v162 offset:2048
	ds_read_b128 v[240:243], v162 offset:3072
	global_load_lds_dwordx4 v[252:253], off
	v_lshl_add_u64 v[252:253], v[250:251], 0, s[24:25]
	s_mov_b32 m0, s4
	s_nop 0
	global_load_lds_dwordx4 v[252:253], off
	s_barrier
	s_waitcnt lgkmcnt(0)
	s_waitcnt lgkmcnt(0)
	v_mfma_f32_16x16x32_bf16 v[92:95], v[228:231], v[196:199], v[92:95]
	v_mfma_f32_16x16x32_bf16 v[88:91], v[236:239], v[196:199], v[88:91]
	v_mfma_f32_16x16x32_bf16 v[84:87], v[228:231], v[204:207], v[84:87]
	v_mfma_f32_16x16x32_bf16 v[80:83], v[236:239], v[204:207], v[80:83]
	v_mfma_f32_16x16x32_bf16 v[76:79], v[228:231], v[212:215], v[76:79]
	v_mfma_f32_16x16x32_bf16 v[72:75], v[236:239], v[212:215], v[72:75]
	v_mfma_f32_16x16x32_bf16 v[68:71], v[228:231], v[220:223], v[68:71]
	v_mfma_f32_16x16x32_bf16 v[64:67], v[236:239], v[220:223], v[64:67]
	v_mfma_f32_16x16x32_bf16 v[92:95], v[232:235], v[200:203], v[92:95]
	v_mfma_f32_16x16x32_bf16 v[88:91], v[240:243], v[200:203], v[88:91]
	v_mfma_f32_16x16x32_bf16 v[84:87], v[232:235], v[208:211], v[84:87]
	v_mfma_f32_16x16x32_bf16 v[80:83], v[240:243], v[208:211], v[80:83]
	v_mfma_f32_16x16x32_bf16 v[76:79], v[232:235], v[216:219], v[76:79]
	v_mfma_f32_16x16x32_bf16 v[72:75], v[240:243], v[216:219], v[72:75]
	v_mfma_f32_16x16x32_bf16 v[68:71], v[232:235], v[224:227], v[68:71]
	v_mfma_f32_16x16x32_bf16 v[64:67], v[240:243], v[224:227], v[64:67]
	v_readfirstlane_b32 s4, v169
	v_lshl_add_u64 v[244:245], v[244:245], 0, s[26:27]
	s_mov_b32 m0, s4
	v_readfirstlane_b32 s4, v170
	s_barrier
	ds_read_b128 v[196:199], v161 offset:49152
	ds_read_b128 v[200:203], v161 offset:50176
	ds_read_b128 v[204:207], v160 offset:49152
	ds_read_b128 v[208:211], v160 offset:50176
	ds_read_b128 v[212:215], v159 offset:49152
	ds_read_b128 v[216:219], v159 offset:50176
	ds_read_b128 v[220:223], v158 offset:49152
	ds_read_b128 v[224:227], v158 offset:50176
	global_load_lds_dwordx4 v[244:245], off
	v_lshl_add_u64 v[244:245], v[246:247], 0, s[26:27]
	s_mov_b32 m0, s4
	s_nop 0
	global_load_lds_dwordx4 v[244:245], off
	s_barrier
	s_waitcnt lgkmcnt(0)
	s_waitcnt lgkmcnt(0)
	v_mfma_f32_16x16x32_bf16 v[60:63], v[180:183], v[196:199], v[60:63]
	v_mfma_f32_16x16x32_bf16 v[56:59], v[188:191], v[196:199], v[56:59]
	v_mfma_f32_16x16x32_bf16 v[52:55], v[180:183], v[204:207], v[52:55]
	v_mfma_f32_16x16x32_bf16 v[48:51], v[188:191], v[204:207], v[48:51]
	v_mfma_f32_16x16x32_bf16 v[44:47], v[180:183], v[212:215], v[44:47]
	v_mfma_f32_16x16x32_bf16 v[40:43], v[188:191], v[212:215], v[40:43]
	v_mfma_f32_16x16x32_bf16 v[36:39], v[180:183], v[220:223], v[36:39]
	v_mfma_f32_16x16x32_bf16 v[32:35], v[188:191], v[220:223], v[32:35]
	v_mfma_f32_16x16x32_bf16 v[60:63], v[184:187], v[200:203], v[60:63]
	v_mfma_f32_16x16x32_bf16 v[56:59], v[192:195], v[200:203], v[56:59]
	v_mfma_f32_16x16x32_bf16 v[52:55], v[184:187], v[208:211], v[52:55]
	v_mfma_f32_16x16x32_bf16 v[48:51], v[192:195], v[208:211], v[48:51]
	v_mfma_f32_16x16x32_bf16 v[44:47], v[184:187], v[216:219], v[44:47]
	v_mfma_f32_16x16x32_bf16 v[40:43], v[192:195], v[216:219], v[40:43]
	v_mfma_f32_16x16x32_bf16 v[36:39], v[184:187], v[224:227], v[36:39]
	v_mfma_f32_16x16x32_bf16 v[32:35], v[192:195], v[224:227], v[32:35]
	s_barrier
	v_readfirstlane_b32 s4, v171
	v_add_u32_e32 v182, 0x2000, v171
	v_lshl_add_u64 v[180:181], v[248:249], 0, s[28:29]
	s_mov_b32 m0, s4
	v_readfirstlane_b32 s4, v182
	global_load_lds_dwordx4 v[180:181], off
	v_lshl_add_u64 v[180:181], v[250:251], 0, s[28:29]
	s_mov_b32 m0, s4
	s_nop 0
	global_load_lds_dwordx4 v[180:181], off
	s_waitcnt vmcnt(6)
	s_barrier
	v_mfma_f32_16x16x32_bf16 v[28:31], v[228:231], v[196:199], v[28:31]
	v_mfma_f32_16x16x32_bf16 v[24:27], v[236:239], v[196:199], v[24:27]
	v_mfma_f32_16x16x32_bf16 v[20:23], v[228:231], v[204:207], v[20:23]
	v_mfma_f32_16x16x32_bf16 v[16:19], v[236:239], v[204:207], v[16:19]
	v_mfma_f32_16x16x32_bf16 v[12:15], v[228:231], v[212:215], v[12:15]
	v_mfma_f32_16x16x32_bf16 v[8:11], v[236:239], v[212:215], v[8:11]
	v_mfma_f32_16x16x32_bf16 v[4:7], v[228:231], v[220:223], v[4:7]
	v_mfma_f32_16x16x32_bf16 v[0:3], v[236:239], v[220:223], v[0:3]
	v_mfma_f32_16x16x32_bf16 v[28:31], v[232:235], v[200:203], v[28:31]
	v_mfma_f32_16x16x32_bf16 v[24:27], v[240:243], v[200:203], v[24:27]
	v_mfma_f32_16x16x32_bf16 v[20:23], v[232:235], v[208:211], v[20:23]
	v_mfma_f32_16x16x32_bf16 v[16:19], v[240:243], v[208:211], v[16:19]
	v_mfma_f32_16x16x32_bf16 v[12:15], v[232:235], v[216:219], v[12:15]
	v_mfma_f32_16x16x32_bf16 v[8:11], v[240:243], v[216:219], v[8:11]
	v_mfma_f32_16x16x32_bf16 v[4:7], v[232:235], v[224:227], v[4:7]
	v_mfma_f32_16x16x32_bf16 v[0:3], v[240:243], v[224:227], v[0:3]
	s_add_i32 s2, s2, 2
	v_lshl_add_u64 v[142:143], v[142:143], 0, s[30:31]
	v_lshl_add_u64 v[144:145], v[144:145], 0, s[30:31]
	v_lshl_add_u64 v[146:147], v[146:147], 0, s[30:31]
	s_cmp_lt_u32 s2, 12
	v_lshl_add_u64 v[148:149], v[148:149], 0, s[30:31]
	s_barrier
	s_cbranch_scc1 .LBB0_2916
	s_or_b32 s4, s36, 0x80
	s_ashr_i32 s5, s4, 31
	s_lshl_b64 s[4:5], s[4:5], 11
	s_add_u32 s4, s1, s4
	s_addc_u32 s5, s23, s5
	v_lshl_add_u64 v[170:171], s[4:5], 0, v[130:131]
	v_lshl_add_u64 v[138:139], v[138:139], 1, v[170:171]
	v_readfirstlane_b32 s2, v178
	v_lshl_add_u64 v[138:139], v[138:139], 0, s[34:35]
	s_mov_b32 m0, s2
	ds_read_b128 v[142:145], v172
	ds_read_b128 v[146:149], v172 offset:1024
	ds_read_b128 v[180:183], v172 offset:2048
	ds_read_b128 v[184:187], v172 offset:3072
	ds_read_b128 v[188:191], v161
	ds_read_b128 v[192:195], v161 offset:1024
	ds_read_b128 v[196:199], v160
	ds_read_b128 v[200:203], v160 offset:1024
	ds_read_b128 v[204:207], v159
	ds_read_b128 v[208:211], v159 offset:1024
	ds_read_b128 v[212:215], v158
	ds_read_b128 v[216:219], v158 offset:1024
	global_load_lds_dwordx4 v[138:139], off
	v_lshl_add_u64 v[138:139], s[4:5], 0, v[134:135]
	v_lshl_add_u64 v[138:139], v[140:141], 1, v[138:139]
	v_readfirstlane_b32 s2, v179
	v_lshl_add_u64 v[138:139], v[138:139], 0, s[34:35]
	s_mov_b32 m0, s2
	v_readlane_b32 s2, v255, 11
	global_load_lds_dwordx4 v[138:139], off
	s_add_i32 s60, s60, s2
	s_barrier
	s_waitcnt lgkmcnt(0)
	s_cmpk_gt_i32 s60, 0x7f
	s_cselect_b64 s[38:39], -1, 0
	s_waitcnt lgkmcnt(0)
	v_mfma_f32_16x16x32_bf16 v[124:127], v[142:145], v[188:191], v[124:127]
	v_mfma_f32_16x16x32_bf16 v[120:123], v[180:183], v[188:191], v[120:123]
	v_mfma_f32_16x16x32_bf16 v[116:119], v[142:145], v[196:199], v[116:119]
	v_mfma_f32_16x16x32_bf16 v[112:115], v[180:183], v[196:199], v[112:115]
	v_mfma_f32_16x16x32_bf16 v[108:111], v[142:145], v[204:207], v[108:111]
	v_mfma_f32_16x16x32_bf16 v[104:107], v[180:183], v[204:207], v[104:107]
	v_mfma_f32_16x16x32_bf16 v[100:103], v[142:145], v[212:215], v[100:103]
	v_mfma_f32_16x16x32_bf16 v[96:99], v[180:183], v[212:215], v[96:99]
	v_mfma_f32_16x16x32_bf16 v[124:127], v[146:149], v[192:195], v[124:127]
	v_mfma_f32_16x16x32_bf16 v[120:123], v[184:187], v[192:195], v[120:123]
	v_mfma_f32_16x16x32_bf16 v[116:119], v[146:149], v[200:203], v[116:119]
	v_mfma_f32_16x16x32_bf16 v[112:115], v[184:187], v[200:203], v[112:115]
	v_mfma_f32_16x16x32_bf16 v[108:111], v[146:149], v[208:211], v[108:111]
	v_mfma_f32_16x16x32_bf16 v[104:107], v[184:187], v[208:211], v[104:107]
	v_mfma_f32_16x16x32_bf16 v[100:103], v[146:149], v[216:219], v[100:103]
	v_mfma_f32_16x16x32_bf16 v[96:99], v[184:187], v[216:219], v[96:99]
	s_barrier
	ds_read_b128 v[138:141], v168
	ds_read_b128 v[220:223], v168 offset:1024
	ds_read_b128 v[224:227], v168 offset:2048
	ds_read_b128 v[168:171], v168 offset:3072
	s_barrier
	s_waitcnt lgkmcnt(0)
	s_waitcnt lgkmcnt(0)
	v_mfma_f32_16x16x32_bf16 v[92:95], v[138:141], v[188:191], v[92:95]
	v_mfma_f32_16x16x32_bf16 v[88:91], v[224:227], v[188:191], v[88:91]
	v_mfma_f32_16x16x32_bf16 v[84:87], v[138:141], v[196:199], v[84:87]
	v_mfma_f32_16x16x32_bf16 v[80:83], v[224:227], v[196:199], v[80:83]
	v_mfma_f32_16x16x32_bf16 v[76:79], v[138:141], v[204:207], v[76:79]
	v_mfma_f32_16x16x32_bf16 v[72:75], v[224:227], v[204:207], v[72:75]
	v_mfma_f32_16x16x32_bf16 v[68:71], v[138:141], v[212:215], v[68:71]
	v_mfma_f32_16x16x32_bf16 v[64:67], v[224:227], v[212:215], v[64:67]
	v_mfma_f32_16x16x32_bf16 v[92:95], v[220:223], v[192:195], v[92:95]
	v_mfma_f32_16x16x32_bf16 v[88:91], v[168:171], v[192:195], v[88:91]
	v_mfma_f32_16x16x32_bf16 v[84:87], v[220:223], v[200:203], v[84:87]
	v_mfma_f32_16x16x32_bf16 v[80:83], v[168:171], v[200:203], v[80:83]
	v_mfma_f32_16x16x32_bf16 v[76:79], v[220:223], v[208:211], v[76:79]
	v_mfma_f32_16x16x32_bf16 v[72:75], v[168:171], v[208:211], v[72:75]
	v_mfma_f32_16x16x32_bf16 v[68:71], v[220:223], v[216:219], v[68:71]
	v_mfma_f32_16x16x32_bf16 v[64:67], v[168:171], v[216:219], v[64:67]
	s_barrier
	ds_read_b128 v[188:191], v161 offset:16384
	ds_read_b128 v[192:195], v161 offset:17408
	ds_read_b128 v[196:199], v160 offset:16384
	ds_read_b128 v[200:203], v160 offset:17408
	ds_read_b128 v[204:207], v159 offset:16384
	ds_read_b128 v[208:211], v159 offset:17408
	ds_read_b128 v[212:215], v158 offset:16384
	ds_read_b128 v[216:219], v158 offset:17408
	s_waitcnt vmcnt(4)
	s_barrier
	s_waitcnt lgkmcnt(0)
	s_waitcnt lgkmcnt(0)
	v_mfma_f32_16x16x32_bf16 v[60:63], v[142:145], v[188:191], v[60:63]
	v_mfma_f32_16x16x32_bf16 v[56:59], v[180:183], v[188:191], v[56:59]
	v_mfma_f32_16x16x32_bf16 v[52:55], v[142:145], v[196:199], v[52:55]
	v_mfma_f32_16x16x32_bf16 v[48:51], v[180:183], v[196:199], v[48:51]
	v_mfma_f32_16x16x32_bf16 v[44:47], v[142:145], v[204:207], v[44:47]
	v_mfma_f32_16x16x32_bf16 v[40:43], v[180:183], v[204:207], v[40:43]
	v_mfma_f32_16x16x32_bf16 v[36:39], v[142:145], v[212:215], v[36:39]
	v_mfma_f32_16x16x32_bf16 v[32:35], v[180:183], v[212:215], v[32:35]
	v_mfma_f32_16x16x32_bf16 v[60:63], v[146:149], v[192:195], v[60:63]
	v_mfma_f32_16x16x32_bf16 v[56:59], v[184:187], v[192:195], v[56:59]
	v_mfma_f32_16x16x32_bf16 v[52:55], v[146:149], v[200:203], v[52:55]
	v_mfma_f32_16x16x32_bf16 v[48:51], v[184:187], v[200:203], v[48:51]
	v_mfma_f32_16x16x32_bf16 v[44:47], v[146:149], v[208:211], v[44:47]
	v_mfma_f32_16x16x32_bf16 v[40:43], v[184:187], v[208:211], v[40:43]
	v_mfma_f32_16x16x32_bf16 v[36:39], v[146:149], v[216:219], v[36:39]
	v_mfma_f32_16x16x32_bf16 v[32:35], v[184:187], v[216:219], v[32:35]
	v_mfma_f32_16x16x32_bf16 v[28:31], v[138:141], v[188:191], v[28:31]
	v_mfma_f32_16x16x32_bf16 v[24:27], v[224:227], v[188:191], v[24:27]
	v_mfma_f32_16x16x32_bf16 v[20:23], v[138:141], v[196:199], v[20:23]
	v_mfma_f32_16x16x32_bf16 v[16:19], v[224:227], v[196:199], v[16:19]
	v_mfma_f32_16x16x32_bf16 v[12:15], v[138:141], v[204:207], v[12:15]
	v_mfma_f32_16x16x32_bf16 v[8:11], v[224:227], v[204:207], v[8:11]
	v_mfma_f32_16x16x32_bf16 v[4:7], v[138:141], v[212:215], v[4:7]
	v_mfma_f32_16x16x32_bf16 v[0:3], v[224:227], v[212:215], v[0:3]
	v_mfma_f32_16x16x32_bf16 v[28:31], v[220:223], v[192:195], v[28:31]
	v_mfma_f32_16x16x32_bf16 v[24:27], v[168:171], v[192:195], v[24:27]
	v_mfma_f32_16x16x32_bf16 v[20:23], v[220:223], v[200:203], v[20:23]
	v_mfma_f32_16x16x32_bf16 v[16:19], v[168:171], v[200:203], v[16:19]
	v_mfma_f32_16x16x32_bf16 v[12:15], v[220:223], v[208:211], v[12:15]
	v_mfma_f32_16x16x32_bf16 v[8:11], v[168:171], v[208:211], v[8:11]
	v_mfma_f32_16x16x32_bf16 v[4:7], v[220:223], v[216:219], v[4:7]
	v_mfma_f32_16x16x32_bf16 v[0:3], v[168:171], v[216:219], v[0:3]
	s_barrier
	ds_read_b128 v[138:141], v163
	ds_read_b128 v[142:145], v163 offset:1024
	ds_read_b128 v[146:149], v163 offset:2048
	ds_read_b128 v[168:171], v163 offset:3072
	ds_read_b128 v[178:181], v161 offset:32768
	ds_read_b128 v[182:185], v161 offset:33792
	ds_read_b128 v[186:189], v160 offset:32768
	ds_read_b128 v[190:193], v160 offset:33792
	ds_read_b128 v[194:197], v159 offset:32768
	ds_read_b128 v[198:201], v159 offset:33792
	ds_read_b128 v[202:205], v158 offset:32768
	ds_read_b128 v[206:209], v158 offset:33792
	s_waitcnt vmcnt(2)
	s_barrier
	s_waitcnt lgkmcnt(0)
	s_waitcnt lgkmcnt(0)
	v_mfma_f32_16x16x32_bf16 v[124:127], v[138:141], v[178:181], v[124:127]
	v_mfma_f32_16x16x32_bf16 v[120:123], v[146:149], v[178:181], v[120:123]
	v_mfma_f32_16x16x32_bf16 v[116:119], v[138:141], v[186:189], v[116:119]
	v_mfma_f32_16x16x32_bf16 v[112:115], v[146:149], v[186:189], v[112:115]
	v_mfma_f32_16x16x32_bf16 v[108:111], v[138:141], v[194:197], v[108:111]
	v_mfma_f32_16x16x32_bf16 v[104:107], v[146:149], v[194:197], v[104:107]
	v_mfma_f32_16x16x32_bf16 v[100:103], v[138:141], v[202:205], v[100:103]
	v_mfma_f32_16x16x32_bf16 v[96:99], v[146:149], v[202:205], v[96:99]
	v_mfma_f32_16x16x32_bf16 v[124:127], v[142:145], v[182:185], v[124:127]
	v_mfma_f32_16x16x32_bf16 v[120:123], v[168:171], v[182:185], v[120:123]
	v_mfma_f32_16x16x32_bf16 v[116:119], v[142:145], v[190:193], v[116:119]
	v_mfma_f32_16x16x32_bf16 v[112:115], v[168:171], v[190:193], v[112:115]
	v_mfma_f32_16x16x32_bf16 v[108:111], v[142:145], v[198:201], v[108:111]
	v_mfma_f32_16x16x32_bf16 v[104:107], v[168:171], v[198:201], v[104:107]
	v_mfma_f32_16x16x32_bf16 v[100:103], v[142:145], v[206:209], v[100:103]
	v_mfma_f32_16x16x32_bf16 v[96:99], v[168:171], v[206:209], v[96:99]
	s_barrier
	ds_read_b128 v[210:213], v162
	ds_read_b128 v[214:217], v162 offset:1024
	ds_read_b128 v[218:221], v162 offset:2048
	ds_read_b128 v[222:225], v162 offset:3072
	s_waitcnt vmcnt(0)
	s_barrier
	s_waitcnt lgkmcnt(0)
	s_waitcnt lgkmcnt(0)
	v_mfma_f32_16x16x32_bf16 v[92:95], v[210:213], v[178:181], v[92:95]
	v_mfma_f32_16x16x32_bf16 v[88:91], v[218:221], v[178:181], v[88:91]
	v_mfma_f32_16x16x32_bf16 v[84:87], v[210:213], v[186:189], v[84:87]
	v_mfma_f32_16x16x32_bf16 v[80:83], v[218:221], v[186:189], v[80:83]
	v_mfma_f32_16x16x32_bf16 v[76:79], v[210:213], v[194:197], v[76:79]
	v_mfma_f32_16x16x32_bf16 v[72:75], v[218:221], v[194:197], v[72:75]
	v_mfma_f32_16x16x32_bf16 v[68:71], v[210:213], v[202:205], v[68:71]
	v_mfma_f32_16x16x32_bf16 v[64:67], v[218:221], v[202:205], v[64:67]
	v_mfma_f32_16x16x32_bf16 v[92:95], v[214:217], v[182:185], v[92:95]
	v_mfma_f32_16x16x32_bf16 v[88:91], v[222:225], v[182:185], v[88:91]
	v_mfma_f32_16x16x32_bf16 v[84:87], v[214:217], v[190:193], v[84:87]
	v_mfma_f32_16x16x32_bf16 v[80:83], v[222:225], v[190:193], v[80:83]
	v_mfma_f32_16x16x32_bf16 v[76:79], v[214:217], v[198:201], v[76:79]
	v_mfma_f32_16x16x32_bf16 v[72:75], v[222:225], v[198:201], v[72:75]
	v_mfma_f32_16x16x32_bf16 v[68:71], v[214:217], v[206:209], v[68:71]
	v_mfma_f32_16x16x32_bf16 v[64:67], v[222:225], v[206:209], v[64:67]
	s_barrier
	ds_read_b128 v[178:181], v161 offset:49152
	ds_read_b128 v[182:185], v161 offset:50176
	ds_read_b128 v[186:189], v160 offset:49152
	ds_read_b128 v[160:163], v160 offset:50176
	ds_read_b128 v[190:193], v159 offset:49152
	ds_read_b128 v[194:197], v159 offset:50176
	ds_read_b128 v[198:201], v158 offset:49152
	ds_read_b128 v[202:205], v158 offset:50176
	s_barrier
	s_waitcnt lgkmcnt(0)
	s_waitcnt lgkmcnt(0)
	v_mfma_f32_16x16x32_bf16 v[60:63], v[138:141], v[178:181], v[60:63]
	v_mfma_f32_16x16x32_bf16 v[56:59], v[146:149], v[178:181], v[56:59]
	v_mfma_f32_16x16x32_bf16 v[52:55], v[138:141], v[186:189], v[52:55]
	v_mfma_f32_16x16x32_bf16 v[48:51], v[146:149], v[186:189], v[48:51]
	v_mfma_f32_16x16x32_bf16 v[44:47], v[138:141], v[190:193], v[44:47]
	v_mfma_f32_16x16x32_bf16 v[40:43], v[146:149], v[190:193], v[40:43]
	v_mfma_f32_16x16x32_bf16 v[36:39], v[138:141], v[198:201], v[36:39]
	v_mfma_f32_16x16x32_bf16 v[32:35], v[146:149], v[198:201], v[32:35]
	v_mfma_f32_16x16x32_bf16 v[60:63], v[142:145], v[182:185], v[60:63]
	v_mfma_f32_16x16x32_bf16 v[56:59], v[168:171], v[182:185], v[56:59]
	v_mfma_f32_16x16x32_bf16 v[52:55], v[142:145], v[160:163], v[52:55]
	v_mfma_f32_16x16x32_bf16 v[48:51], v[168:171], v[160:163], v[48:51]
	v_mfma_f32_16x16x32_bf16 v[44:47], v[142:145], v[194:197], v[44:47]
	v_mfma_f32_16x16x32_bf16 v[40:43], v[168:171], v[194:197], v[40:43]
	v_mfma_f32_16x16x32_bf16 v[36:39], v[142:145], v[202:205], v[36:39]
	v_mfma_f32_16x16x32_bf16 v[32:35], v[168:171], v[202:205], v[32:35]
	v_mfma_f32_16x16x32_bf16 v[28:31], v[210:213], v[178:181], v[28:31]
	v_mfma_f32_16x16x32_bf16 v[24:27], v[218:221], v[178:181], v[24:27]
	v_mfma_f32_16x16x32_bf16 v[20:23], v[210:213], v[186:189], v[20:23]
	v_mfma_f32_16x16x32_bf16 v[16:19], v[218:221], v[186:189], v[16:19]
	v_mfma_f32_16x16x32_bf16 v[12:15], v[210:213], v[190:193], v[12:15]
	v_mfma_f32_16x16x32_bf16 v[8:11], v[218:221], v[190:193], v[8:11]
	v_mfma_f32_16x16x32_bf16 v[4:7], v[210:213], v[198:201], v[4:7]
	v_mfma_f32_16x16x32_bf16 v[0:3], v[218:221], v[198:201], v[0:3]
	v_mfma_f32_16x16x32_bf16 v[28:31], v[214:217], v[182:185], v[28:31]
	v_mfma_f32_16x16x32_bf16 v[24:27], v[222:225], v[182:185], v[24:27]
	v_mfma_f32_16x16x32_bf16 v[20:23], v[214:217], v[160:163], v[20:23]
	v_mfma_f32_16x16x32_bf16 v[16:19], v[222:225], v[160:163], v[16:19]
	v_mfma_f32_16x16x32_bf16 v[12:15], v[214:217], v[194:197], v[12:15]
	v_mfma_f32_16x16x32_bf16 v[8:11], v[222:225], v[194:197], v[8:11]
	v_mfma_f32_16x16x32_bf16 v[4:7], v[214:217], v[202:205], v[4:7]
	v_mfma_f32_16x16x32_bf16 v[0:3], v[222:225], v[202:205], v[0:3]
	s_and_b64 vcc, exec, s[38:39]
	s_barrier
	s_cbranch_vccnz .LBB0_2919
	s_lshr_b32 s2, s60, 2
	s_and_b32 s4, s60, 3
	s_add_i32 s2, s2, s56
	s_or_b32 s5, s4, s53
	s_lshl_b32 s4, s2, 8
	s_lshl_b32 s2, s5, 19
	s_add_u32 s42, s40, s2
	s_addc_u32 s43, s46, 0
	v_lshl_add_u64 v[138:139], s[42:43], 0, v[130:131]
	v_readfirstlane_b32 s2, v153
	s_ashr_i32 s5, s4, 31
	v_lshl_add_u64 v[138:139], v[138:139], 0, v[132:133]
	s_mov_b32 m0, s2
	s_lshl_b64 s[44:45], s[4:5], 11
	global_load_lds_dwordx4 v[138:139], off
	v_lshl_add_u64 v[138:139], s[42:43], 0, v[134:135]
	v_readfirstlane_b32 s2, v173
	s_add_u32 s44, s1, s44
	v_lshl_add_u64 v[138:139], v[138:139], 0, v[136:137]
	s_mov_b32 m0, s2
	s_addc_u32 s45, s23, s45
	global_load_lds_dwordx4 v[138:139], off
	v_lshl_add_u64 v[138:139], s[44:45], 0, v[130:131]
	v_readfirstlane_b32 s2, v152
	v_lshl_add_u64 v[138:139], v[138:139], 0, v[132:133]
	s_mov_b32 m0, s2
	s_add_u32 s42, s42, 0x40000
	global_load_lds_dwordx4 v[138:139], off
	v_lshl_add_u64 v[138:139], s[44:45], 0, v[134:135]
	v_readfirstlane_b32 s2, v174
	s_addc_u32 s43, s43, 0
	s_bitset1_b32 s4, 7
	v_lshl_add_u64 v[138:139], v[138:139], 0, v[136:137]
	s_mov_b32 m0, s2
	s_ashr_i32 s5, s4, 31
	global_load_lds_dwordx4 v[138:139], off
	v_lshl_add_u64 v[138:139], s[42:43], 0, v[130:131]
	v_readfirstlane_b32 s2, v151
	s_lshl_b64 s[4:5], s[4:5], 11
	v_lshl_add_u64 v[138:139], v[138:139], 0, v[132:133]
	s_mov_b32 m0, s2
	s_add_u32 s4, s1, s4
	global_load_lds_dwordx4 v[138:139], off
	v_lshl_add_u64 v[138:139], s[42:43], 0, v[134:135]
	v_readfirstlane_b32 s2, v175
	s_addc_u32 s5, s23, s5
	v_lshl_add_u64 v[138:139], v[138:139], 0, v[136:137]
	s_mov_b32 m0, s2
	v_lshl_add_u64 v[130:131], s[4:5], 0, v[130:131]
	v_readfirstlane_b32 s2, v176
	global_load_lds_dwordx4 v[138:139], off
	v_lshl_add_u64 v[130:131], v[130:131], 0, v[132:133]
	s_mov_b32 m0, s2
	v_readfirstlane_b32 s2, v177
	global_load_lds_dwordx4 v[130:131], off
	v_lshl_add_u64 v[130:131], s[4:5], 0, v[134:135]
	v_lshl_add_u64 v[130:131], v[130:131], 0, v[136:137]
	s_mov_b32 m0, s2
	s_nop 0
	global_load_lds_dwordx4 v[130:131], off

.LBB0_2971:
	ds_read_b128 v[176:179], v173
	ds_read_b128 v[180:183], v173 offset:1024
	ds_read_b128 v[184:187], v173 offset:2048
	ds_read_b128 v[188:191], v173 offset:3072
	v_add_u32_e32 v174, 0xc000, v157
	v_lshl_add_u64 v[240:241], s[2:3], 0, v[142:143]
	v_readfirstlane_b32 s31, v174
	v_add_u32_e32 v175, 0xe000, v157
	v_lshl_add_u64 v[224:225], v[240:241], 0, s[10:11]
	s_mov_b32 m0, s31
	v_lshl_add_u64 v[242:243], s[2:3], 0, v[144:145]
	v_readfirstlane_b32 s31, v175
	ds_read_b128 v[192:195], v155
	ds_read_b128 v[196:199], v155 offset:1024
	ds_read_b128 v[200:203], v154
	ds_read_b128 v[204:207], v154 offset:1024
	ds_read_b128 v[208:211], v153
	ds_read_b128 v[212:215], v153 offset:1024
	ds_read_b128 v[216:219], v152
	ds_read_b128 v[220:223], v152 offset:1024
	global_load_lds_dwordx4 v[224:225], off
	v_lshl_add_u64 v[224:225], v[242:243], 0, s[10:11]
	s_mov_b32 m0, s31
	s_nop 0
	global_load_lds_dwordx4 v[224:225], off
	s_waitcnt lgkmcnt(8)
	s_barrier
	s_waitcnt lgkmcnt(0)
	s_waitcnt lgkmcnt(0)
	v_mfma_f32_16x16x32_bf16 v[124:127], v[176:179], v[192:195], v[124:127]
	v_mfma_f32_16x16x32_bf16 v[120:123], v[184:187], v[192:195], v[120:123]
	v_mfma_f32_16x16x32_bf16 v[116:119], v[176:179], v[200:203], v[116:119]
	v_mfma_f32_16x16x32_bf16 v[112:115], v[184:187], v[200:203], v[112:115]
	v_mfma_f32_16x16x32_bf16 v[108:111], v[176:179], v[208:211], v[108:111]
	v_mfma_f32_16x16x32_bf16 v[104:107], v[184:187], v[208:211], v[104:107]
	v_mfma_f32_16x16x32_bf16 v[100:103], v[176:179], v[216:219], v[100:103]
	v_mfma_f32_16x16x32_bf16 v[96:99], v[184:187], v[216:219], v[96:99]
	v_mfma_f32_16x16x32_bf16 v[124:127], v[180:183], v[196:199], v[124:127]
	v_mfma_f32_16x16x32_bf16 v[120:123], v[188:191], v[196:199], v[120:123]
	v_mfma_f32_16x16x32_bf16 v[116:119], v[180:183], v[204:207], v[116:119]
	v_mfma_f32_16x16x32_bf16 v[112:115], v[188:191], v[204:207], v[112:115]
	v_mfma_f32_16x16x32_bf16 v[108:111], v[180:183], v[212:215], v[108:111]
	v_mfma_f32_16x16x32_bf16 v[104:107], v[188:191], v[212:215], v[104:107]
	v_mfma_f32_16x16x32_bf16 v[100:103], v[180:183], v[220:223], v[100:103]
	v_mfma_f32_16x16x32_bf16 v[96:99], v[188:191], v[220:223], v[96:99]
	s_barrier
	v_lshl_add_u64 v[244:245], s[2:3], 0, v[138:139]
	v_readfirstlane_b32 s31, v151
	v_lshl_add_u64 v[246:247], v[244:245], 0, s[12:13]
	s_mov_b32 m0, s31
	v_add_u32_e32 v250, 0x2000, v151
	ds_read_b128 v[224:227], v170
	ds_read_b128 v[228:231], v170 offset:1024
	ds_read_b128 v[232:235], v170 offset:2048
	ds_read_b128 v[236:239], v170 offset:3072
	global_load_lds_dwordx4 v[246:247], off
	v_lshl_add_u64 v[246:247], s[2:3], 0, v[140:141]
	v_readfirstlane_b32 s31, v250
	v_lshl_add_u64 v[248:249], v[246:247], 0, s[12:13]
	s_mov_b32 m0, s31
	s_nop 0
	global_load_lds_dwordx4 v[248:249], off
	s_barrier
	s_waitcnt lgkmcnt(0)
	s_waitcnt lgkmcnt(0)
	v_mfma_f32_16x16x32_bf16 v[92:95], v[224:227], v[192:195], v[92:95]
	v_mfma_f32_16x16x32_bf16 v[88:91], v[232:235], v[192:195], v[88:91]
	v_mfma_f32_16x16x32_bf16 v[84:87], v[224:227], v[200:203], v[84:87]
	v_mfma_f32_16x16x32_bf16 v[80:83], v[232:235], v[200:203], v[80:83]
	v_mfma_f32_16x16x32_bf16 v[76:79], v[224:227], v[208:211], v[76:79]
	v_mfma_f32_16x16x32_bf16 v[72:75], v[232:235], v[208:211], v[72:75]
	v_mfma_f32_16x16x32_bf16 v[68:71], v[224:227], v[216:219], v[68:71]
	v_mfma_f32_16x16x32_bf16 v[64:67], v[232:235], v[216:219], v[64:67]
	v_mfma_f32_16x16x32_bf16 v[92:95], v[228:231], v[196:199], v[92:95]
	v_mfma_f32_16x16x32_bf16 v[88:91], v[236:239], v[196:199], v[88:91]
	v_mfma_f32_16x16x32_bf16 v[84:87], v[228:231], v[204:207], v[84:87]
	v_mfma_f32_16x16x32_bf16 v[80:83], v[236:239], v[204:207], v[80:83]
	v_mfma_f32_16x16x32_bf16 v[76:79], v[228:231], v[212:215], v[76:79]
	v_mfma_f32_16x16x32_bf16 v[72:75], v[236:239], v[212:215], v[72:75]
	v_mfma_f32_16x16x32_bf16 v[68:71], v[228:231], v[220:223], v[68:71]
	v_mfma_f32_16x16x32_bf16 v[64:67], v[236:239], v[220:223], v[64:67]
	v_readfirstlane_b32 s31, v157
	v_lshl_add_u64 v[248:249], v[240:241], 0, s[14:15]
	s_mov_b32 m0, s31
	v_readfirstlane_b32 s31, v158
	s_barrier
	ds_read_b128 v[192:195], v155 offset:16384
	ds_read_b128 v[196:199], v155 offset:17408
	ds_read_b128 v[200:203], v154 offset:16384
	ds_read_b128 v[204:207], v154 offset:17408
	ds_read_b128 v[208:211], v153 offset:16384
	ds_read_b128 v[212:215], v153 offset:17408
	ds_read_b128 v[216:219], v152 offset:16384
	ds_read_b128 v[220:223], v152 offset:17408
	global_load_lds_dwordx4 v[248:249], off
	v_lshl_add_u64 v[248:249], v[242:243], 0, s[14:15]
	s_mov_b32 m0, s31
	s_nop 0
	global_load_lds_dwordx4 v[248:249], off
	s_barrier
	s_waitcnt lgkmcnt(0)
	s_waitcnt lgkmcnt(0)
	v_mfma_f32_16x16x32_bf16 v[60:63], v[176:179], v[192:195], v[60:63]
	v_mfma_f32_16x16x32_bf16 v[56:59], v[184:187], v[192:195], v[56:59]
	v_mfma_f32_16x16x32_bf16 v[52:55], v[176:179], v[200:203], v[52:55]
	v_mfma_f32_16x16x32_bf16 v[48:51], v[184:187], v[200:203], v[48:51]
	v_mfma_f32_16x16x32_bf16 v[44:47], v[176:179], v[208:211], v[44:47]
	v_mfma_f32_16x16x32_bf16 v[40:43], v[184:187], v[208:211], v[40:43]
	v_mfma_f32_16x16x32_bf16 v[36:39], v[176:179], v[216:219], v[36:39]
	v_mfma_f32_16x16x32_bf16 v[32:35], v[184:187], v[216:219], v[32:35]
	v_mfma_f32_16x16x32_bf16 v[60:63], v[180:183], v[196:199], v[60:63]
	v_mfma_f32_16x16x32_bf16 v[56:59], v[188:191], v[196:199], v[56:59]
	v_mfma_f32_16x16x32_bf16 v[52:55], v[180:183], v[204:207], v[52:55]
	v_mfma_f32_16x16x32_bf16 v[48:51], v[188:191], v[204:207], v[48:51]
	v_mfma_f32_16x16x32_bf16 v[44:47], v[180:183], v[212:215], v[44:47]
	v_mfma_f32_16x16x32_bf16 v[40:43], v[188:191], v[212:215], v[40:43]
	v_mfma_f32_16x16x32_bf16 v[36:39], v[180:183], v[220:223], v[36:39]
	v_mfma_f32_16x16x32_bf16 v[32:35], v[188:191], v[220:223], v[32:35]
	s_barrier
	v_readfirstlane_b32 s31, v159
	v_add_u32_e32 v178, 0x2000, v159
	v_lshl_add_u64 v[176:177], v[244:245], 0, s[16:17]
	s_mov_b32 m0, s31
	v_readfirstlane_b32 s31, v178
	global_load_lds_dwordx4 v[176:177], off
	v_lshl_add_u64 v[176:177], v[246:247], 0, s[16:17]
	s_mov_b32 m0, s31
	s_nop 0
	global_load_lds_dwordx4 v[176:177], off
	s_waitcnt vmcnt(6)
	s_barrier
	v_mfma_f32_16x16x32_bf16 v[28:31], v[224:227], v[192:195], v[28:31]
	v_mfma_f32_16x16x32_bf16 v[24:27], v[232:235], v[192:195], v[24:27]
	v_mfma_f32_16x16x32_bf16 v[20:23], v[224:227], v[200:203], v[20:23]
	v_mfma_f32_16x16x32_bf16 v[16:19], v[232:235], v[200:203], v[16:19]
	v_mfma_f32_16x16x32_bf16 v[12:15], v[224:227], v[208:211], v[12:15]
	v_mfma_f32_16x16x32_bf16 v[8:11], v[232:235], v[208:211], v[8:11]
	v_mfma_f32_16x16x32_bf16 v[4:7], v[224:227], v[216:219], v[4:7]
	v_mfma_f32_16x16x32_bf16 v[0:3], v[232:235], v[216:219], v[0:3]
	v_mfma_f32_16x16x32_bf16 v[28:31], v[228:231], v[196:199], v[28:31]
	v_mfma_f32_16x16x32_bf16 v[24:27], v[236:239], v[196:199], v[24:27]
	v_mfma_f32_16x16x32_bf16 v[20:23], v[228:231], v[204:207], v[20:23]
	v_mfma_f32_16x16x32_bf16 v[16:19], v[236:239], v[204:207], v[16:19]
	v_mfma_f32_16x16x32_bf16 v[12:15], v[228:231], v[212:215], v[12:15]
	v_mfma_f32_16x16x32_bf16 v[8:11], v[236:239], v[212:215], v[8:11]
	v_mfma_f32_16x16x32_bf16 v[4:7], v[228:231], v[220:223], v[4:7]
	v_mfma_f32_16x16x32_bf16 v[0:3], v[236:239], v[220:223], v[0:3]
	s_barrier
	ds_read_b128 v[176:179], v160
	ds_read_b128 v[180:183], v160 offset:1024
	ds_read_b128 v[184:187], v160 offset:2048
	ds_read_b128 v[188:191], v160 offset:3072
	v_readfirstlane_b32 s31, v161
	v_lshl_add_u64 v[224:225], v[240:241], 0, s[18:19]
	s_mov_b32 m0, s31
	v_readfirstlane_b32 s31, v162
	ds_read_b128 v[192:195], v155 offset:32768
	ds_read_b128 v[196:199], v155 offset:33792
	ds_read_b128 v[200:203], v154 offset:32768
	ds_read_b128 v[204:207], v154 offset:33792
	ds_read_b128 v[208:211], v153 offset:32768
	ds_read_b128 v[212:215], v153 offset:33792
	ds_read_b128 v[216:219], v152 offset:32768
	ds_read_b128 v[220:223], v152 offset:33792
	global_load_lds_dwordx4 v[224:225], off
	v_lshl_add_u64 v[224:225], v[242:243], 0, s[18:19]
	s_mov_b32 m0, s31
	s_nop 0
	global_load_lds_dwordx4 v[224:225], off
	s_waitcnt lgkmcnt(8)
	s_barrier
	s_waitcnt lgkmcnt(0)
	s_waitcnt lgkmcnt(0)
	v_mfma_f32_16x16x32_bf16 v[124:127], v[176:179], v[192:195], v[124:127]
	v_mfma_f32_16x16x32_bf16 v[120:123], v[184:187], v[192:195], v[120:123]
	v_mfma_f32_16x16x32_bf16 v[116:119], v[176:179], v[200:203], v[116:119]
	v_mfma_f32_16x16x32_bf16 v[112:115], v[184:187], v[200:203], v[112:115]
	v_mfma_f32_16x16x32_bf16 v[108:111], v[176:179], v[208:211], v[108:111]
	v_mfma_f32_16x16x32_bf16 v[104:107], v[184:187], v[208:211], v[104:107]
	v_mfma_f32_16x16x32_bf16 v[100:103], v[176:179], v[216:219], v[100:103]
	v_mfma_f32_16x16x32_bf16 v[96:99], v[184:187], v[216:219], v[96:99]
	v_mfma_f32_16x16x32_bf16 v[124:127], v[180:183], v[196:199], v[124:127]
	v_mfma_f32_16x16x32_bf16 v[120:123], v[188:191], v[196:199], v[120:123]
	v_mfma_f32_16x16x32_bf16 v[116:119], v[180:183], v[204:207], v[116:119]
	v_mfma_f32_16x16x32_bf16 v[112:115], v[188:191], v[204:207], v[112:115]
	v_mfma_f32_16x16x32_bf16 v[108:111], v[180:183], v[212:215], v[108:111]
	v_mfma_f32_16x16x32_bf16 v[104:107], v[188:191], v[212:215], v[104:107]
	v_mfma_f32_16x16x32_bf16 v[100:103], v[180:183], v[220:223], v[100:103]
	v_mfma_f32_16x16x32_bf16 v[96:99], v[188:191], v[220:223], v[96:99]
	s_barrier
	v_readfirstlane_b32 s31, v163
	v_lshl_add_u64 v[248:249], v[244:245], 0, s[20:21]
	s_mov_b32 m0, s31
	v_readfirstlane_b32 s31, v167
	ds_read_b128 v[224:227], v156
	ds_read_b128 v[228:231], v156 offset:1024
	ds_read_b128 v[232:235], v156 offset:2048
	ds_read_b128 v[236:239], v156 offset:3072
	global_load_lds_dwordx4 v[248:249], off
	v_lshl_add_u64 v[248:249], v[246:247], 0, s[20:21]
	s_mov_b32 m0, s31
	s_nop 0
	global_load_lds_dwordx4 v[248:249], off
	s_barrier
	s_waitcnt lgkmcnt(0)
	s_waitcnt lgkmcnt(0)
	v_mfma_f32_16x16x32_bf16 v[92:95], v[224:227], v[192:195], v[92:95]
	v_mfma_f32_16x16x32_bf16 v[88:91], v[232:235], v[192:195], v[88:91]
	v_mfma_f32_16x16x32_bf16 v[84:87], v[224:227], v[200:203], v[84:87]
	v_mfma_f32_16x16x32_bf16 v[80:83], v[232:235], v[200:203], v[80:83]
	v_mfma_f32_16x16x32_bf16 v[76:79], v[224:227], v[208:211], v[76:79]
	v_mfma_f32_16x16x32_bf16 v[72:75], v[232:235], v[208:211], v[72:75]
	v_mfma_f32_16x16x32_bf16 v[68:71], v[224:227], v[216:219], v[68:71]
	v_mfma_f32_16x16x32_bf16 v[64:67], v[232:235], v[216:219], v[64:67]
	v_mfma_f32_16x16x32_bf16 v[92:95], v[228:231], v[196:199], v[92:95]
	v_mfma_f32_16x16x32_bf16 v[88:91], v[236:239], v[196:199], v[88:91]
	v_mfma_f32_16x16x32_bf16 v[84:87], v[228:231], v[204:207], v[84:87]
	v_mfma_f32_16x16x32_bf16 v[80:83], v[236:239], v[204:207], v[80:83]
	v_mfma_f32_16x16x32_bf16 v[76:79], v[228:231], v[212:215], v[76:79]
	v_mfma_f32_16x16x32_bf16 v[72:75], v[236:239], v[212:215], v[72:75]
	v_mfma_f32_16x16x32_bf16 v[68:71], v[228:231], v[220:223], v[68:71]
	v_mfma_f32_16x16x32_bf16 v[64:67], v[236:239], v[220:223], v[64:67]
	v_readfirstlane_b32 s31, v168
	v_lshl_add_u64 v[240:241], v[240:241], 0, s[24:25]
	s_mov_b32 m0, s31
	v_readfirstlane_b32 s31, v169
	s_barrier
	ds_read_b128 v[192:195], v155 offset:49152
	ds_read_b128 v[196:199], v155 offset:50176
	ds_read_b128 v[200:203], v154 offset:49152
	ds_read_b128 v[204:207], v154 offset:50176
	ds_read_b128 v[208:211], v153 offset:49152
	ds_read_b128 v[212:215], v153 offset:50176
	ds_read_b128 v[216:219], v152 offset:49152
	ds_read_b128 v[220:223], v152 offset:50176
	global_load_lds_dwordx4 v[240:241], off
	v_lshl_add_u64 v[240:241], v[242:243], 0, s[24:25]
	s_mov_b32 m0, s31
	s_nop 0
	global_load_lds_dwordx4 v[240:241], off
	s_barrier
	s_waitcnt lgkmcnt(0)
	s_waitcnt lgkmcnt(0)
	v_mfma_f32_16x16x32_bf16 v[60:63], v[176:179], v[192:195], v[60:63]
	v_mfma_f32_16x16x32_bf16 v[56:59], v[184:187], v[192:195], v[56:59]
	v_mfma_f32_16x16x32_bf16 v[52:55], v[176:179], v[200:203], v[52:55]
	v_mfma_f32_16x16x32_bf16 v[48:51], v[184:187], v[200:203], v[48:51]
	v_mfma_f32_16x16x32_bf16 v[44:47], v[176:179], v[208:211], v[44:47]
	v_mfma_f32_16x16x32_bf16 v[40:43], v[184:187], v[208:211], v[40:43]
	v_mfma_f32_16x16x32_bf16 v[36:39], v[176:179], v[216:219], v[36:39]
	v_mfma_f32_16x16x32_bf16 v[32:35], v[184:187], v[216:219], v[32:35]
	v_mfma_f32_16x16x32_bf16 v[60:63], v[180:183], v[196:199], v[60:63]
	v_mfma_f32_16x16x32_bf16 v[56:59], v[188:191], v[196:199], v[56:59]
	v_mfma_f32_16x16x32_bf16 v[52:55], v[180:183], v[204:207], v[52:55]
	v_mfma_f32_16x16x32_bf16 v[48:51], v[188:191], v[204:207], v[48:51]
	v_mfma_f32_16x16x32_bf16 v[44:47], v[180:183], v[212:215], v[44:47]
	v_mfma_f32_16x16x32_bf16 v[40:43], v[188:191], v[212:215], v[40:43]
	v_mfma_f32_16x16x32_bf16 v[36:39], v[180:183], v[220:223], v[36:39]
	v_mfma_f32_16x16x32_bf16 v[32:35], v[188:191], v[220:223], v[32:35]
	s_barrier
	v_readfirstlane_b32 s31, v171
	v_lshl_add_u64 v[176:177], v[244:245], 0, s[26:27]
	s_mov_b32 m0, s31
	v_readfirstlane_b32 s31, v172
	global_load_lds_dwordx4 v[176:177], off
	v_lshl_add_u64 v[176:177], v[246:247], 0, s[26:27]
	s_mov_b32 m0, s31
	s_nop 0
	global_load_lds_dwordx4 v[176:177], off
	s_waitcnt vmcnt(6)
	s_barrier
	v_mfma_f32_16x16x32_bf16 v[28:31], v[224:227], v[192:195], v[28:31]
	v_mfma_f32_16x16x32_bf16 v[24:27], v[232:235], v[192:195], v[24:27]
	v_mfma_f32_16x16x32_bf16 v[20:23], v[224:227], v[200:203], v[20:23]
	v_mfma_f32_16x16x32_bf16 v[16:19], v[232:235], v[200:203], v[16:19]
	v_mfma_f32_16x16x32_bf16 v[12:15], v[224:227], v[208:211], v[12:15]
	v_mfma_f32_16x16x32_bf16 v[8:11], v[232:235], v[208:211], v[8:11]
	v_mfma_f32_16x16x32_bf16 v[4:7], v[224:227], v[216:219], v[4:7]
	v_mfma_f32_16x16x32_bf16 v[0:3], v[232:235], v[216:219], v[0:3]
	v_mfma_f32_16x16x32_bf16 v[28:31], v[228:231], v[196:199], v[28:31]
	v_mfma_f32_16x16x32_bf16 v[24:27], v[236:239], v[196:199], v[24:27]
	v_mfma_f32_16x16x32_bf16 v[20:23], v[228:231], v[204:207], v[20:23]
	v_mfma_f32_16x16x32_bf16 v[16:19], v[236:239], v[204:207], v[16:19]
	v_mfma_f32_16x16x32_bf16 v[12:15], v[228:231], v[212:215], v[12:15]
	v_mfma_f32_16x16x32_bf16 v[8:11], v[236:239], v[212:215], v[8:11]
	v_mfma_f32_16x16x32_bf16 v[4:7], v[228:231], v[220:223], v[4:7]
	v_mfma_f32_16x16x32_bf16 v[0:3], v[236:239], v[220:223], v[0:3]
	s_add_i32 s6, s6, 2
	v_lshl_add_u64 v[138:139], v[138:139], 0, s[28:29]
	v_lshl_add_u64 v[140:141], v[140:141], 0, s[28:29]
	v_lshl_add_u64 v[142:143], v[142:143], 0, s[28:29]
	s_cmp_lt_u32 s6, 60
	v_lshl_add_u64 v[144:145], v[144:145], 0, s[28:29]
	s_barrier
	s_cbranch_scc1 .LBB0_2971
	s_add_u32 s34, s34, 0x1f80
	s_addc_u32 s35, s35, 0
	v_lshl_add_u64 v[132:133], s[34:35], 0, v[132:133]
	v_readfirstlane_b32 s6, v174
	v_lshl_add_u64 v[130:131], v[130:131], 1, v[132:133]
	s_mov_b32 m0, s6
	ds_read_b128 v[138:141], v173
	ds_read_b128 v[142:145], v173 offset:1024
	ds_read_b128 v[176:179], v173 offset:2048
	ds_read_b128 v[180:183], v173 offset:3072
	ds_read_b128 v[184:187], v155
	ds_read_b128 v[188:191], v155 offset:1024
	ds_read_b128 v[192:195], v154
	ds_read_b128 v[196:199], v154 offset:1024
	ds_read_b128 v[200:203], v153
	ds_read_b128 v[204:207], v153 offset:1024
	ds_read_b128 v[208:211], v152
	ds_read_b128 v[212:215], v152 offset:1024
	global_load_lds_dwordx4 v[130:131], off
	v_lshl_add_u64 v[130:131], s[34:35], 0, v[136:137]
	v_readfirstlane_b32 s6, v175
	v_lshl_add_u64 v[130:131], v[134:135], 1, v[130:131]
	s_mov_b32 m0, s6
	s_nop 0
	global_load_lds_dwordx4 v[130:131], off
	s_barrier
	s_waitcnt lgkmcnt(0)
	s_waitcnt lgkmcnt(0)
	v_mfma_f32_16x16x32_bf16 v[124:127], v[138:141], v[184:187], v[124:127]
	v_mfma_f32_16x16x32_bf16 v[116:119], v[138:141], v[192:195], v[116:119]
	v_mfma_f32_16x16x32_bf16 v[108:111], v[138:141], v[200:203], v[108:111]
	v_mfma_f32_16x16x32_bf16 v[100:103], v[138:141], v[208:211], v[100:103]
	v_mfma_f32_16x16x32_bf16 v[124:127], v[142:145], v[188:191], v[124:127]
	v_mfma_f32_16x16x32_bf16 v[120:123], v[176:179], v[184:187], v[120:123]
	v_mfma_f32_16x16x32_bf16 v[116:119], v[142:145], v[196:199], v[116:119]
	v_mfma_f32_16x16x32_bf16 v[112:115], v[176:179], v[192:195], v[112:115]
	v_mfma_f32_16x16x32_bf16 v[108:111], v[142:145], v[204:207], v[108:111]
	v_mfma_f32_16x16x32_bf16 v[104:107], v[176:179], v[200:203], v[104:107]
	v_mfma_f32_16x16x32_bf16 v[100:103], v[142:145], v[212:215], v[100:103]
	v_mfma_f32_16x16x32_bf16 v[96:99], v[176:179], v[208:211], v[96:99]
	v_mfma_f32_16x16x32_bf16 v[130:133], v[180:183], v[188:191], v[120:123]
	v_mfma_f32_16x16x32_bf16 v[134:137], v[180:183], v[196:199], v[112:115]
	v_mfma_f32_16x16x32_bf16 v[172:175], v[180:183], v[204:207], v[104:107]
	v_mfma_f32_16x16x32_bf16 v[216:219], v[180:183], v[212:215], v[96:99]
	s_barrier
	s_nop 1
	ds_read_b128 v[96:99], v170
	ds_read_b128 v[104:107], v170 offset:1024
	ds_read_b128 v[112:115], v170 offset:2048
	ds_read_b128 v[120:123], v170 offset:3072
	s_barrier
	s_waitcnt lgkmcnt(0)
	s_waitcnt lgkmcnt(0)
	v_mfma_f32_16x16x32_bf16 v[92:95], v[96:99], v[184:187], v[92:95]
	v_mfma_f32_16x16x32_bf16 v[84:87], v[96:99], v[192:195], v[84:87]
	v_mfma_f32_16x16x32_bf16 v[76:79], v[96:99], v[200:203], v[76:79]
	v_mfma_f32_16x16x32_bf16 v[68:71], v[96:99], v[208:211], v[68:71]
	v_mfma_f32_16x16x32_bf16 v[92:95], v[104:107], v[188:191], v[92:95]
	v_mfma_f32_16x16x32_bf16 v[88:91], v[112:115], v[184:187], v[88:91]
	v_mfma_f32_16x16x32_bf16 v[84:87], v[104:107], v[196:199], v[84:87]
	v_mfma_f32_16x16x32_bf16 v[80:83], v[112:115], v[192:195], v[80:83]
	v_mfma_f32_16x16x32_bf16 v[76:79], v[104:107], v[204:207], v[76:79]
	v_mfma_f32_16x16x32_bf16 v[72:75], v[112:115], v[200:203], v[72:75]
	v_mfma_f32_16x16x32_bf16 v[68:71], v[104:107], v[212:215], v[68:71]
	v_mfma_f32_16x16x32_bf16 v[64:67], v[112:115], v[208:211], v[64:67]
	v_mfma_f32_16x16x32_bf16 v[168:171], v[120:123], v[188:191], v[88:91]
	v_mfma_f32_16x16x32_bf16 v[184:187], v[120:123], v[196:199], v[80:83]
	v_mfma_f32_16x16x32_bf16 v[188:191], v[120:123], v[204:207], v[72:75]
	v_mfma_f32_16x16x32_bf16 v[192:195], v[120:123], v[212:215], v[64:67]
	s_barrier
	s_nop 1
	ds_read_b128 v[64:67], v155 offset:16384
	ds_read_b128 v[72:75], v155 offset:17408
	ds_read_b128 v[80:83], v154 offset:16384
	ds_read_b128 v[88:91], v154 offset:17408
	ds_read_b128 v[196:199], v153 offset:16384
	ds_read_b128 v[200:203], v153 offset:17408
	ds_read_b128 v[204:207], v152 offset:16384
	ds_read_b128 v[208:211], v152 offset:17408
	s_waitcnt vmcnt(4)
	s_barrier
	s_waitcnt lgkmcnt(0)
	s_waitcnt lgkmcnt(0)
	v_mfma_f32_16x16x32_bf16 v[60:63], v[138:141], v[64:67], v[60:63]
	v_mfma_f32_16x16x32_bf16 v[52:55], v[138:141], v[80:83], v[52:55]
	v_mfma_f32_16x16x32_bf16 v[44:47], v[138:141], v[196:199], v[44:47]
	v_mfma_f32_16x16x32_bf16 v[36:39], v[138:141], v[204:207], v[36:39]
	v_mfma_f32_16x16x32_bf16 v[60:63], v[142:145], v[72:75], v[60:63]
	v_mfma_f32_16x16x32_bf16 v[56:59], v[176:179], v[64:67], v[56:59]
	v_mfma_f32_16x16x32_bf16 v[52:55], v[142:145], v[88:91], v[52:55]
	v_mfma_f32_16x16x32_bf16 v[48:51], v[176:179], v[80:83], v[48:51]
	v_mfma_f32_16x16x32_bf16 v[44:47], v[142:145], v[200:203], v[44:47]
	v_mfma_f32_16x16x32_bf16 v[40:43], v[176:179], v[196:199], v[40:43]
	v_mfma_f32_16x16x32_bf16 v[36:39], v[142:145], v[208:211], v[36:39]
	v_mfma_f32_16x16x32_bf16 v[32:35], v[176:179], v[204:207], v[32:35]
	v_mfma_f32_16x16x32_bf16 v[212:215], v[180:183], v[72:75], v[56:59]
	v_mfma_f32_16x16x32_bf16 v[220:223], v[180:183], v[88:91], v[48:51]
	v_mfma_f32_16x16x32_bf16 v[224:227], v[180:183], v[200:203], v[40:43]
	v_mfma_f32_16x16x32_bf16 v[138:141], v[180:183], v[208:211], v[32:35]
	v_mfma_f32_16x16x32_bf16 v[28:31], v[96:99], v[64:67], v[28:31]
	v_mfma_f32_16x16x32_bf16 v[20:23], v[96:99], v[80:83], v[20:23]
	v_mfma_f32_16x16x32_bf16 v[12:15], v[96:99], v[196:199], v[12:15]
	v_mfma_f32_16x16x32_bf16 v[4:7], v[96:99], v[204:207], v[4:7]
	v_mfma_f32_16x16x32_bf16 v[28:31], v[104:107], v[72:75], v[28:31]
	v_mfma_f32_16x16x32_bf16 v[24:27], v[112:115], v[64:67], v[24:27]
	v_mfma_f32_16x16x32_bf16 v[20:23], v[104:107], v[88:91], v[20:23]
	v_mfma_f32_16x16x32_bf16 v[16:19], v[112:115], v[80:83], v[16:19]
	v_mfma_f32_16x16x32_bf16 v[12:15], v[104:107], v[200:203], v[12:15]
	v_mfma_f32_16x16x32_bf16 v[8:11], v[112:115], v[196:199], v[8:11]
	v_mfma_f32_16x16x32_bf16 v[4:7], v[104:107], v[208:211], v[4:7]
	v_mfma_f32_16x16x32_bf16 v[0:3], v[112:115], v[204:207], v[0:3]
	v_mfma_f32_16x16x32_bf16 v[142:145], v[120:123], v[72:75], v[24:27]
	v_mfma_f32_16x16x32_bf16 v[176:179], v[120:123], v[88:91], v[16:19]
	v_mfma_f32_16x16x32_bf16 v[180:183], v[120:123], v[200:203], v[8:11]
	v_mfma_f32_16x16x32_bf16 v[196:199], v[120:123], v[208:211], v[0:3]
	s_barrier
	s_nop 1
	ds_read_b128 v[0:3], v160
	ds_read_b128 v[8:11], v160 offset:1024
	ds_read_b128 v[16:19], v160 offset:2048
	ds_read_b128 v[24:27], v160 offset:3072
	ds_read_b128 v[32:35], v155 offset:32768
	ds_read_b128 v[40:43], v155 offset:33792
	ds_read_b128 v[48:51], v154 offset:32768
	ds_read_b128 v[56:59], v154 offset:33792
	ds_read_b128 v[64:67], v153 offset:32768
	ds_read_b128 v[158:161], v153 offset:33792
	ds_read_b128 v[200:203], v152 offset:32768
	ds_read_b128 v[204:207], v152 offset:33792
	s_waitcnt vmcnt(2)
	s_barrier
	s_waitcnt lgkmcnt(0)
	s_waitcnt lgkmcnt(0)
	v_mfma_f32_16x16x32_bf16 v[72:75], v[0:3], v[32:35], v[124:127]
	v_mfma_f32_16x16x32_bf16 v[120:123], v[8:11], v[40:43], v[72:75]
	v_mfma_f32_16x16x32_bf16 v[72:75], v[16:19], v[32:35], v[130:133]
	v_mfma_f32_16x16x32_bf16 v[124:127], v[24:27], v[40:43], v[72:75]
	v_mfma_f32_16x16x32_bf16 v[72:75], v[0:3], v[48:51], v[116:119]
	v_mfma_f32_16x16x32_bf16 v[112:115], v[8:11], v[56:59], v[72:75]
	v_mfma_f32_16x16x32_bf16 v[72:75], v[16:19], v[48:51], v[134:137]
	v_mfma_f32_16x16x32_bf16 v[116:119], v[24:27], v[56:59], v[72:75]
	v_mfma_f32_16x16x32_bf16 v[72:75], v[0:3], v[64:67], v[108:111]
	v_mfma_f32_16x16x32_bf16 v[104:107], v[8:11], v[158:161], v[72:75]
	v_mfma_f32_16x16x32_bf16 v[72:75], v[16:19], v[64:67], v[172:175]
	v_mfma_f32_16x16x32_bf16 v[108:111], v[24:27], v[158:161], v[72:75]
	v_mfma_f32_16x16x32_bf16 v[72:75], v[0:3], v[200:203], v[100:103]
	v_mfma_f32_16x16x32_bf16 v[96:99], v[8:11], v[204:207], v[72:75]
	v_mfma_f32_16x16x32_bf16 v[72:75], v[16:19], v[200:203], v[216:219]
	v_mfma_f32_16x16x32_bf16 v[100:103], v[24:27], v[204:207], v[72:75]
	s_barrier
	ds_read_b128 v[130:133], v156
	ds_read_b128 v[134:137], v156 offset:1024
	ds_read_b128 v[172:175], v156 offset:2048
	ds_read_b128 v[208:211], v156 offset:3072
	s_waitcnt vmcnt(0)
	s_barrier
	s_waitcnt lgkmcnt(0)
	s_waitcnt lgkmcnt(0)
	v_mfma_f32_16x16x32_bf16 v[72:75], v[130:133], v[32:35], v[92:95]
	v_mfma_f32_16x16x32_bf16 v[32:35], v[172:175], v[32:35], v[168:171]
	v_mfma_f32_16x16x32_bf16 v[92:95], v[208:211], v[40:43], v[32:35]
	v_mfma_f32_16x16x32_bf16 v[32:35], v[130:133], v[48:51], v[84:87]
	v_mfma_f32_16x16x32_bf16 v[80:83], v[134:137], v[56:59], v[32:35]
	v_mfma_f32_16x16x32_bf16 v[32:35], v[172:175], v[48:51], v[184:187]
	v_mfma_f32_16x16x32_bf16 v[84:87], v[208:211], v[56:59], v[32:35]
	v_mfma_f32_16x16x32_bf16 v[32:35], v[130:133], v[64:67], v[76:79]
	v_mfma_f32_16x16x32_bf16 v[88:91], v[134:137], v[40:43], v[72:75]
	v_mfma_f32_16x16x32_bf16 v[72:75], v[134:137], v[158:161], v[32:35]
	v_mfma_f32_16x16x32_bf16 v[32:35], v[172:175], v[64:67], v[188:191]
	v_mfma_f32_16x16x32_bf16 v[76:79], v[208:211], v[158:161], v[32:35]
	v_mfma_f32_16x16x32_bf16 v[32:35], v[130:133], v[200:203], v[68:71]
	v_mfma_f32_16x16x32_bf16 v[64:67], v[134:137], v[204:207], v[32:35]
	v_mfma_f32_16x16x32_bf16 v[32:35], v[172:175], v[200:203], v[192:195]
	v_mfma_f32_16x16x32_bf16 v[68:71], v[208:211], v[204:207], v[32:35]
	s_barrier
	ds_read_b128 v[156:159], v155 offset:49152
	ds_read_b128 v[160:163], v155 offset:50176
	ds_read_b128 v[168:171], v154 offset:49152
	ds_read_b128 v[184:187], v154 offset:50176
	ds_read_b128 v[188:191], v153 offset:49152
	ds_read_b128 v[192:195], v153 offset:50176
	ds_read_b128 v[200:203], v152 offset:49152
	ds_read_b128 v[152:155], v152 offset:50176
	s_barrier
	s_waitcnt lgkmcnt(0)
	s_waitcnt lgkmcnt(0)
	v_mfma_f32_16x16x32_bf16 v[32:35], v[0:3], v[156:159], v[60:63]
	v_mfma_f32_16x16x32_bf16 v[56:59], v[8:11], v[160:163], v[32:35]
	v_mfma_f32_16x16x32_bf16 v[32:35], v[16:19], v[156:159], v[212:215]
	v_mfma_f32_16x16x32_bf16 v[60:63], v[24:27], v[160:163], v[32:35]
	v_mfma_f32_16x16x32_bf16 v[32:35], v[0:3], v[168:171], v[52:55]
	v_mfma_f32_16x16x32_bf16 v[48:51], v[8:11], v[184:187], v[32:35]
	v_mfma_f32_16x16x32_bf16 v[32:35], v[16:19], v[168:171], v[220:223]
	v_mfma_f32_16x16x32_bf16 v[52:55], v[24:27], v[184:187], v[32:35]
	v_mfma_f32_16x16x32_bf16 v[32:35], v[0:3], v[188:191], v[44:47]
	v_mfma_f32_16x16x32_bf16 v[40:43], v[8:11], v[192:195], v[32:35]
	v_mfma_f32_16x16x32_bf16 v[32:35], v[16:19], v[188:191], v[224:227]
	v_mfma_f32_16x16x32_bf16 v[0:3], v[0:3], v[200:203], v[36:39]
	v_mfma_f32_16x16x32_bf16 v[44:47], v[24:27], v[192:195], v[32:35]
	v_mfma_f32_16x16x32_bf16 v[32:35], v[8:11], v[152:155], v[0:3]
	v_mfma_f32_16x16x32_bf16 v[0:3], v[16:19], v[200:203], v[138:141]
	v_mfma_f32_16x16x32_bf16 v[36:39], v[24:27], v[152:155], v[0:3]
	v_mfma_f32_16x16x32_bf16 v[0:3], v[130:133], v[156:159], v[28:31]
	v_mfma_f32_16x16x32_bf16 v[24:27], v[134:137], v[160:163], v[0:3]
	v_mfma_f32_16x16x32_bf16 v[0:3], v[172:175], v[156:159], v[142:145]
	v_mfma_f32_16x16x32_bf16 v[28:31], v[208:211], v[160:163], v[0:3]
	v_mfma_f32_16x16x32_bf16 v[0:3], v[130:133], v[168:171], v[20:23]
	v_mfma_f32_16x16x32_bf16 v[16:19], v[134:137], v[184:187], v[0:3]
	v_mfma_f32_16x16x32_bf16 v[0:3], v[172:175], v[168:171], v[176:179]
	v_mfma_f32_16x16x32_bf16 v[20:23], v[208:211], v[184:187], v[0:3]
	v_mfma_f32_16x16x32_bf16 v[0:3], v[130:133], v[188:191], v[12:15]
	v_mfma_f32_16x16x32_bf16 v[8:11], v[134:137], v[192:195], v[0:3]
	v_mfma_f32_16x16x32_bf16 v[0:3], v[172:175], v[188:191], v[180:183]
	v_mfma_f32_16x16x32_bf16 v[12:15], v[208:211], v[192:195], v[0:3]
	v_mfma_f32_16x16x32_bf16 v[0:3], v[130:133], v[200:203], v[4:7]
	v_mfma_f32_16x16x32_bf16 v[4:7], v[172:175], v[200:203], v[196:199]
	v_mfma_f32_16x16x32_bf16 v[0:3], v[134:137], v[152:155], v[0:3]
	v_mfma_f32_16x16x32_bf16 v[4:7], v[208:211], v[152:155], v[4:7]
	v_cmp_gt_u32_e32 vcc, s56, v128
	s_barrier
	s_and_saveexec_b64 s[34:35], vcc
	s_cbranch_execz .LBB0_2967
	s_barrier
	s_branch .LBB0_2967
